# compress stage-2 broadcast loops via v_readlane instead of LDS shuffles; redundant hazard pads between plain VALU max chains removed
# speedup vs baseline: 1.0083x; 1.0013x over previous
.LBB0_1032:
	ds_read2st64_b32 v[48:49], v34 offset0:0 offset1:1
	ds_read2st64_b32 v[50:51], v34 offset0:2 offset1:3
	ds_read2st64_b32 v[52:53], v34 offset0:4 offset1:5
	ds_read2st64_b32 v[54:55], v34 offset0:6 offset1:7
	ds_read2st64_b32 v[56:57], v34 offset0:8 offset1:9
	ds_read2st64_b32 v[58:59], v34 offset0:10 offset1:11
	ds_read2st64_b32 v[60:61], v34 offset0:12 offset1:13
	ds_read2st64_b32 v[62:63], v34 offset0:14 offset1:15
	ds_read2st64_b32 v[64:65], v34 offset0:16 offset1:17
	ds_read2st64_b32 v[66:67], v34 offset0:18 offset1:19
	ds_read2st64_b32 v[68:69], v34 offset0:20 offset1:21
	ds_read2st64_b32 v[70:71], v34 offset0:22 offset1:23
	ds_read2st64_b32 v[72:73], v34 offset0:24 offset1:25
	ds_read2st64_b32 v[74:75], v34 offset0:26 offset1:27
	ds_read2st64_b32 v[76:77], v34 offset0:28 offset1:29
	ds_read2st64_b32 v[78:79], v34 offset0:30 offset1:31
	v_readlane_b32 s0, v35, 0
	v_readlane_b32 s1, v35, 1
	v_readlane_b32 s16, v35, 2
	s_waitcnt lgkmcnt(0)
	v_readlane_b32 s17, v35, 3
	v_fmac_f32_e32 v5, s0, v48
	v_readlane_b32 s0, v35, 4
	v_fmac_f32_e32 v5, s1, v49
	v_readlane_b32 s1, v35, 5
	v_fmac_f32_e32 v5, s16, v50
	v_readlane_b32 s16, v35, 6
	v_fmac_f32_e32 v5, s17, v51
	v_readlane_b32 s17, v35, 7
	v_fmac_f32_e32 v5, s0, v52
	v_readlane_b32 s0, v35, 8
	v_fmac_f32_e32 v5, s1, v53
	v_readlane_b32 s1, v35, 9
	v_fmac_f32_e32 v5, s16, v54
	v_readlane_b32 s16, v35, 10
	v_fmac_f32_e32 v5, s17, v55
	v_readlane_b32 s17, v35, 11
	v_fmac_f32_e32 v5, s0, v56
	v_readlane_b32 s0, v35, 12
	v_fmac_f32_e32 v5, s1, v57
	v_readlane_b32 s1, v35, 13
	v_fmac_f32_e32 v5, s16, v58
	v_readlane_b32 s16, v35, 14
	v_fmac_f32_e32 v5, s17, v59
	v_readlane_b32 s17, v35, 15
	v_fmac_f32_e32 v5, s0, v60
	v_readlane_b32 s0, v35, 16
	v_fmac_f32_e32 v5, s1, v61
	v_readlane_b32 s1, v35, 17
	v_fmac_f32_e32 v5, s16, v62
	v_readlane_b32 s16, v35, 18
	v_fmac_f32_e32 v5, s17, v63
	v_readlane_b32 s17, v35, 19
	v_fmac_f32_e32 v5, s0, v64
	v_readlane_b32 s0, v35, 20
	v_fmac_f32_e32 v5, s1, v65
	v_readlane_b32 s1, v35, 21
	v_fmac_f32_e32 v5, s16, v66
	v_readlane_b32 s16, v35, 22
	v_fmac_f32_e32 v5, s17, v67
	v_readlane_b32 s17, v35, 23
	v_fmac_f32_e32 v5, s0, v68
	v_readlane_b32 s0, v35, 24
	v_fmac_f32_e32 v5, s1, v69
	v_readlane_b32 s1, v35, 25
	v_fmac_f32_e32 v5, s16, v70
	v_readlane_b32 s16, v35, 26
	v_fmac_f32_e32 v5, s17, v71
	v_readlane_b32 s17, v35, 27
	v_fmac_f32_e32 v5, s0, v72
	v_readlane_b32 s0, v35, 28
	v_fmac_f32_e32 v5, s1, v73
	v_readlane_b32 s1, v35, 29
	v_fmac_f32_e32 v5, s16, v74
	v_readlane_b32 s16, v35, 30
	v_fmac_f32_e32 v5, s17, v75
	v_readlane_b32 s17, v35, 31
	v_fmac_f32_e32 v5, s0, v76
	v_fmac_f32_e32 v5, s1, v77
	v_fmac_f32_e32 v5, s16, v78
	v_fmac_f32_e32 v5, s17, v79
	ds_read2st64_b32 v[48:49], v34 offset0:32 offset1:33
	ds_read2st64_b32 v[50:51], v34 offset0:34 offset1:35
	ds_read2st64_b32 v[52:53], v34 offset0:36 offset1:37
	ds_read2st64_b32 v[54:55], v34 offset0:38 offset1:39
	ds_read2st64_b32 v[56:57], v34 offset0:40 offset1:41
	ds_read2st64_b32 v[58:59], v34 offset0:42 offset1:43
	ds_read2st64_b32 v[60:61], v34 offset0:44 offset1:45
	ds_read2st64_b32 v[62:63], v34 offset0:46 offset1:47
	ds_read2st64_b32 v[64:65], v34 offset0:48 offset1:49
	ds_read2st64_b32 v[66:67], v34 offset0:50 offset1:51
	ds_read2st64_b32 v[68:69], v34 offset0:52 offset1:53
	ds_read2st64_b32 v[70:71], v34 offset0:54 offset1:55
	ds_read2st64_b32 v[72:73], v34 offset0:56 offset1:57
	ds_read2st64_b32 v[74:75], v34 offset0:58 offset1:59
	ds_read2st64_b32 v[76:77], v34 offset0:60 offset1:61
	ds_read2st64_b32 v[78:79], v34 offset0:62 offset1:63
	v_readlane_b32 s0, v35, 32
	v_readlane_b32 s1, v35, 33
	v_readlane_b32 s16, v35, 34
	s_waitcnt lgkmcnt(0)
	v_readlane_b32 s17, v35, 35
	v_fmac_f32_e32 v5, s0, v48
	v_readlane_b32 s0, v35, 36
	v_fmac_f32_e32 v5, s1, v49
	v_readlane_b32 s1, v35, 37
	v_fmac_f32_e32 v5, s16, v50
	v_readlane_b32 s16, v35, 38
	v_fmac_f32_e32 v5, s17, v51
	v_readlane_b32 s17, v35, 39
	v_fmac_f32_e32 v5, s0, v52
	v_readlane_b32 s0, v35, 40
	v_fmac_f32_e32 v5, s1, v53
	v_readlane_b32 s1, v35, 41
	v_fmac_f32_e32 v5, s16, v54
	v_readlane_b32 s16, v35, 42
	v_fmac_f32_e32 v5, s17, v55
	v_readlane_b32 s17, v35, 43
	v_fmac_f32_e32 v5, s0, v56
	v_readlane_b32 s0, v35, 44
	v_fmac_f32_e32 v5, s1, v57
	v_readlane_b32 s1, v35, 45
	v_fmac_f32_e32 v5, s16, v58
	v_readlane_b32 s16, v35, 46
	v_fmac_f32_e32 v5, s17, v59
	v_readlane_b32 s17, v35, 47
	v_fmac_f32_e32 v5, s0, v60
	v_readlane_b32 s0, v35, 48
	v_fmac_f32_e32 v5, s1, v61
	v_readlane_b32 s1, v35, 49
	v_fmac_f32_e32 v5, s16, v62
	v_readlane_b32 s16, v35, 50
	v_fmac_f32_e32 v5, s17, v63
	v_readlane_b32 s17, v35, 51
	v_fmac_f32_e32 v5, s0, v64
	v_readlane_b32 s0, v35, 52
	v_fmac_f32_e32 v5, s1, v65
	v_readlane_b32 s1, v35, 53
	v_fmac_f32_e32 v5, s16, v66
	v_readlane_b32 s16, v35, 54
	v_fmac_f32_e32 v5, s17, v67
	v_readlane_b32 s17, v35, 55
	v_fmac_f32_e32 v5, s0, v68
	v_readlane_b32 s0, v35, 56
	v_fmac_f32_e32 v5, s1, v69
	v_readlane_b32 s1, v35, 57
	v_fmac_f32_e32 v5, s16, v70
	v_readlane_b32 s16, v35, 58
	v_fmac_f32_e32 v5, s17, v71
	v_readlane_b32 s17, v35, 59
	v_fmac_f32_e32 v5, s0, v72
	v_readlane_b32 s0, v35, 60
	v_fmac_f32_e32 v5, s1, v73
	v_readlane_b32 s1, v35, 61
	v_fmac_f32_e32 v5, s16, v74
	v_readlane_b32 s16, v35, 62
	v_fmac_f32_e32 v5, s17, v75
	v_readlane_b32 s17, v35, 63
	v_fmac_f32_e32 v5, s0, v76
	v_fmac_f32_e32 v5, s1, v77
	v_fmac_f32_e32 v5, s16, v78
	v_fmac_f32_e32 v5, s17, v79
	s_waitcnt vmcnt(0)
	v_add_f32_e32 v3, 0, v10
	v_add_f32_e32 v3, v3, v11
	v_add_f32_e32 v3, v3, v12
	v_add_f32_e32 v3, v3, v13
	v_add_f32_e32 v3, v3, v14
	v_add_f32_e32 v3, v3, v15
	v_add_f32_e32 v3, v3, v16
	v_add_f32_e32 v3, v3, v17
	v_add_f32_e32 v3, v3, v18
	v_add_f32_e32 v3, v3, v19
	v_add_f32_e32 v3, v3, v20
	v_add_f32_e32 v3, v3, v21
	v_add_f32_e32 v3, v3, v22
	v_add_f32_e32 v3, v3, v23
	v_add_f32_e32 v3, v3, v24
	v_add_f32_e32 v3, v3, v25
	v_add_f32_e32 v3, v3, v26
	v_add_f32_e32 v3, v3, v27
	v_add_f32_e32 v3, v3, v28
	v_add_f32_e32 v3, v3, v29
	v_add_f32_e32 v3, v3, v30
	v_add_f32_e32 v3, v3, v31
	v_add_f32_e32 v3, v3, v32
	v_add_f32_e32 v3, v3, v33
	v_mul_f32_e32 v10, 0xbfb8aa3b, v3
	v_exp_f32_e32 v10, v10
	s_nop 0
	v_add_f32_e32 v10, 1.0, v10
	v_rcp_f32_e32 v10, v10
	s_nop 0
	v_mul_f32_e32 v10, v3, v10
	v_ashrrev_i32_e32 v3, 11, v1
	v_lshlrev_b32_e32 v3, 15, v3
	v_add_u32_e32 v3, v9, v3
	s_mov_b32 s0, 0
.LBB0_1034:
	ds_read2st64_b32 v[48:49], v3 offset0:0 offset1:1
	ds_read2st64_b32 v[50:51], v3 offset0:2 offset1:3
	ds_read2st64_b32 v[52:53], v3 offset0:4 offset1:5
	ds_read2st64_b32 v[54:55], v3 offset0:6 offset1:7
	ds_read2st64_b32 v[56:57], v3 offset0:8 offset1:9
	ds_read2st64_b32 v[58:59], v3 offset0:10 offset1:11
	ds_read2st64_b32 v[60:61], v3 offset0:12 offset1:13
	ds_read2st64_b32 v[62:63], v3 offset0:14 offset1:15
	ds_read2st64_b32 v[64:65], v3 offset0:16 offset1:17
	ds_read2st64_b32 v[66:67], v3 offset0:18 offset1:19
	ds_read2st64_b32 v[68:69], v3 offset0:20 offset1:21
	ds_read2st64_b32 v[70:71], v3 offset0:22 offset1:23
	ds_read2st64_b32 v[72:73], v3 offset0:24 offset1:25
	ds_read2st64_b32 v[74:75], v3 offset0:26 offset1:27
	ds_read2st64_b32 v[76:77], v3 offset0:28 offset1:29
	ds_read2st64_b32 v[78:79], v3 offset0:30 offset1:31
	v_readlane_b32 s0, v10, 0
	v_readlane_b32 s1, v10, 1
	v_readlane_b32 s16, v10, 2
	s_waitcnt lgkmcnt(0)
	v_readlane_b32 s17, v10, 3
	v_fmac_f32_e32 v5, s0, v48
	v_readlane_b32 s0, v10, 4
	v_fmac_f32_e32 v5, s1, v49
	v_readlane_b32 s1, v10, 5
	v_fmac_f32_e32 v5, s16, v50
	v_readlane_b32 s16, v10, 6
	v_fmac_f32_e32 v5, s17, v51
	v_readlane_b32 s17, v10, 7
	v_fmac_f32_e32 v5, s0, v52
	v_readlane_b32 s0, v10, 8
	v_fmac_f32_e32 v5, s1, v53
	v_readlane_b32 s1, v10, 9
	v_fmac_f32_e32 v5, s16, v54
	v_readlane_b32 s16, v10, 10
	v_fmac_f32_e32 v5, s17, v55
	v_readlane_b32 s17, v10, 11
	v_fmac_f32_e32 v5, s0, v56
	v_readlane_b32 s0, v10, 12
	v_fmac_f32_e32 v5, s1, v57
	v_readlane_b32 s1, v10, 13
	v_fmac_f32_e32 v5, s16, v58
	v_readlane_b32 s16, v10, 14
	v_fmac_f32_e32 v5, s17, v59
	v_readlane_b32 s17, v10, 15
	v_fmac_f32_e32 v5, s0, v60
	v_readlane_b32 s0, v10, 16
	v_fmac_f32_e32 v5, s1, v61
	v_readlane_b32 s1, v10, 17
	v_fmac_f32_e32 v5, s16, v62
	v_readlane_b32 s16, v10, 18
	v_fmac_f32_e32 v5, s17, v63
	v_readlane_b32 s17, v10, 19
	v_fmac_f32_e32 v5, s0, v64
	v_readlane_b32 s0, v10, 20
	v_fmac_f32_e32 v5, s1, v65
	v_readlane_b32 s1, v10, 21
	v_fmac_f32_e32 v5, s16, v66
	v_readlane_b32 s16, v10, 22
	v_fmac_f32_e32 v5, s17, v67
	v_readlane_b32 s17, v10, 23
	v_fmac_f32_e32 v5, s0, v68
	v_readlane_b32 s0, v10, 24
	v_fmac_f32_e32 v5, s1, v69
	v_readlane_b32 s1, v10, 25
	v_fmac_f32_e32 v5, s16, v70
	v_readlane_b32 s16, v10, 26
	v_fmac_f32_e32 v5, s17, v71
	v_readlane_b32 s17, v10, 27
	v_fmac_f32_e32 v5, s0, v72
	v_readlane_b32 s0, v10, 28
	v_fmac_f32_e32 v5, s1, v73
	v_readlane_b32 s1, v10, 29
	v_fmac_f32_e32 v5, s16, v74
	v_readlane_b32 s16, v10, 30
	v_fmac_f32_e32 v5, s17, v75
	v_readlane_b32 s17, v10, 31
	v_fmac_f32_e32 v5, s0, v76
	v_fmac_f32_e32 v5, s1, v77
	v_fmac_f32_e32 v5, s16, v78
	v_fmac_f32_e32 v5, s17, v79
	ds_read2st64_b32 v[48:49], v3 offset0:32 offset1:33
	ds_read2st64_b32 v[50:51], v3 offset0:34 offset1:35
	ds_read2st64_b32 v[52:53], v3 offset0:36 offset1:37
	ds_read2st64_b32 v[54:55], v3 offset0:38 offset1:39
	ds_read2st64_b32 v[56:57], v3 offset0:40 offset1:41
	ds_read2st64_b32 v[58:59], v3 offset0:42 offset1:43
	ds_read2st64_b32 v[60:61], v3 offset0:44 offset1:45
	ds_read2st64_b32 v[62:63], v3 offset0:46 offset1:47
	ds_read2st64_b32 v[64:65], v3 offset0:48 offset1:49
	ds_read2st64_b32 v[66:67], v3 offset0:50 offset1:51
	ds_read2st64_b32 v[68:69], v3 offset0:52 offset1:53
	ds_read2st64_b32 v[70:71], v3 offset0:54 offset1:55
	ds_read2st64_b32 v[72:73], v3 offset0:56 offset1:57
	ds_read2st64_b32 v[74:75], v3 offset0:58 offset1:59
	ds_read2st64_b32 v[76:77], v3 offset0:60 offset1:61
	ds_read2st64_b32 v[78:79], v3 offset0:62 offset1:63
	v_readlane_b32 s0, v10, 32
	v_readlane_b32 s1, v10, 33
	v_readlane_b32 s16, v10, 34
	s_waitcnt lgkmcnt(0)
	v_readlane_b32 s17, v10, 35
	v_fmac_f32_e32 v5, s0, v48
	v_readlane_b32 s0, v10, 36
	v_fmac_f32_e32 v5, s1, v49
	v_readlane_b32 s1, v10, 37
	v_fmac_f32_e32 v5, s16, v50
	v_readlane_b32 s16, v10, 38
	v_fmac_f32_e32 v5, s17, v51
	v_readlane_b32 s17, v10, 39
	v_fmac_f32_e32 v5, s0, v52
	v_readlane_b32 s0, v10, 40
	v_fmac_f32_e32 v5, s1, v53
	v_readlane_b32 s1, v10, 41
	v_fmac_f32_e32 v5, s16, v54
	v_readlane_b32 s16, v10, 42
	v_fmac_f32_e32 v5, s17, v55
	v_readlane_b32 s17, v10, 43
	v_fmac_f32_e32 v5, s0, v56
	v_readlane_b32 s0, v10, 44
	v_fmac_f32_e32 v5, s1, v57
	v_readlane_b32 s1, v10, 45
	v_fmac_f32_e32 v5, s16, v58
	v_readlane_b32 s16, v10, 46
	v_fmac_f32_e32 v5, s17, v59
	v_readlane_b32 s17, v10, 47
	v_fmac_f32_e32 v5, s0, v60
	v_readlane_b32 s0, v10, 48
	v_fmac_f32_e32 v5, s1, v61
	v_readlane_b32 s1, v10, 49
	v_fmac_f32_e32 v5, s16, v62
	v_readlane_b32 s16, v10, 50
	v_fmac_f32_e32 v5, s17, v63
	v_readlane_b32 s17, v10, 51
	v_fmac_f32_e32 v5, s0, v64
	v_readlane_b32 s0, v10, 52
	v_fmac_f32_e32 v5, s1, v65
	v_readlane_b32 s1, v10, 53
	v_fmac_f32_e32 v5, s16, v66
	v_readlane_b32 s16, v10, 54
	v_fmac_f32_e32 v5, s17, v67
	v_readlane_b32 s17, v10, 55
	v_fmac_f32_e32 v5, s0, v68
	v_readlane_b32 s0, v10, 56
	v_fmac_f32_e32 v5, s1, v69
	v_readlane_b32 s1, v10, 57
	v_fmac_f32_e32 v5, s16, v70
	v_readlane_b32 s16, v10, 58
	v_fmac_f32_e32 v5, s17, v71
	v_readlane_b32 s17, v10, 59
	v_fmac_f32_e32 v5, s0, v72
	v_readlane_b32 s0, v10, 60
	v_fmac_f32_e32 v5, s1, v73
	v_readlane_b32 s1, v10, 61
	v_fmac_f32_e32 v5, s16, v74
	v_readlane_b32 s16, v10, 62
	v_fmac_f32_e32 v5, s17, v75
	v_readlane_b32 s17, v10, 63
	v_fmac_f32_e32 v5, s0, v76
	v_fmac_f32_e32 v5, s1, v77
	v_fmac_f32_e32 v5, s16, v78
	v_fmac_f32_e32 v5, s17, v79
	v_and_b32_e32 v10, 0x7f, v1
	s_movk_i32 s0, 0x7f
	v_cmp_ne_u32_e32 vcc, s0, v10
	s_movk_i32 s0, 0x7ff
	s_nop 0
	v_cndmask_b32_e32 v3, 0, v5, vcc
	v_cmp_lt_u32_e32 vcc, s0, v1
	v_cvt_pk_bf16_f32 v3, v3, v93
	s_and_saveexec_b64 s[0:1], vcc
	s_xor_b64 s[14:15], exec, s[0:1]
	v_lshlrev_b32_e32 v4, 6, v4
	v_and_b32_e32 v4, 0x1e000, v4
	v_or3_b32 v92, v4, v7, v10
	s_or_saveexec_b64 s[14:15], s[14:15]
	v_mov_b64_e32 v[4:5], s[10:11]
	s_xor_b64 exec, exec, s[14:15]
	s_cbranch_execz .LBB0_1030
	v_lshl_or_b32 v92, v1, 6, v0
	v_mov_b64_e32 v[4:5], s[8:9]
	s_branch .LBB0_1030

.LBB0_1284:
	s_lshl_b32 s13, s14, 6
	s_lshl_b32 s14, 1, s14
	s_mul_i32 s2, s0, 0x4800
	v_and_b32_e32 v32, s14, v172
	s_add_i32 s96, s2, 0
	v_cmp_ne_u32_e32 vcc, 0, v32
	s_cmp_eq_u64 vcc, 0
	s_cselect_b64 s[2:3], -1, 0
	s_cmp_gt_i32 s13, s76
	s_cselect_b64 s[74:75], -1, 0
	s_or_b64 s[2:3], s[2:3], s[74:75]
	v_mov_b32_e32 v133, v196
	s_and_b64 vcc, exec, s[2:3]
	s_cbranch_vccnz .LBB0_1306
	v_cmp_eq_u32_e32 vcc, 0, v32
	s_or_b32 s15, s13, 63
	v_cmp_le_i32_e64 s[74:75], s15, v152
	v_cndmask_b32_e32 v138, 0, v211, vcc
	v_cmp_ge_u32_e64 s[2:3], s13, v138
	s_and_b64 s[2:3], s[2:3], s[74:75]
	v_and_b32_e32 v139, 63, v133
	v_cndmask_b32_e64 v32, 0, 1, s[2:3]
	v_cmp_ne_u32_e64 s[2:3], 0, v32
	v_and_b32_e32 v137, 15, v133
	v_and_b32_e32 v32, 48, v133
	v_or_b32_e32 v135, 48, v139
	s_mov_b64 s[74:75], -1
	s_cmp_lg_u64 s[2:3], exec
	v_add_u32_e32 v136, s96, v32
	v_mul_u32_u24_e32 v134, 0x90, v137
	v_mul_u32_u24_e32 v132, 0x90, v135
	s_cbranch_scc0 .LBB0_1299
	v_mad_u32_u24 v32, v137, s88, v136
	ds_read_b128 v[52:55], v32
	ds_read_b128 v[56:59], v32 offset:64
	ds_read_b128 v[60:63], v32 offset:2304
	ds_read_b128 v[64:67], v32 offset:2368
	ds_read_b128 v[68:71], v32 offset:4608
	ds_read_b128 v[72:75], v32 offset:4672
	v_mad_u32_u24 v32, v135, s88, v136
	ds_read_b128 v[76:79], v32
	ds_read_b128 v[48:51], v32 offset:64
	s_cmp_gt_i32 s15, s78
	s_mov_b64 s[2:3], -1
	s_cbranch_scc1 .LBB0_1292
	s_waitcnt lgkmcnt(7)
	v_mfma_f32_16x16x32_bf16 v[32:35], v[52:55], v[96:99], 0
	s_waitcnt lgkmcnt(5)
	v_mfma_f32_16x16x32_bf16 v[36:39], v[60:63], v[96:99], 0
	s_waitcnt lgkmcnt(3)
	v_mfma_f32_16x16x32_bf16 v[40:43], v[68:71], v[96:99], 0
	s_waitcnt lgkmcnt(1)
	v_mfma_f32_16x16x32_bf16 v[44:47], v[76:79], v[96:99], 0
	v_mfma_f32_16x16x32_bf16 v[32:35], v[56:59], v[100:103], v[32:35]
	v_mfma_f32_16x16x32_bf16 v[36:39], v[64:67], v[100:103], v[36:39]
	v_mfma_f32_16x16x32_bf16 v[40:43], v[72:75], v[100:103], v[40:43]
	s_waitcnt lgkmcnt(0)
	v_mfma_f32_16x16x32_bf16 v[44:47], v[48:51], v[100:103], v[44:47]
	s_nop 7
	s_nop 0
	v_max3_f32 v80, v158, v32, v33
	v_max3_f32 v80, v80, v34, v35
	v_max3_f32 v80, v80, v36, v37
	v_max3_f32 v80, v80, v38, v39
	v_max3_f32 v80, v80, v40, v41
	v_max3_f32 v80, v80, v42, v43
	v_max3_f32 v80, v80, v44, v45
	v_max3_f32 v80, v80, v46, v47
	s_nop 0
	v_cndmask_b32_e32 v80, v80, v158, vcc
	v_mov_b32_e32 v81, v80
	s_nop 1
	v_permlane16_swap_b32_e32 v81, v80
	s_waitcnt lgkmcnt(0)
	v_max3_f32 v80, v80, v81, v158
	v_mov_b32_e32 v81, v80
	s_nop 1
	v_permlane32_swap_b32_e32 v81, v80
	s_waitcnt lgkmcnt(0)
	v_max3_f32 v80, v80, v81, v158
	v_max3_f32 v163, v155, v80, v158
	s_nop 0
	v_cndmask_b32_e32 v84, v163, v212, vcc
	v_sub_f32_e32 v35, v35, v84
	v_sub_f32_e32 v34, v34, v84
	v_sub_f32_e32 v33, v33, v84
	v_sub_f32_e32 v32, v32, v84
	v_sub_f32_e32 v39, v39, v84
	v_sub_f32_e32 v38, v38, v84
	v_exp_f32_e32 v88, v32
	v_exp_f32_e32 v89, v33
	v_exp_f32_e32 v90, v34
	v_exp_f32_e32 v91, v35
	v_sub_f32_e32 v32, v37, v84
	v_sub_f32_e32 v33, v36, v84
	v_exp_f32_e32 v128, v33
	v_exp_f32_e32 v130, v38
	v_exp_f32_e32 v131, v39
	v_exp_f32_e32 v129, v32
	v_sub_f32_e32 v36, v43, v84
	v_sub_f32_e32 v37, v42, v84
	v_sub_f32_e32 v38, v41, v84
	v_sub_f32_e32 v39, v40, v84
	v_exp_f32_e32 v80, v39
	v_exp_f32_e32 v81, v38
	v_exp_f32_e32 v82, v37
	v_exp_f32_e32 v83, v36
	v_sub_f32_e32 v36, v47, v84
	v_sub_f32_e32 v37, v46, v84
	v_sub_f32_e32 v38, v45, v84
	v_sub_f32_e32 v39, v44, v84
	v_exp_f32_e32 v84, v39
	v_exp_f32_e32 v86, v37
	v_exp_f32_e32 v87, v36
	v_exp_f32_e32 v85, v38
	v_pk_add_f32 v[32:33], v[88:89], 0 op_sel_hi:[1,0]
	v_pk_add_f32 v[34:35], v[90:91], 0 op_sel_hi:[1,0]
	v_pk_add_f32 v[32:33], v[128:129], v[32:33]
	v_pk_add_f32 v[34:35], v[130:131], v[34:35]
	v_pk_add_f32 v[32:33], v[80:81], v[32:33]
	v_pk_add_f32 v[34:35], v[82:83], v[34:35]
	v_pk_add_f32 v[32:33], v[84:85], v[32:33]
	v_pk_add_f32 v[34:35], v[86:87], v[34:35]
	v_add_f32_e32 v32, v32, v33
	v_add_f32_e32 v33, v34, v35
	v_add_f32_e32 v32, v32, v33
	v_mov_b32_e32 v33, v32
	s_nop 1
	v_permlane16_swap_b32_e32 v33, v32
	v_sub_f32_e32 v34, v155, v163
	v_exp_f32_e32 v92, v34
	s_waitcnt lgkmcnt(0)
	v_add_f32_e32 v140, v32, v33
	v_mov_b32_e32 v141, v140
	s_nop 1
	v_permlane32_swap_b32_e32 v141, v140
	v_cmp_eq_f32_e32 vcc, 1.0, v92
	s_cmp_lg_u64 vcc, exec
	s_cbranch_scc0 .LBB0_1289
	v_pk_mul_f32 v[46:47], v[18:19], v[92:93] op_sel_hi:[1,0]
	v_pk_mul_f32 v[44:45], v[16:17], v[92:93] op_sel_hi:[1,0]
	v_pk_mul_f32 v[42:43], v[22:23], v[92:93] op_sel_hi:[1,0]
	v_pk_mul_f32 v[40:41], v[20:21], v[92:93] op_sel_hi:[1,0]
	v_pk_mul_f32 v[38:39], v[26:27], v[92:93] op_sel_hi:[1,0]
	v_pk_mul_f32 v[36:37], v[24:25], v[92:93] op_sel_hi:[1,0]
	v_pk_mul_f32 v[34:35], v[30:31], v[92:93] op_sel_hi:[1,0]
	v_pk_mul_f32 v[32:33], v[28:29], v[92:93] op_sel_hi:[1,0]
	s_mov_b64 s[2:3], 0

.LBB0_1292:
	s_and_b64 vcc, exec, s[2:3]
	s_cbranch_vccz .LBB0_1298
	s_waitcnt lgkmcnt(1)
	v_mfma_f32_16x16x32_bf16 v[44:47], v[76:79], v[96:99], 0
	v_mfma_f32_16x16x32_bf16 v[32:35], v[52:55], v[96:99], 0
	v_lshrrev_b32_e32 v52, 4, v139
	v_mfma_f32_16x16x32_bf16 v[36:39], v[60:63], v[96:99], 0
	v_mfma_f32_16x16x32_bf16 v[40:43], v[68:71], v[96:99], 0
	s_waitcnt lgkmcnt(0)
	v_mfma_f32_16x16x32_bf16 v[44:47], v[48:51], v[100:103], v[44:47]
	v_lshl_or_b32 v48, v52, 2, s13
	v_cmp_ge_u32_e32 vcc, v48, v138
	v_cmp_le_i32_e64 s[2:3], v48, v152
	v_mfma_f32_16x16x32_bf16 v[32:35], v[56:59], v[100:103], v[32:35]
	s_and_b64 vcc, vcc, s[2:3]
	v_or_b32_e32 v49, 1, v48
	v_cmp_lt_i32_e64 s[2:3], v48, v152
	v_mfma_f32_16x16x32_bf16 v[36:39], v[64:67], v[100:103], v[36:39]
	v_or_b32_e32 v50, 2, v48
	v_mfma_f32_16x16x32_bf16 v[40:43], v[72:75], v[100:103], v[40:43]
	s_nop 7
	s_nop 1
	v_cndmask_b32_e32 v32, v158, v32, vcc
	v_cmp_ge_u32_e32 vcc, v49, v138
	s_and_b64 vcc, s[2:3], vcc
	v_cmp_le_i32_e64 s[2:3], v50, v152
	v_cndmask_b32_e32 v33, v158, v33, vcc
	v_cmp_ge_u32_e32 vcc, v50, v138
	s_and_b64 vcc, vcc, s[2:3]
	v_or_b32_e32 v50, 3, v48
	v_cndmask_b32_e32 v34, v158, v34, vcc
	v_cmp_ge_u32_e32 vcc, v50, v138
	v_cmp_le_i32_e64 s[2:3], v50, v152
	s_and_b64 vcc, vcc, s[2:3]
	v_or_b32_e32 v50, 16, v48
	v_cndmask_b32_e32 v35, v158, v35, vcc
	v_cmp_ge_u32_e32 vcc, v50, v138
	v_cmp_le_i32_e64 s[2:3], v50, v152
	s_and_b64 vcc, vcc, s[2:3]
	v_or_b32_e32 v50, 17, v48
	v_cndmask_b32_e32 v36, v158, v36, vcc
	v_cmp_ge_u32_e32 vcc, v50, v138
	v_cmp_le_i32_e64 s[2:3], v50, v152
	s_and_b64 vcc, vcc, s[2:3]
	v_or_b32_e32 v50, 18, v48
	v_cndmask_b32_e32 v37, v158, v37, vcc
	v_cmp_ge_u32_e32 vcc, v50, v138
	v_cmp_le_i32_e64 s[2:3], v50, v152
	s_and_b64 vcc, vcc, s[2:3]
	v_or_b32_e32 v50, 19, v48
	v_cndmask_b32_e32 v38, v158, v38, vcc
	v_cmp_ge_u32_e32 vcc, v50, v138
	v_cmp_le_i32_e64 s[2:3], v50, v152
	s_and_b64 vcc, vcc, s[2:3]
	v_or_b32_e32 v50, 32, v48
	v_cndmask_b32_e32 v39, v158, v39, vcc
	v_cmp_ge_u32_e32 vcc, v50, v138
	v_cmp_le_i32_e64 s[2:3], v50, v152
	s_and_b64 vcc, vcc, s[2:3]
	v_or_b32_e32 v50, 33, v48
	v_cndmask_b32_e32 v40, v158, v40, vcc
	v_cmp_ge_u32_e32 vcc, v50, v138
	v_cmp_le_i32_e64 s[2:3], v50, v152
	s_and_b64 vcc, vcc, s[2:3]
	v_or_b32_e32 v50, 34, v48
	v_cndmask_b32_e32 v41, v158, v41, vcc
	v_cmp_ge_u32_e32 vcc, v50, v138
	v_cmp_le_i32_e64 s[2:3], v50, v152
	s_and_b64 vcc, vcc, s[2:3]
	v_or_b32_e32 v50, 35, v48
	v_cndmask_b32_e32 v42, v158, v42, vcc
	v_cmp_ge_u32_e32 vcc, v50, v138
	v_cmp_le_i32_e64 s[2:3], v50, v152
	s_and_b64 vcc, vcc, s[2:3]
	v_or_b32_e32 v50, 48, v48
	v_cndmask_b32_e32 v43, v158, v43, vcc
	v_cmp_ge_u32_e32 vcc, v50, v138
	v_cmp_le_i32_e64 s[2:3], v50, v152
	s_and_b64 vcc, vcc, s[2:3]
	v_or_b32_e32 v50, 49, v48
	v_max3_f32 v49, v32, s87, v33
	v_cndmask_b32_e32 v44, v158, v44, vcc
	v_cmp_ge_u32_e32 vcc, v50, v138
	v_cmp_le_i32_e64 s[2:3], v50, v152
	v_max3_f32 v49, v49, v34, v35
	s_and_b64 vcc, vcc, s[2:3]
	v_or_b32_e32 v50, 50, v48
	v_max3_f32 v49, v49, v36, v37
	v_cndmask_b32_e32 v45, v158, v45, vcc
	v_cmp_ge_u32_e32 vcc, v50, v138
	v_cmp_le_i32_e64 s[2:3], v50, v152
	v_max3_f32 v49, v49, v38, v39
	s_and_b64 vcc, vcc, s[2:3]
	v_or_b32_e32 v48, 51, v48
	v_max3_f32 v49, v49, v40, v41
	v_cndmask_b32_e32 v46, v158, v46, vcc
	v_cmp_ge_u32_e32 vcc, v48, v138
	v_cmp_le_i32_e64 s[2:3], v48, v152
	v_max3_f32 v49, v49, v42, v43
	s_and_b64 vcc, vcc, s[2:3]
	v_max3_f32 v49, v49, v44, v45
	v_cndmask_b32_e32 v47, v158, v47, vcc
	v_max3_f32 v48, v49, v46, v47
	v_mov_b32_e32 v49, v48
	s_nop 1
	v_permlane16_swap_b32_e32 v49, v48
	s_waitcnt lgkmcnt(0)
	v_max3_f32 v48, v48, v49, v158
	v_mov_b32_e32 v49, v48
	s_nop 1
	v_permlane32_swap_b32_e32 v49, v48
	s_waitcnt lgkmcnt(0)
	v_max3_f32 v48, v48, v49, v158
	v_cmp_lt_f32_e32 vcc, s86, v32
	v_max3_f32 v163, v155, v48, v158
	s_mov_b64 s[2:3], -1
	v_sub_f32_e32 v48, v32, v163
	v_exp_f32_e32 v48, v48
	v_sub_f32_e32 v49, v33, v163
	v_exp_f32_e32 v49, v49
	v_cndmask_b32_e32 v56, 0, v48, vcc
	v_cmp_lt_f32_e32 vcc, s86, v33
	v_sub_f32_e32 v33, v34, v163
	v_exp_f32_e32 v33, v33
	v_cndmask_b32_e32 v57, 0, v49, vcc
	v_sub_f32_e32 v48, v35, v163
	v_cmp_lt_f32_e32 vcc, s86, v34
	v_exp_f32_e32 v48, v48
	v_sub_f32_e32 v34, v37, v163
	v_cndmask_b32_e32 v60, 0, v33, vcc
	v_sub_f32_e32 v33, v36, v163
	v_exp_f32_e32 v33, v33
	v_exp_f32_e32 v34, v34
	v_cmp_lt_f32_e32 vcc, s86, v35
	v_add_f32_e32 v32, 0, v56
	v_add_f32_e32 v32, v57, v32
	v_cndmask_b32_e32 v61, 0, v48, vcc
	v_cmp_lt_f32_e32 vcc, s86, v36
	v_add_f32_e32 v32, v60, v32
	v_add_f32_e32 v32, v61, v32
	v_cndmask_b32_e32 v62, 0, v33, vcc
	v_cmp_lt_f32_e32 vcc, s86, v37
	v_sub_f32_e32 v33, v38, v163
	v_exp_f32_e32 v33, v33
	v_cndmask_b32_e32 v63, 0, v34, vcc
	v_sub_f32_e32 v34, v39, v163
	v_exp_f32_e32 v34, v34
	v_cmp_lt_f32_e32 vcc, s86, v38
	v_add_f32_e32 v32, v62, v32
	v_add_f32_e32 v32, v63, v32
	v_cndmask_b32_e32 v64, 0, v33, vcc
	v_cmp_lt_f32_e32 vcc, s86, v39
	v_sub_f32_e32 v33, v40, v163
	v_exp_f32_e32 v33, v33
	v_cndmask_b32_e32 v65, 0, v34, vcc
	v_sub_f32_e32 v34, v41, v163
	v_exp_f32_e32 v34, v34
	v_cmp_lt_f32_e32 vcc, s86, v40
	v_add_f32_e32 v32, v64, v32
	v_add_f32_e32 v32, v65, v32
	v_cndmask_b32_e32 v49, 0, v33, vcc
	v_cmp_lt_f32_e32 vcc, s86, v41
	v_sub_f32_e32 v33, v42, v163
	v_exp_f32_e32 v33, v33
	v_cndmask_b32_e32 v50, 0, v34, vcc
	v_sub_f32_e32 v34, v43, v163
	v_exp_f32_e32 v34, v34
	v_cmp_lt_f32_e32 vcc, s86, v42
	v_add_f32_e32 v32, v49, v32
	v_add_f32_e32 v32, v50, v32
	v_cndmask_b32_e32 v51, 0, v33, vcc
	v_cmp_lt_f32_e32 vcc, s86, v43
	v_sub_f32_e32 v33, v44, v163
	v_exp_f32_e32 v33, v33
	v_cndmask_b32_e32 v53, 0, v34, vcc
	v_sub_f32_e32 v34, v45, v163
	v_exp_f32_e32 v34, v34
	v_cmp_lt_f32_e32 vcc, s86, v44
	v_add_f32_e32 v32, v51, v32
	v_add_f32_e32 v32, v53, v32
	v_cndmask_b32_e32 v54, 0, v33, vcc
	v_cmp_lt_f32_e32 vcc, s86, v45
	v_sub_f32_e32 v33, v46, v163
	v_exp_f32_e32 v33, v33
	v_cndmask_b32_e32 v55, 0, v34, vcc
	v_sub_f32_e32 v34, v47, v163
	v_exp_f32_e32 v34, v34
	v_add_f32_e32 v32, v54, v32
	v_cmp_lt_f32_e32 vcc, s86, v46
	v_add_f32_e32 v32, v55, v32
	s_nop 0
	v_cndmask_b32_e32 v58, 0, v33, vcc
	v_cmp_lt_f32_e32 vcc, s86, v47
	v_add_f32_e32 v32, v58, v32
	s_nop 0
	v_cndmask_b32_e32 v59, 0, v34, vcc
	v_add_f32_e32 v32, v59, v32
	v_mov_b32_e32 v33, v32
	s_nop 1
	v_permlane16_swap_b32_e32 v33, v32
	v_sub_f32_e32 v34, v155, v163
	v_exp_f32_e32 v48, v34
	s_waitcnt lgkmcnt(0)
	v_add_f32_e32 v66, v32, v33
	v_mov_b32_e32 v67, v66
	s_nop 1
	v_permlane32_swap_b32_e32 v67, v66
	v_cmp_eq_f32_e32 vcc, 1.0, v48
	s_cmp_lg_u64 vcc, exec
	s_cbranch_scc0 .LBB0_1295
	v_pk_mul_f32 v[46:47], v[18:19], v[48:49] op_sel_hi:[1,0]
	v_pk_mul_f32 v[44:45], v[16:17], v[48:49] op_sel_hi:[1,0]
	v_pk_mul_f32 v[42:43], v[22:23], v[48:49] op_sel_hi:[1,0]
	v_pk_mul_f32 v[40:41], v[20:21], v[48:49] op_sel_hi:[1,0]
	v_pk_mul_f32 v[38:39], v[26:27], v[48:49] op_sel_hi:[1,0]
	v_pk_mul_f32 v[36:37], v[24:25], v[48:49] op_sel_hi:[1,0]
	v_pk_mul_f32 v[34:35], v[30:31], v[48:49] op_sel_hi:[1,0]
	v_pk_mul_f32 v[32:33], v[28:29], v[48:49] op_sel_hi:[1,0]
	s_mov_b64 s[2:3], 0

.LBB0_1299:
	s_andn2_b64 vcc, exec, s[74:75]
	s_cbranch_vccnz .LBB0_1305
	s_nop 4
	v_mad_u32_u24 v44, v137, s88, v136
	ds_read_b128 v[32:35], v44
	ds_read_b128 v[40:43], v44 offset:64
	ds_read_b128 v[36:39], v44 offset:2304
	s_waitcnt lgkmcnt(3)
	v_mad_u32_u24 v48, v135, s88, v136
	s_mov_b64 s[2:3], -1
	s_waitcnt lgkmcnt(2)
	v_mfma_f32_16x16x32_bf16 v[32:35], v[32:35], v[96:99], 0
	s_waitcnt lgkmcnt(1)
	v_mfma_f32_16x16x32_bf16 v[32:35], v[40:43], v[100:103], v[32:35]
	ds_read_b128 v[40:43], v44 offset:2368
	s_waitcnt lgkmcnt(1)
	v_mfma_f32_16x16x32_bf16 v[36:39], v[36:39], v[96:99], 0
	s_waitcnt lgkmcnt(0)
	v_mfma_f32_16x16x32_bf16 v[36:39], v[40:43], v[100:103], v[36:39]
	ds_read_b128 v[40:43], v44 offset:4608
	ds_read_b128 v[44:47], v44 offset:4672
	s_waitcnt lgkmcnt(1)
	v_mfma_f32_16x16x32_bf16 v[40:43], v[40:43], v[96:99], 0
	s_waitcnt lgkmcnt(0)
	v_mfma_f32_16x16x32_bf16 v[40:43], v[44:47], v[100:103], v[40:43]
	ds_read_b128 v[44:47], v48
	ds_read_b128 v[48:51], v48 offset:64
	s_waitcnt lgkmcnt(1)
	v_mfma_f32_16x16x32_bf16 v[44:47], v[44:47], v[96:99], 0
	s_waitcnt lgkmcnt(0)
	v_mfma_f32_16x16x32_bf16 v[44:47], v[48:51], v[100:103], v[44:47]
	s_nop 7
	s_nop 0
	v_max3_f32 v48, v158, v32, v33
	v_max3_f32 v48, v48, v34, v35
	v_max3_f32 v48, v48, v36, v37
	v_max3_f32 v48, v48, v38, v39
	v_max3_f32 v48, v48, v40, v41
	v_max3_f32 v48, v48, v42, v43
	v_max3_f32 v48, v48, v44, v45
	v_max3_f32 v48, v48, v46, v47
	v_mov_b32_e32 v49, v48
	s_nop 1
	v_permlane16_swap_b32_e32 v49, v48
	s_waitcnt lgkmcnt(0)
	v_max3_f32 v48, v48, v49, v158
	v_mov_b32_e32 v49, v48
	s_nop 1
	v_permlane32_swap_b32_e32 v49, v48
	s_waitcnt lgkmcnt(0)
	v_max3_f32 v48, v48, v49, v158
	v_max3_f32 v163, v155, v48, v158
	s_nop 0
	v_sub_f32_e32 v35, v35, v163
	v_sub_f32_e32 v34, v34, v163
	v_sub_f32_e32 v33, v33, v163
	v_sub_f32_e32 v32, v32, v163
	v_sub_f32_e32 v39, v39, v163
	v_sub_f32_e32 v38, v38, v163
	v_exp_f32_e32 v56, v32
	v_exp_f32_e32 v57, v33
	v_exp_f32_e32 v58, v34
	v_exp_f32_e32 v59, v35
	v_sub_f32_e32 v32, v37, v163
	v_sub_f32_e32 v33, v36, v163
	v_exp_f32_e32 v60, v33
	v_exp_f32_e32 v62, v38
	v_exp_f32_e32 v63, v39
	v_exp_f32_e32 v61, v32
	v_sub_f32_e32 v36, v43, v163
	v_sub_f32_e32 v37, v42, v163
	v_sub_f32_e32 v38, v41, v163
	v_sub_f32_e32 v39, v40, v163
	v_exp_f32_e32 v48, v39
	v_exp_f32_e32 v49, v38
	v_exp_f32_e32 v50, v37
	v_exp_f32_e32 v51, v36
	v_sub_f32_e32 v36, v47, v163
	v_sub_f32_e32 v37, v46, v163
	v_sub_f32_e32 v38, v45, v163
	v_sub_f32_e32 v39, v44, v163
	v_exp_f32_e32 v52, v39
	v_exp_f32_e32 v54, v37
	v_exp_f32_e32 v55, v36
	v_exp_f32_e32 v53, v38
	v_pk_add_f32 v[32:33], v[56:57], 0 op_sel_hi:[1,0]
	v_pk_add_f32 v[34:35], v[58:59], 0 op_sel_hi:[1,0]
	v_pk_add_f32 v[32:33], v[60:61], v[32:33]
	v_pk_add_f32 v[34:35], v[62:63], v[34:35]
	v_pk_add_f32 v[32:33], v[48:49], v[32:33]
	v_pk_add_f32 v[34:35], v[50:51], v[34:35]
	v_pk_add_f32 v[32:33], v[52:53], v[32:33]
	v_pk_add_f32 v[34:35], v[54:55], v[34:35]
	v_add_f32_e32 v32, v32, v33
	v_add_f32_e32 v33, v34, v35
	v_add_f32_e32 v32, v32, v33
	v_mov_b32_e32 v33, v32
	s_nop 1
	v_permlane16_swap_b32_e32 v33, v32
	v_sub_f32_e32 v34, v155, v163
	v_exp_f32_e32 v64, v34
	s_waitcnt lgkmcnt(0)
	v_add_f32_e32 v65, v32, v33
	ds_bpermute_b32 v66, v217, v65
	v_cmp_eq_f32_e32 vcc, 1.0, v64
	s_cmp_lg_u64 vcc, exec
	s_cbranch_scc0 .LBB0_1302
	v_pk_mul_f32 v[46:47], v[18:19], v[64:65] op_sel_hi:[1,0]
	v_pk_mul_f32 v[44:45], v[16:17], v[64:65] op_sel_hi:[1,0]
	v_pk_mul_f32 v[42:43], v[22:23], v[64:65] op_sel_hi:[1,0]
	v_pk_mul_f32 v[40:41], v[20:21], v[64:65] op_sel_hi:[1,0]
	v_pk_mul_f32 v[38:39], v[26:27], v[64:65] op_sel_hi:[1,0]
	v_pk_mul_f32 v[36:37], v[24:25], v[64:65] op_sel_hi:[1,0]
	v_pk_mul_f32 v[34:35], v[30:31], v[64:65] op_sel_hi:[1,0]
	v_pk_mul_f32 v[32:33], v[28:29], v[64:65] op_sel_hi:[1,0]
	s_mov_b64 s[2:3], 0

.LBB0_1307:
	v_and_b32_e32 v16, s14, v173
	v_cmp_ne_u32_e32 vcc, 0, v16
	s_cmp_eq_u64 vcc, 0
	s_cselect_b64 s[2:3], -1, 0
	s_cmp_gt_i32 s13, s77
	s_cselect_b64 s[14:15], -1, 0
	s_or_b64 s[2:3], s[2:3], s[14:15]
	v_mov_b32_e32 v181, v196
	s_and_b64 vcc, exec, s[2:3]
	s_cbranch_vccnz .LBB0_1330
	v_cmp_eq_u32_e32 vcc, 0, v16
	s_or_b32 s14, s13, 63
	v_cmp_le_i32_e64 s[74:75], s14, v154
	v_cndmask_b32_e32 v186, 0, v211, vcc
	v_cmp_ge_u32_e64 s[2:3], s13, v186
	s_and_b64 s[2:3], s[2:3], s[74:75]
	v_and_b32_e32 v187, 63, v181
	v_cndmask_b32_e64 v16, 0, 1, s[2:3]
	v_cmp_ne_u32_e64 s[2:3], 0, v16
	v_and_b32_e32 v185, 15, v181
	v_and_b32_e32 v16, 48, v181
	v_or_b32_e32 v183, 48, v187
	s_mov_b64 s[74:75], -1
	s_cmp_lg_u64 s[2:3], exec
	v_add_u32_e32 v184, s96, v16
	v_mul_u32_u24_e32 v182, 0x90, v185
	v_mul_u32_u24_e32 v155, 0x90, v183
	s_cbranch_scc0 .LBB0_1322
	v_mad_u32_u24 v16, v185, s88, v184
	ds_read_b128 v[20:23], v16
	ds_read_b128 v[24:27], v16 offset:64
	s_waitcnt lgkmcnt(3)
	ds_read_b128 v[76:79], v16 offset:2304
	ds_read_b128 v[80:83], v16 offset:2368
	ds_read_b128 v[84:87], v16 offset:4608
	ds_read_b128 v[88:91], v16 offset:4672
	v_mad_u32_u24 v16, v183, s88, v184
	ds_read_b128 v[128:131], v16
	ds_read_b128 v[16:19], v16 offset:64
	s_cmp_gt_i32 s14, s93
	s_mov_b64 s[2:3], -1
	s_cbranch_scc1 .LBB0_1315
	s_waitcnt lgkmcnt(7)
	v_mfma_f32_16x16x32_bf16 v[44:47], v[20:23], v[104:107], 0
	s_waitcnt lgkmcnt(5)
	v_mfma_f32_16x16x32_bf16 v[48:51], v[76:79], v[104:107], 0
	s_waitcnt lgkmcnt(3)
	v_mfma_f32_16x16x32_bf16 v[52:55], v[84:87], v[104:107], 0
	s_waitcnt lgkmcnt(1)
	v_mfma_f32_16x16x32_bf16 v[56:59], v[128:131], v[104:107], 0
	v_mfma_f32_16x16x32_bf16 v[44:47], v[24:27], v[108:111], v[44:47]
	v_mfma_f32_16x16x32_bf16 v[48:51], v[80:83], v[108:111], v[48:51]
	v_mfma_f32_16x16x32_bf16 v[52:55], v[88:91], v[108:111], v[52:55]
	s_waitcnt lgkmcnt(0)
	v_mfma_f32_16x16x32_bf16 v[56:59], v[16:19], v[108:111], v[56:59]
	s_nop 7
	s_nop 0
	v_max3_f32 v92, v158, v44, v45
	v_max3_f32 v92, v92, v46, v47
	v_max3_f32 v92, v92, v48, v49
	v_max3_f32 v92, v92, v50, v51
	v_max3_f32 v92, v92, v52, v53
	v_max3_f32 v92, v92, v54, v55
	v_max3_f32 v92, v92, v56, v57
	v_max3_f32 v92, v92, v58, v59
	s_nop 0
	v_cndmask_b32_e32 v92, v92, v158, vcc
	v_mov_b32_e32 v132, v92
	s_nop 1
	v_permlane16_swap_b32_e32 v132, v92
	s_waitcnt lgkmcnt(0)
	v_max3_f32 v92, v92, v132, v158
	v_mov_b32_e32 v132, v92
	s_nop 1
	v_permlane32_swap_b32_e32 v132, v92
	s_waitcnt lgkmcnt(0)
	v_max3_f32 v92, v92, v132, v158
	v_max3_f32 v175, v153, v92, v158
	s_nop 0
	v_cndmask_b32_e32 v92, v175, v212, vcc
	v_sub_f32_e32 v47, v47, v92
	v_sub_f32_e32 v46, v46, v92
	v_sub_f32_e32 v45, v45, v92
	v_sub_f32_e32 v44, v44, v92
	v_sub_f32_e32 v51, v51, v92
	v_sub_f32_e32 v50, v50, v92
	v_exp_f32_e32 v140, v44
	v_exp_f32_e32 v141, v45
	v_exp_f32_e32 v142, v46
	v_exp_f32_e32 v143, v47
	v_sub_f32_e32 v44, v49, v92
	v_sub_f32_e32 v45, v48, v92
	v_exp_f32_e32 v144, v45
	v_exp_f32_e32 v146, v50
	v_exp_f32_e32 v147, v51
	v_exp_f32_e32 v145, v44
	v_sub_f32_e32 v48, v55, v92
	v_sub_f32_e32 v49, v54, v92
	v_sub_f32_e32 v50, v53, v92
	v_sub_f32_e32 v51, v52, v92
	v_exp_f32_e32 v132, v51
	v_exp_f32_e32 v133, v50
	v_exp_f32_e32 v134, v49
	v_exp_f32_e32 v135, v48
	v_sub_f32_e32 v48, v59, v92
	v_sub_f32_e32 v49, v58, v92
	v_sub_f32_e32 v50, v57, v92
	v_sub_f32_e32 v51, v56, v92
	v_exp_f32_e32 v136, v51
	v_exp_f32_e32 v138, v49
	v_exp_f32_e32 v139, v48
	v_exp_f32_e32 v137, v50
	v_pk_add_f32 v[44:45], v[140:141], 0 op_sel_hi:[1,0]
	v_pk_add_f32 v[46:47], v[142:143], 0 op_sel_hi:[1,0]
	v_pk_add_f32 v[44:45], v[144:145], v[44:45]
	v_pk_add_f32 v[46:47], v[146:147], v[46:47]
	v_pk_add_f32 v[44:45], v[132:133], v[44:45]
	v_pk_add_f32 v[46:47], v[134:135], v[46:47]
	v_pk_add_f32 v[44:45], v[136:137], v[44:45]
	v_pk_add_f32 v[46:47], v[138:139], v[46:47]
	v_add_f32_e32 v44, v44, v45
	v_add_f32_e32 v45, v46, v47
	v_add_f32_e32 v44, v44, v45
	v_mov_b32_e32 v45, v44
	s_nop 1
	v_permlane16_swap_b32_e32 v45, v44
	v_sub_f32_e32 v46, v153, v175
	v_exp_f32_e32 v92, v46
	s_waitcnt lgkmcnt(0)
	v_add_f32_e32 v188, v44, v45
	v_mov_b32_e32 v189, v188
	s_nop 1
	v_permlane32_swap_b32_e32 v189, v188
	v_cmp_eq_f32_e32 vcc, 1.0, v92
	s_cmp_lg_u64 vcc, exec
	s_cbranch_scc0 .LBB0_1312
	v_pk_mul_f32 v[58:59], v[2:3], v[92:93] op_sel_hi:[1,0]
	v_pk_mul_f32 v[56:57], v[0:1], v[92:93] op_sel_hi:[1,0]
	v_pk_mul_f32 v[54:55], v[6:7], v[92:93] op_sel_hi:[1,0]
	v_pk_mul_f32 v[52:53], v[4:5], v[92:93] op_sel_hi:[1,0]
	v_pk_mul_f32 v[50:51], v[10:11], v[92:93] op_sel_hi:[1,0]
	v_pk_mul_f32 v[48:49], v[8:9], v[92:93] op_sel_hi:[1,0]
	v_pk_mul_f32 v[46:47], v[14:15], v[92:93] op_sel_hi:[1,0]
	v_pk_mul_f32 v[44:45], v[12:13], v[92:93] op_sel_hi:[1,0]
	s_mov_b64 s[2:3], 0

.LBB0_1315:
	s_and_b64 vcc, exec, s[2:3]
	s_cbranch_vccz .LBB0_1321
	s_waitcnt lgkmcnt(7)
	v_mfma_f32_16x16x32_bf16 v[20:23], v[20:23], v[104:107], 0
	v_lshrrev_b32_e32 v49, 4, v187
	v_lshl_or_b32 v48, v49, 2, s13
	v_cmp_ge_u32_e32 vcc, v48, v186
	s_waitcnt lgkmcnt(6)
	v_mfma_f32_16x16x32_bf16 v[20:23], v[24:27], v[108:111], v[20:23]
	v_cmp_le_i32_e64 s[2:3], v48, v154
	s_and_b64 vcc, vcc, s[2:3]
	v_cmp_lt_i32_e64 s[2:3], v48, v154
	s_waitcnt lgkmcnt(5)
	v_mfma_f32_16x16x32_bf16 v[24:27], v[76:79], v[104:107], 0
	s_waitcnt lgkmcnt(3)
	v_mfma_f32_16x16x32_bf16 v[44:47], v[84:87], v[104:107], 0
	s_waitcnt lgkmcnt(1)
	v_mfma_f32_16x16x32_bf16 v[50:53], v[128:131], v[104:107], 0
	v_mfma_f32_16x16x32_bf16 v[24:27], v[80:83], v[108:111], v[24:27]
	v_mfma_f32_16x16x32_bf16 v[44:47], v[88:91], v[108:111], v[44:47]
	s_waitcnt lgkmcnt(0)
	v_mfma_f32_16x16x32_bf16 v[16:19], v[16:19], v[108:111], v[50:53]
	s_nop 7
	s_nop 0
	v_cndmask_b32_e32 v20, v158, v20, vcc
	s_nop 1
	v_or_b32_e32 v50, 1, v48
	v_cmp_ge_u32_e32 vcc, v50, v186
	s_and_b64 vcc, s[2:3], vcc
	v_or_b32_e32 v51, 2, v48
	v_cndmask_b32_e32 v21, v158, v21, vcc
	v_cmp_ge_u32_e32 vcc, v51, v186
	v_cmp_le_i32_e64 s[2:3], v48, v152
	s_and_b64 vcc, s[2:3], vcc
	v_or_b32_e32 v51, 3, v48
	v_cndmask_b32_e32 v22, v158, v22, vcc
	v_cmp_ge_u32_e32 vcc, v51, v186
	v_cmp_le_i32_e64 s[2:3], v51, v154
	s_and_b64 vcc, vcc, s[2:3]
	v_or_b32_e32 v51, 16, v48
	v_cndmask_b32_e32 v23, v158, v23, vcc
	v_cmp_ge_u32_e32 vcc, v51, v186
	v_cmp_le_i32_e64 s[2:3], v51, v154
	s_and_b64 vcc, vcc, s[2:3]
	v_or_b32_e32 v51, 17, v48
	v_cndmask_b32_e32 v24, v158, v24, vcc
	v_cmp_ge_u32_e32 vcc, v51, v186
	v_cmp_le_i32_e64 s[2:3], v51, v154
	s_and_b64 vcc, vcc, s[2:3]
	v_or_b32_e32 v51, 18, v48
	v_cndmask_b32_e32 v25, v158, v25, vcc
	v_cmp_ge_u32_e32 vcc, v51, v186
	v_cmp_le_i32_e64 s[2:3], v51, v154
	s_and_b64 vcc, vcc, s[2:3]
	v_or_b32_e32 v51, 19, v48
	v_cndmask_b32_e32 v26, v158, v26, vcc
	v_cmp_ge_u32_e32 vcc, v51, v186
	v_cmp_le_i32_e64 s[2:3], v51, v154
	s_and_b64 vcc, vcc, s[2:3]
	v_or_b32_e32 v51, 32, v48
	v_cndmask_b32_e32 v27, v158, v27, vcc
	v_cmp_ge_u32_e32 vcc, v51, v186
	v_cmp_le_i32_e64 s[2:3], v51, v154
	s_and_b64 vcc, vcc, s[2:3]
	v_or_b32_e32 v51, 33, v48
	v_cndmask_b32_e32 v44, v158, v44, vcc
	v_cmp_ge_u32_e32 vcc, v51, v186
	v_cmp_le_i32_e64 s[2:3], v51, v154
	s_and_b64 vcc, vcc, s[2:3]
	v_or_b32_e32 v51, 34, v48
	v_cndmask_b32_e32 v45, v158, v45, vcc
	v_cmp_ge_u32_e32 vcc, v51, v186
	v_cmp_le_i32_e64 s[2:3], v51, v154
	s_and_b64 vcc, vcc, s[2:3]
	v_or_b32_e32 v51, 35, v48
	v_cndmask_b32_e32 v46, v158, v46, vcc
	v_cmp_ge_u32_e32 vcc, v51, v186
	v_cmp_le_i32_e64 s[2:3], v51, v154
	s_and_b64 vcc, vcc, s[2:3]
	v_or_b32_e32 v51, 48, v48
	v_cndmask_b32_e32 v47, v158, v47, vcc
	v_cmp_ge_u32_e32 vcc, v51, v186
	v_cmp_le_i32_e64 s[2:3], v51, v154
	s_and_b64 vcc, vcc, s[2:3]
	v_or_b32_e32 v51, 49, v48
	v_max3_f32 v50, v20, s87, v21
	v_cndmask_b32_e32 v16, v158, v16, vcc
	v_cmp_ge_u32_e32 vcc, v51, v186
	v_cmp_le_i32_e64 s[2:3], v51, v154
	v_max3_f32 v50, v50, v22, v23
	s_and_b64 vcc, vcc, s[2:3]
	v_or_b32_e32 v51, 50, v48
	v_max3_f32 v50, v50, v24, v25
	v_cndmask_b32_e32 v17, v158, v17, vcc
	v_cmp_ge_u32_e32 vcc, v51, v186
	v_cmp_le_i32_e64 s[2:3], v51, v154
	v_max3_f32 v50, v50, v26, v27
	s_and_b64 vcc, vcc, s[2:3]
	v_or_b32_e32 v48, 51, v48
	v_max3_f32 v50, v50, v44, v45
	v_cndmask_b32_e32 v18, v158, v18, vcc
	v_cmp_ge_u32_e32 vcc, v48, v186
	v_cmp_le_i32_e64 s[2:3], v48, v154
	v_max3_f32 v50, v50, v46, v47
	s_and_b64 vcc, vcc, s[2:3]
	v_max3_f32 v50, v50, v16, v17
	v_cndmask_b32_e32 v19, v158, v19, vcc
	v_max3_f32 v48, v50, v18, v19
	v_mov_b32_e32 v50, v48
	s_nop 1
	v_permlane16_swap_b32_e32 v50, v48
	s_waitcnt lgkmcnt(0)
	v_max3_f32 v48, v48, v50, v158
	v_mov_b32_e32 v50, v48
	s_nop 1
	v_permlane32_swap_b32_e32 v50, v48
	s_waitcnt lgkmcnt(0)
	v_max3_f32 v48, v48, v50, v158
	v_cmp_lt_f32_e32 vcc, s86, v20
	v_max3_f32 v175, v153, v48, v158
	s_mov_b64 s[2:3], -1
	v_sub_f32_e32 v48, v20, v175
	v_exp_f32_e32 v48, v48
	v_sub_f32_e32 v50, v21, v175
	v_exp_f32_e32 v50, v50
	v_cndmask_b32_e32 v56, 0, v48, vcc
	v_cmp_lt_f32_e32 vcc, s86, v21
	v_sub_f32_e32 v21, v22, v175
	v_exp_f32_e32 v21, v21
	v_cndmask_b32_e32 v57, 0, v50, vcc
	v_sub_f32_e32 v48, v23, v175
	v_cmp_lt_f32_e32 vcc, s86, v22
	v_exp_f32_e32 v48, v48
	v_sub_f32_e32 v22, v25, v175
	v_cndmask_b32_e32 v76, 0, v21, vcc
	v_sub_f32_e32 v21, v24, v175
	v_exp_f32_e32 v21, v21
	v_cmp_lt_f32_e32 vcc, s86, v23
	v_exp_f32_e32 v22, v22
	v_add_f32_e32 v20, 0, v56
	v_cndmask_b32_e32 v77, 0, v48, vcc
	v_cmp_lt_f32_e32 vcc, s86, v24
	v_add_f32_e32 v20, v57, v20
	v_add_f32_e32 v20, v76, v20
	v_cndmask_b32_e32 v78, 0, v21, vcc
	v_sub_f32_e32 v21, v26, v175
	v_exp_f32_e32 v21, v21
	v_cmp_lt_f32_e32 vcc, s86, v25
	v_add_f32_e32 v20, v77, v20
	v_add_f32_e32 v20, v78, v20
	v_cndmask_b32_e32 v79, 0, v22, vcc
	v_sub_f32_e32 v22, v27, v175
	v_cmp_lt_f32_e32 vcc, s86, v26
	v_exp_f32_e32 v22, v22
	v_add_f32_e32 v20, v79, v20
	v_cndmask_b32_e32 v80, 0, v21, vcc
	v_sub_f32_e32 v21, v44, v175
	v_exp_f32_e32 v21, v21
	v_cmp_lt_f32_e32 vcc, s86, v27
	v_add_f32_e32 v20, v80, v20
	s_nop 0
	v_cndmask_b32_e32 v81, 0, v22, vcc
	v_sub_f32_e32 v22, v45, v175
	v_cmp_lt_f32_e32 vcc, s86, v44
	v_exp_f32_e32 v22, v22
	v_add_f32_e32 v20, v81, v20
	v_cndmask_b32_e32 v50, 0, v21, vcc
	v_sub_f32_e32 v21, v46, v175
	v_exp_f32_e32 v21, v21
	v_cmp_lt_f32_e32 vcc, s86, v45
	v_add_f32_e32 v20, v50, v20
	s_nop 0
	v_cndmask_b32_e32 v51, 0, v22, vcc
	v_sub_f32_e32 v22, v47, v175
	v_cmp_lt_f32_e32 vcc, s86, v46
	v_exp_f32_e32 v22, v22
	v_add_f32_e32 v20, v51, v20
	v_cndmask_b32_e32 v52, 0, v21, vcc
	v_sub_f32_e32 v21, v16, v175
	v_exp_f32_e32 v21, v21
	v_cmp_lt_f32_e32 vcc, s86, v47
	v_add_f32_e32 v20, v52, v20
	s_nop 0
	v_cndmask_b32_e32 v53, 0, v22, vcc
	v_sub_f32_e32 v22, v17, v175
	v_cmp_lt_f32_e32 vcc, s86, v16
	v_add_f32_e32 v20, v53, v20
	v_exp_f32_e32 v22, v22
	v_cndmask_b32_e32 v54, 0, v21, vcc
	v_cmp_lt_f32_e32 vcc, s86, v17
	v_sub_f32_e32 v17, v18, v175
	v_add_f32_e32 v16, v54, v20
	v_exp_f32_e32 v17, v17
	v_sub_f32_e32 v20, v19, v175
	v_exp_f32_e32 v20, v20
	v_cndmask_b32_e32 v55, 0, v22, vcc
	v_cmp_lt_f32_e32 vcc, s86, v18
	v_add_f32_e32 v16, v55, v16
	v_sub_f32_e32 v18, v153, v175
	v_cndmask_b32_e32 v58, 0, v17, vcc
	v_cmp_lt_f32_e32 vcc, s86, v19
	v_add_f32_e32 v16, v58, v16
	v_exp_f32_e32 v48, v18
	v_cndmask_b32_e32 v59, 0, v20, vcc
	v_add_f32_e32 v16, v59, v16
	v_mov_b32_e32 v17, v16
	s_nop 1
	v_permlane16_swap_b32_e32 v17, v16
	v_cmp_eq_f32_e32 vcc, 1.0, v48
	s_cmp_lg_u64 vcc, exec
	s_waitcnt lgkmcnt(0)
	v_add_f32_e32 v82, v16, v17
	v_mov_b32_e32 v83, v82
	s_nop 1
	v_permlane32_swap_b32_e32 v83, v82
	s_cbranch_scc0 .LBB0_1318
	v_pk_mul_f32 v[46:47], v[2:3], v[48:49] op_sel_hi:[1,0]
	v_pk_mul_f32 v[44:45], v[0:1], v[48:49] op_sel_hi:[1,0]
	v_pk_mul_f32 v[26:27], v[6:7], v[48:49] op_sel_hi:[1,0]
	v_pk_mul_f32 v[24:25], v[4:5], v[48:49] op_sel_hi:[1,0]
	v_pk_mul_f32 v[22:23], v[10:11], v[48:49] op_sel_hi:[1,0]
	v_pk_mul_f32 v[20:21], v[8:9], v[48:49] op_sel_hi:[1,0]
	v_pk_mul_f32 v[18:19], v[14:15], v[48:49] op_sel_hi:[1,0]
	v_pk_mul_f32 v[16:17], v[12:13], v[48:49] op_sel_hi:[1,0]
	s_mov_b64 s[2:3], 0

.LBB0_1322:
	s_andn2_b64 vcc, exec, s[74:75]
	s_cbranch_vccnz .LBB0_1328
	v_mad_u32_u24 v44, v185, s88, v184
	s_waitcnt lgkmcnt(0)
	ds_read_b128 v[16:19], v44
	ds_read_b128 v[24:27], v44 offset:64
	ds_read_b128 v[20:23], v44 offset:2304
	v_mad_u32_u24 v48, v183, s88, v184
	s_mov_b64 s[2:3], -1
	s_waitcnt lgkmcnt(2)
	v_mfma_f32_16x16x32_bf16 v[16:19], v[16:19], v[104:107], 0
	s_waitcnt lgkmcnt(1)
	v_mfma_f32_16x16x32_bf16 v[16:19], v[24:27], v[108:111], v[16:19]
	ds_read_b128 v[24:27], v44 offset:2368
	s_waitcnt lgkmcnt(1)
	v_mfma_f32_16x16x32_bf16 v[20:23], v[20:23], v[104:107], 0
	s_waitcnt lgkmcnt(0)
	v_mfma_f32_16x16x32_bf16 v[20:23], v[24:27], v[108:111], v[20:23]
	ds_read_b128 v[24:27], v44 offset:4608
	ds_read_b128 v[44:47], v44 offset:4672
	s_waitcnt lgkmcnt(1)
	v_mfma_f32_16x16x32_bf16 v[24:27], v[24:27], v[104:107], 0
	s_waitcnt lgkmcnt(0)
	v_mfma_f32_16x16x32_bf16 v[24:27], v[44:47], v[108:111], v[24:27]
	ds_read_b128 v[44:47], v48
	ds_read_b128 v[48:51], v48 offset:64
	s_waitcnt lgkmcnt(1)
	v_mfma_f32_16x16x32_bf16 v[44:47], v[44:47], v[104:107], 0
	s_waitcnt lgkmcnt(0)
	v_mfma_f32_16x16x32_bf16 v[44:47], v[48:51], v[108:111], v[44:47]
	s_nop 7
	s_nop 0
	v_max3_f32 v48, v158, v16, v17
	v_max3_f32 v48, v48, v18, v19
	v_max3_f32 v48, v48, v20, v21
	v_max3_f32 v48, v48, v22, v23
	v_max3_f32 v48, v48, v24, v25
	v_max3_f32 v48, v48, v26, v27
	v_max3_f32 v48, v48, v44, v45
	v_max3_f32 v48, v48, v46, v47
	v_mov_b32_e32 v49, v48
	s_nop 1
	v_permlane16_swap_b32_e32 v49, v48
	s_waitcnt lgkmcnt(0)
	v_max3_f32 v48, v48, v49, v158
	v_mov_b32_e32 v49, v48
	s_nop 1
	v_permlane32_swap_b32_e32 v49, v48
	s_waitcnt lgkmcnt(0)
	v_max3_f32 v48, v48, v49, v158
	v_max3_f32 v175, v153, v48, v158
	s_nop 0
	v_sub_f32_e32 v19, v19, v175
	v_sub_f32_e32 v18, v18, v175
	v_sub_f32_e32 v17, v17, v175
	v_sub_f32_e32 v16, v16, v175
	v_sub_f32_e32 v23, v23, v175
	v_sub_f32_e32 v22, v22, v175
	v_exp_f32_e32 v56, v16
	v_exp_f32_e32 v57, v17
	v_exp_f32_e32 v58, v18
	v_exp_f32_e32 v59, v19
	v_sub_f32_e32 v16, v21, v175
	v_sub_f32_e32 v17, v20, v175
	v_exp_f32_e32 v76, v17
	v_exp_f32_e32 v78, v22
	v_exp_f32_e32 v79, v23
	v_exp_f32_e32 v77, v16
	v_sub_f32_e32 v20, v27, v175
	v_sub_f32_e32 v21, v26, v175
	v_sub_f32_e32 v22, v25, v175
	v_sub_f32_e32 v23, v24, v175
	v_exp_f32_e32 v48, v23
	v_exp_f32_e32 v49, v22
	v_exp_f32_e32 v50, v21
	v_exp_f32_e32 v51, v20
	v_sub_f32_e32 v20, v47, v175
	v_sub_f32_e32 v21, v46, v175
	v_sub_f32_e32 v22, v45, v175
	v_sub_f32_e32 v23, v44, v175
	v_exp_f32_e32 v52, v23
	v_exp_f32_e32 v54, v21
	v_exp_f32_e32 v55, v20
	v_exp_f32_e32 v53, v22
	v_pk_add_f32 v[16:17], v[56:57], 0 op_sel_hi:[1,0]
	v_pk_add_f32 v[18:19], v[58:59], 0 op_sel_hi:[1,0]
	v_pk_add_f32 v[16:17], v[76:77], v[16:17]
	v_pk_add_f32 v[18:19], v[78:79], v[18:19]
	v_pk_add_f32 v[16:17], v[48:49], v[16:17]
	v_pk_add_f32 v[18:19], v[50:51], v[18:19]
	v_pk_add_f32 v[16:17], v[52:53], v[16:17]
	v_pk_add_f32 v[18:19], v[54:55], v[18:19]
	v_add_f32_e32 v16, v16, v17
	v_add_f32_e32 v17, v18, v19
	v_add_f32_e32 v16, v16, v17
	v_mov_b32_e32 v17, v16
	s_nop 1
	v_permlane16_swap_b32_e32 v17, v16
	v_sub_f32_e32 v18, v153, v175
	v_exp_f32_e32 v80, v18
	s_waitcnt lgkmcnt(0)
	v_add_f32_e32 v81, v16, v17
	ds_bpermute_b32 v82, v217, v81
	v_cmp_eq_f32_e32 vcc, 1.0, v80
	s_cmp_lg_u64 vcc, exec
	s_cbranch_scc0 .LBB0_1325
	v_pk_mul_f32 v[46:47], v[2:3], v[80:81] op_sel_hi:[1,0]
	v_pk_mul_f32 v[44:45], v[0:1], v[80:81] op_sel_hi:[1,0]
	v_pk_mul_f32 v[26:27], v[6:7], v[80:81] op_sel_hi:[1,0]
	v_pk_mul_f32 v[24:25], v[4:5], v[80:81] op_sel_hi:[1,0]
	v_pk_mul_f32 v[22:23], v[10:11], v[80:81] op_sel_hi:[1,0]
	v_pk_mul_f32 v[20:21], v[8:9], v[80:81] op_sel_hi:[1,0]
	v_pk_mul_f32 v[18:19], v[14:15], v[80:81] op_sel_hi:[1,0]
	v_pk_mul_f32 v[16:17], v[12:13], v[80:81] op_sel_hi:[1,0]
	s_mov_b64 s[2:3], 0

.LBB0_1331:
	s_lshl_b32 s13, s4, 6
	s_lshl_b32 s4, 1, s4
	v_and_b32_e32 v0, s4, v172
	v_cmp_ne_u32_e32 vcc, 0, v0
	s_cmp_eq_u64 vcc, 0
	s_cselect_b64 s[2:3], -1, 0
	s_cmp_gt_i32 s13, s76
	s_cselect_b64 s[14:15], -1, 0
	s_or_b64 s[2:3], s[2:3], s[14:15]
	v_mov_b32_e32 v222, v196
	s_and_b64 vcc, exec, s[2:3]
	s_cbranch_vccnz .LBB0_1353
	v_cmp_eq_u32_e32 vcc, 0, v0
	s_or_b32 s14, s13, 63
	v_cmp_le_i32_e64 s[74:75], s14, v152
	v_cndmask_b32_e32 v227, 0, v211, vcc
	v_cmp_ge_u32_e64 s[2:3], s13, v227
	s_and_b64 s[2:3], s[2:3], s[74:75]
	v_and_b32_e32 v228, 63, v222
	v_cndmask_b32_e64 v0, 0, 1, s[2:3]
	v_cmp_ne_u32_e64 s[2:3], 0, v0
	v_and_b32_e32 v226, 15, v222
	v_and_b32_e32 v0, 48, v222
	v_or_b32_e32 v224, 48, v228
	s_mov_b64 s[74:75], -1
	s_cmp_lg_u64 s[2:3], exec
	v_add_u32_e32 v225, s96, v0
	v_mul_u32_u24_e32 v223, 0x90, v226
	v_mul_u32_u24_e32 v153, 0x90, v224
	s_cbranch_scc0 .LBB0_1346
	v_mad_u32_u24 v0, v226, s88, v225
	ds_read_b128 v[4:7], v0 offset:9216
	ds_read_b128 v[8:11], v0 offset:9280
	ds_read_b128 v[56:59], v0 offset:11520
	ds_read_b128 v[128:131], v0 offset:11584
	ds_read_b128 v[132:135], v0 offset:13824
	ds_read_b128 v[136:139], v0 offset:13888
	v_mad_u32_u24 v0, v224, s88, v225
	ds_read_b128 v[140:143], v0 offset:9216
	ds_read_b128 v[0:3], v0 offset:9280
	s_cmp_gt_i32 s14, s78
	s_mov_b64 s[2:3], -1
	s_cbranch_scc1 .LBB0_1339
	s_waitcnt lgkmcnt(7)
	v_mfma_f32_16x16x32_bf16 v[16:19], v[4:7], v[96:99], 0
	s_waitcnt lgkmcnt(5)
	v_mfma_f32_16x16x32_bf16 v[20:23], v[56:59], v[96:99], 0
	s_waitcnt lgkmcnt(3)
	v_mfma_f32_16x16x32_bf16 v[24:27], v[132:135], v[96:99], 0
	s_waitcnt lgkmcnt(1)
	v_mfma_f32_16x16x32_bf16 v[144:147], v[140:143], v[96:99], 0
	v_mfma_f32_16x16x32_bf16 v[16:19], v[8:11], v[100:103], v[16:19]
	v_mfma_f32_16x16x32_bf16 v[20:23], v[128:131], v[100:103], v[20:23]
	v_mfma_f32_16x16x32_bf16 v[24:27], v[136:139], v[100:103], v[24:27]
	s_waitcnt lgkmcnt(0)
	v_mfma_f32_16x16x32_bf16 v[144:147], v[0:3], v[100:103], v[144:147]
	s_nop 7
	s_nop 0
	v_max3_f32 v92, v158, v16, v17
	v_max3_f32 v92, v92, v18, v19
	v_max3_f32 v92, v92, v20, v21
	v_max3_f32 v92, v92, v22, v23
	v_max3_f32 v92, v92, v24, v25
	v_max3_f32 v92, v92, v26, v27
	v_max3_f32 v92, v92, v144, v145
	v_max3_f32 v92, v92, v146, v147
	s_nop 0
	v_cndmask_b32_e32 v92, v92, v158, vcc
	v_mov_b32_e32 v155, v92
	s_nop 1
	v_permlane16_swap_b32_e32 v155, v92
	s_waitcnt lgkmcnt(0)
	v_max3_f32 v92, v92, v155, v158
	v_mov_b32_e32 v155, v92
	s_nop 1
	v_permlane32_swap_b32_e32 v155, v92
	s_waitcnt lgkmcnt(0)
	v_max3_f32 v92, v92, v155, v158
	v_max3_f32 v155, v163, v92, v158
	s_nop 0
	v_cndmask_b32_e32 v92, v155, v212, vcc
	v_sub_f32_e32 v19, v19, v92
	v_sub_f32_e32 v18, v18, v92
	v_sub_f32_e32 v17, v17, v92
	v_sub_f32_e32 v16, v16, v92
	v_sub_f32_e32 v23, v23, v92
	v_sub_f32_e32 v22, v22, v92
	v_exp_f32_e32 v188, v16
	v_exp_f32_e32 v189, v17
	v_exp_f32_e32 v190, v18
	v_exp_f32_e32 v191, v19
	v_sub_f32_e32 v16, v21, v92
	v_sub_f32_e32 v17, v20, v92
	v_exp_f32_e32 v192, v17
	v_exp_f32_e32 v194, v22
	v_exp_f32_e32 v195, v23
	v_exp_f32_e32 v193, v16
	v_sub_f32_e32 v20, v27, v92
	v_sub_f32_e32 v21, v26, v92
	v_sub_f32_e32 v22, v25, v92
	v_sub_f32_e32 v23, v24, v92
	v_exp_f32_e32 v180, v23
	v_exp_f32_e32 v181, v22
	v_exp_f32_e32 v182, v21
	v_exp_f32_e32 v183, v20
	v_sub_f32_e32 v20, v147, v92
	v_sub_f32_e32 v21, v146, v92
	v_sub_f32_e32 v22, v145, v92
	v_sub_f32_e32 v23, v144, v92
	v_exp_f32_e32 v184, v23
	v_exp_f32_e32 v186, v21
	v_exp_f32_e32 v187, v20
	v_exp_f32_e32 v185, v22
	v_pk_add_f32 v[16:17], v[188:189], 0 op_sel_hi:[1,0]
	v_pk_add_f32 v[18:19], v[190:191], 0 op_sel_hi:[1,0]
	v_pk_add_f32 v[16:17], v[192:193], v[16:17]
	v_pk_add_f32 v[18:19], v[194:195], v[18:19]
	v_pk_add_f32 v[16:17], v[180:181], v[16:17]
	v_pk_add_f32 v[18:19], v[182:183], v[18:19]
	v_pk_add_f32 v[16:17], v[184:185], v[16:17]
	v_pk_add_f32 v[18:19], v[186:187], v[18:19]
	v_add_f32_e32 v16, v16, v17
	v_add_f32_e32 v17, v18, v19
	v_add_f32_e32 v16, v16, v17
	v_mov_b32_e32 v17, v16
	s_nop 1
	v_permlane16_swap_b32_e32 v17, v16
	v_sub_f32_e32 v18, v163, v155
	v_exp_f32_e32 v92, v18
	s_waitcnt lgkmcnt(0)
	v_add_f32_e32 v219, v16, v17
	v_mov_b32_e32 v229, v219
	s_nop 1
	v_permlane32_swap_b32_e32 v229, v219
	v_cmp_eq_f32_e32 vcc, 1.0, v92
	s_cmp_lg_u64 vcc, exec
	s_cbranch_scc0 .LBB0_1336
	v_pk_mul_f32 v[146:147], v[62:63], v[92:93] op_sel_hi:[1,0]
	v_pk_mul_f32 v[144:145], v[60:61], v[92:93] op_sel_hi:[1,0]
	v_pk_mul_f32 v[26:27], v[66:67], v[92:93] op_sel_hi:[1,0]
	v_pk_mul_f32 v[24:25], v[64:65], v[92:93] op_sel_hi:[1,0]
	v_pk_mul_f32 v[22:23], v[70:71], v[92:93] op_sel_hi:[1,0]
	v_pk_mul_f32 v[20:21], v[68:69], v[92:93] op_sel_hi:[1,0]
	v_pk_mul_f32 v[18:19], v[74:75], v[92:93] op_sel_hi:[1,0]
	v_pk_mul_f32 v[16:17], v[72:73], v[92:93] op_sel_hi:[1,0]
	s_mov_b64 s[2:3], 0

.LBB0_1339:
	s_and_b64 vcc, exec, s[2:3]
	s_cbranch_vccz .LBB0_1345
	s_waitcnt lgkmcnt(7)
	v_mfma_f32_16x16x32_bf16 v[4:7], v[4:7], v[96:99], 0
	v_lshrrev_b32_e32 v21, 4, v228
	v_lshl_or_b32 v20, v21, 2, s13
	v_cmp_ge_u32_e32 vcc, v20, v227
	s_waitcnt lgkmcnt(6)
	v_mfma_f32_16x16x32_bf16 v[4:7], v[8:11], v[100:103], v[4:7]
	v_cmp_le_i32_e64 s[2:3], v20, v152
	s_and_b64 vcc, vcc, s[2:3]
	v_cmp_lt_i32_e64 s[2:3], v20, v152
	s_waitcnt lgkmcnt(5)
	v_mfma_f32_16x16x32_bf16 v[8:11], v[56:59], v[96:99], 0
	s_waitcnt lgkmcnt(3)
	v_mfma_f32_16x16x32_bf16 v[16:19], v[132:135], v[96:99], 0
	s_waitcnt lgkmcnt(1)
	v_mfma_f32_16x16x32_bf16 v[22:25], v[140:143], v[96:99], 0
	v_mfma_f32_16x16x32_bf16 v[8:11], v[128:131], v[100:103], v[8:11]
	v_mfma_f32_16x16x32_bf16 v[16:19], v[136:139], v[100:103], v[16:19]
	s_waitcnt lgkmcnt(0)
	v_mfma_f32_16x16x32_bf16 v[0:3], v[0:3], v[100:103], v[22:25]
	s_nop 7
	s_nop 0
	v_cndmask_b32_e32 v4, v158, v4, vcc
	s_nop 1
	v_or_b32_e32 v22, 1, v20
	v_cmp_ge_u32_e32 vcc, v22, v227
	s_and_b64 vcc, s[2:3], vcc
	v_or_b32_e32 v23, 2, v20
	v_cndmask_b32_e32 v5, v158, v5, vcc
	v_cmp_ge_u32_e32 vcc, v23, v227
	v_cmp_le_i32_e64 s[2:3], v23, v152
	s_and_b64 vcc, vcc, s[2:3]
	v_or_b32_e32 v23, 3, v20
	v_cndmask_b32_e32 v6, v158, v6, vcc
	v_cmp_ge_u32_e32 vcc, v23, v227
	v_cmp_le_i32_e64 s[2:3], v23, v152
	s_and_b64 vcc, vcc, s[2:3]
	v_or_b32_e32 v23, 16, v20
	v_cndmask_b32_e32 v7, v158, v7, vcc
	v_cmp_ge_u32_e32 vcc, v23, v227
	v_cmp_le_i32_e64 s[2:3], v23, v152
	s_and_b64 vcc, vcc, s[2:3]
	v_or_b32_e32 v23, 17, v20
	v_cndmask_b32_e32 v8, v158, v8, vcc
	v_cmp_ge_u32_e32 vcc, v23, v227
	v_cmp_le_i32_e64 s[2:3], v23, v152
	s_and_b64 vcc, vcc, s[2:3]
	v_or_b32_e32 v23, 18, v20
	v_cndmask_b32_e32 v9, v158, v9, vcc
	v_cmp_ge_u32_e32 vcc, v23, v227
	v_cmp_le_i32_e64 s[2:3], v23, v152
	s_and_b64 vcc, vcc, s[2:3]
	v_or_b32_e32 v23, 19, v20
	v_cndmask_b32_e32 v10, v158, v10, vcc
	v_cmp_ge_u32_e32 vcc, v23, v227
	v_cmp_le_i32_e64 s[2:3], v23, v152
	s_and_b64 vcc, vcc, s[2:3]
	v_or_b32_e32 v23, 32, v20
	v_cndmask_b32_e32 v11, v158, v11, vcc
	v_cmp_ge_u32_e32 vcc, v23, v227
	v_cmp_le_i32_e64 s[2:3], v23, v152
	s_and_b64 vcc, vcc, s[2:3]
	v_or_b32_e32 v23, 33, v20
	v_cndmask_b32_e32 v16, v158, v16, vcc
	v_cmp_ge_u32_e32 vcc, v23, v227
	v_cmp_le_i32_e64 s[2:3], v23, v152
	s_and_b64 vcc, vcc, s[2:3]
	v_or_b32_e32 v23, 34, v20
	v_cndmask_b32_e32 v17, v158, v17, vcc
	v_cmp_ge_u32_e32 vcc, v23, v227
	v_cmp_le_i32_e64 s[2:3], v23, v152
	s_and_b64 vcc, vcc, s[2:3]
	v_or_b32_e32 v23, 35, v20
	v_cndmask_b32_e32 v18, v158, v18, vcc
	v_cmp_ge_u32_e32 vcc, v23, v227
	v_cmp_le_i32_e64 s[2:3], v23, v152
	s_and_b64 vcc, vcc, s[2:3]
	v_or_b32_e32 v23, 48, v20
	v_cndmask_b32_e32 v19, v158, v19, vcc
	v_cmp_ge_u32_e32 vcc, v23, v227
	v_cmp_le_i32_e64 s[2:3], v23, v152
	s_and_b64 vcc, vcc, s[2:3]
	v_or_b32_e32 v23, 49, v20
	v_max3_f32 v22, v4, s87, v5
	v_cndmask_b32_e32 v0, v158, v0, vcc
	v_cmp_ge_u32_e32 vcc, v23, v227
	v_cmp_le_i32_e64 s[2:3], v23, v152
	v_max3_f32 v22, v22, v6, v7
	s_and_b64 vcc, vcc, s[2:3]
	v_or_b32_e32 v23, 50, v20
	v_max3_f32 v22, v22, v8, v9
	v_cndmask_b32_e32 v1, v158, v1, vcc
	v_cmp_ge_u32_e32 vcc, v23, v227
	v_cmp_le_i32_e64 s[2:3], v23, v152
	v_max3_f32 v22, v22, v10, v11
	s_and_b64 vcc, vcc, s[2:3]
	v_or_b32_e32 v20, 51, v20
	v_max3_f32 v22, v22, v16, v17
	v_cndmask_b32_e32 v2, v158, v2, vcc
	v_cmp_ge_u32_e32 vcc, v20, v227
	v_cmp_le_i32_e64 s[2:3], v20, v152
	v_max3_f32 v22, v22, v18, v19
	s_and_b64 vcc, vcc, s[2:3]
	v_max3_f32 v22, v22, v0, v1
	v_cndmask_b32_e32 v3, v158, v3, vcc
	v_max3_f32 v20, v22, v2, v3
	v_mov_b32_e32 v22, v20
	s_nop 1
	v_permlane16_swap_b32_e32 v22, v20
	s_waitcnt lgkmcnt(0)
	v_max3_f32 v20, v20, v22, v158
	v_mov_b32_e32 v22, v20
	s_nop 1
	v_permlane32_swap_b32_e32 v22, v20
	s_waitcnt lgkmcnt(0)
	v_max3_f32 v20, v20, v22, v158
	v_cmp_lt_f32_e32 vcc, s86, v4
	v_max3_f32 v155, v163, v20, v158
	s_mov_b64 s[2:3], -1
	v_sub_f32_e32 v20, v4, v155
	v_exp_f32_e32 v20, v20
	v_sub_f32_e32 v22, v5, v155
	v_exp_f32_e32 v22, v22
	v_cndmask_b32_e32 v56, 0, v20, vcc
	v_cmp_lt_f32_e32 vcc, s86, v5
	v_sub_f32_e32 v5, v6, v155
	v_exp_f32_e32 v5, v5
	v_cndmask_b32_e32 v57, 0, v22, vcc
	v_sub_f32_e32 v20, v7, v155
	v_cmp_lt_f32_e32 vcc, s86, v6
	v_exp_f32_e32 v20, v20
	v_sub_f32_e32 v6, v9, v155
	v_cndmask_b32_e32 v92, 0, v5, vcc
	v_sub_f32_e32 v5, v8, v155
	v_exp_f32_e32 v5, v5
	v_cmp_lt_f32_e32 vcc, s86, v7
	v_exp_f32_e32 v6, v6
	v_add_f32_e32 v4, 0, v56
	v_cndmask_b32_e32 v128, 0, v20, vcc
	v_cmp_lt_f32_e32 vcc, s86, v8
	v_add_f32_e32 v4, v57, v4
	v_add_f32_e32 v4, v92, v4
	v_cndmask_b32_e32 v129, 0, v5, vcc
	v_sub_f32_e32 v5, v10, v155
	v_exp_f32_e32 v5, v5
	v_cmp_lt_f32_e32 vcc, s86, v9
	v_add_f32_e32 v4, v128, v4
	v_add_f32_e32 v4, v129, v4
	v_cndmask_b32_e32 v130, 0, v6, vcc
	v_sub_f32_e32 v6, v11, v155
	v_cmp_lt_f32_e32 vcc, s86, v10
	v_exp_f32_e32 v6, v6
	v_add_f32_e32 v4, v130, v4
	v_cndmask_b32_e32 v131, 0, v5, vcc
	v_sub_f32_e32 v5, v16, v155
	v_exp_f32_e32 v5, v5
	v_cmp_lt_f32_e32 vcc, s86, v11
	v_add_f32_e32 v4, v131, v4
	s_nop 0
	v_cndmask_b32_e32 v132, 0, v6, vcc
	v_sub_f32_e32 v6, v17, v155
	v_cmp_lt_f32_e32 vcc, s86, v16
	v_exp_f32_e32 v6, v6
	v_add_f32_e32 v4, v132, v4
	v_cndmask_b32_e32 v22, 0, v5, vcc
	v_sub_f32_e32 v5, v18, v155
	v_exp_f32_e32 v5, v5
	v_cmp_lt_f32_e32 vcc, s86, v17
	v_add_f32_e32 v4, v22, v4
	s_nop 0
	v_cndmask_b32_e32 v23, 0, v6, vcc
	v_sub_f32_e32 v6, v19, v155
	v_cmp_lt_f32_e32 vcc, s86, v18
	v_exp_f32_e32 v6, v6
	v_add_f32_e32 v4, v23, v4
	v_cndmask_b32_e32 v24, 0, v5, vcc
	v_sub_f32_e32 v5, v0, v155
	v_exp_f32_e32 v5, v5
	v_cmp_lt_f32_e32 vcc, s86, v19
	v_add_f32_e32 v4, v24, v4
	s_nop 0
	v_cndmask_b32_e32 v25, 0, v6, vcc
	v_sub_f32_e32 v6, v1, v155
	v_cmp_lt_f32_e32 vcc, s86, v0
	v_add_f32_e32 v4, v25, v4
	v_exp_f32_e32 v6, v6
	v_cndmask_b32_e32 v26, 0, v5, vcc
	v_cmp_lt_f32_e32 vcc, s86, v1
	v_sub_f32_e32 v1, v2, v155
	v_add_f32_e32 v0, v26, v4
	v_exp_f32_e32 v1, v1
	v_sub_f32_e32 v4, v3, v155
	v_exp_f32_e32 v4, v4
	v_cndmask_b32_e32 v27, 0, v6, vcc
	v_cmp_lt_f32_e32 vcc, s86, v2
	v_add_f32_e32 v0, v27, v0
	v_sub_f32_e32 v2, v163, v155
	v_cndmask_b32_e32 v58, 0, v1, vcc
	v_cmp_lt_f32_e32 vcc, s86, v3
	v_add_f32_e32 v0, v58, v0
	v_exp_f32_e32 v20, v2
	v_cndmask_b32_e32 v59, 0, v4, vcc
	v_add_f32_e32 v0, v59, v0
	v_mov_b32_e32 v1, v0
	s_nop 1
	v_permlane16_swap_b32_e32 v1, v0
	v_cmp_eq_f32_e32 vcc, 1.0, v20
	s_cmp_lg_u64 vcc, exec
	s_waitcnt lgkmcnt(0)
	v_add_f32_e32 v133, v0, v1
	v_mov_b32_e32 v134, v133
	s_nop 1
	v_permlane32_swap_b32_e32 v134, v133
	s_cbranch_scc0 .LBB0_1342
	v_pk_mul_f32 v[18:19], v[62:63], v[20:21] op_sel_hi:[1,0]
	v_pk_mul_f32 v[16:17], v[60:61], v[20:21] op_sel_hi:[1,0]
	v_pk_mul_f32 v[10:11], v[66:67], v[20:21] op_sel_hi:[1,0]
	v_pk_mul_f32 v[8:9], v[64:65], v[20:21] op_sel_hi:[1,0]
	v_pk_mul_f32 v[6:7], v[70:71], v[20:21] op_sel_hi:[1,0]
	v_pk_mul_f32 v[4:5], v[68:69], v[20:21] op_sel_hi:[1,0]
	v_pk_mul_f32 v[2:3], v[74:75], v[20:21] op_sel_hi:[1,0]
	v_pk_mul_f32 v[0:1], v[72:73], v[20:21] op_sel_hi:[1,0]
	s_mov_b64 s[2:3], 0

.LBB0_1346:
	s_andn2_b64 vcc, exec, s[74:75]
	s_cbranch_vccnz .LBB0_1352
	v_mad_u32_u24 v16, v226, s88, v225
	s_waitcnt lgkmcnt(0)
	ds_read_b128 v[0:3], v16 offset:9216
	ds_read_b128 v[8:11], v16 offset:9280
	ds_read_b128 v[4:7], v16 offset:11520
	v_mad_u32_u24 v20, v224, s88, v225
	s_mov_b64 s[2:3], -1
	s_waitcnt lgkmcnt(2)
	v_mfma_f32_16x16x32_bf16 v[0:3], v[0:3], v[96:99], 0
	s_waitcnt lgkmcnt(1)
	v_mfma_f32_16x16x32_bf16 v[0:3], v[8:11], v[100:103], v[0:3]
	ds_read_b128 v[8:11], v16 offset:11584
	s_waitcnt lgkmcnt(1)
	v_mfma_f32_16x16x32_bf16 v[4:7], v[4:7], v[96:99], 0
	s_waitcnt lgkmcnt(0)
	v_mfma_f32_16x16x32_bf16 v[4:7], v[8:11], v[100:103], v[4:7]
	ds_read_b128 v[8:11], v16 offset:13824
	ds_read_b128 v[16:19], v16 offset:13888
	s_waitcnt lgkmcnt(1)
	v_mfma_f32_16x16x32_bf16 v[8:11], v[8:11], v[96:99], 0
	s_waitcnt lgkmcnt(0)
	v_mfma_f32_16x16x32_bf16 v[8:11], v[16:19], v[100:103], v[8:11]
	ds_read_b128 v[16:19], v20 offset:9216
	ds_read_b128 v[20:23], v20 offset:9280
	s_waitcnt lgkmcnt(1)
	v_mfma_f32_16x16x32_bf16 v[16:19], v[16:19], v[96:99], 0
	s_waitcnt lgkmcnt(0)
	v_mfma_f32_16x16x32_bf16 v[16:19], v[20:23], v[100:103], v[16:19]
	s_nop 7
	s_nop 0
	v_max3_f32 v20, v158, v0, v1
	v_max3_f32 v20, v20, v2, v3
	v_max3_f32 v20, v20, v4, v5
	v_max3_f32 v20, v20, v6, v7
	v_max3_f32 v20, v20, v8, v9
	v_max3_f32 v20, v20, v10, v11
	v_max3_f32 v20, v20, v16, v17
	v_max3_f32 v20, v20, v18, v19
	v_mov_b32_e32 v21, v20
	s_nop 1
	v_permlane16_swap_b32_e32 v21, v20
	s_waitcnt lgkmcnt(0)
	v_max3_f32 v20, v20, v21, v158
	v_mov_b32_e32 v21, v20
	s_nop 1
	v_permlane32_swap_b32_e32 v21, v20
	s_waitcnt lgkmcnt(0)
	v_max3_f32 v20, v20, v21, v158
	v_max3_f32 v155, v163, v20, v158
	s_nop 0
	v_sub_f32_e32 v3, v3, v155
	v_sub_f32_e32 v2, v2, v155
	v_sub_f32_e32 v1, v1, v155
	v_sub_f32_e32 v0, v0, v155
	v_sub_f32_e32 v7, v7, v155
	v_sub_f32_e32 v6, v6, v155
	v_exp_f32_e32 v56, v0
	v_exp_f32_e32 v57, v1
	v_exp_f32_e32 v58, v2
	v_exp_f32_e32 v59, v3
	v_sub_f32_e32 v0, v5, v155
	v_sub_f32_e32 v1, v4, v155
	v_exp_f32_e32 v128, v1
	v_exp_f32_e32 v130, v6
	v_exp_f32_e32 v131, v7
	v_exp_f32_e32 v129, v0
	v_sub_f32_e32 v4, v11, v155
	v_sub_f32_e32 v5, v10, v155
	v_sub_f32_e32 v6, v9, v155
	v_sub_f32_e32 v7, v8, v155
	v_exp_f32_e32 v20, v7
	v_exp_f32_e32 v21, v6
	v_exp_f32_e32 v22, v5
	v_exp_f32_e32 v23, v4
	v_sub_f32_e32 v4, v19, v155
	v_sub_f32_e32 v5, v18, v155
	v_sub_f32_e32 v6, v17, v155
	v_sub_f32_e32 v7, v16, v155
	v_exp_f32_e32 v24, v7
	v_exp_f32_e32 v26, v5
	v_exp_f32_e32 v27, v4
	v_exp_f32_e32 v25, v6
	v_pk_add_f32 v[0:1], v[56:57], 0 op_sel_hi:[1,0]
	v_pk_add_f32 v[2:3], v[58:59], 0 op_sel_hi:[1,0]
	v_pk_add_f32 v[0:1], v[128:129], v[0:1]
	v_pk_add_f32 v[2:3], v[130:131], v[2:3]
	v_pk_add_f32 v[0:1], v[20:21], v[0:1]
	v_pk_add_f32 v[2:3], v[22:23], v[2:3]
	v_pk_add_f32 v[0:1], v[24:25], v[0:1]
	v_pk_add_f32 v[2:3], v[26:27], v[2:3]
	v_add_f32_e32 v0, v0, v1
	v_add_f32_e32 v1, v2, v3
	v_add_f32_e32 v0, v0, v1
	v_mov_b32_e32 v1, v0
	s_nop 1
	v_permlane16_swap_b32_e32 v1, v0
	v_sub_f32_e32 v2, v163, v155
	v_exp_f32_e32 v92, v2
	s_waitcnt lgkmcnt(0)
	v_add_f32_e32 v132, v0, v1
	v_mov_b32_e32 v133, v132
	s_nop 1
	v_permlane32_swap_b32_e32 v133, v132
	v_cmp_eq_f32_e32 vcc, 1.0, v92
	s_cmp_lg_u64 vcc, exec
	s_cbranch_scc0 .LBB0_1349
	v_pk_mul_f32 v[18:19], v[62:63], v[92:93] op_sel_hi:[1,0]
	v_pk_mul_f32 v[16:17], v[60:61], v[92:93] op_sel_hi:[1,0]
	v_pk_mul_f32 v[10:11], v[66:67], v[92:93] op_sel_hi:[1,0]
	v_pk_mul_f32 v[8:9], v[64:65], v[92:93] op_sel_hi:[1,0]
	v_pk_mul_f32 v[6:7], v[70:71], v[92:93] op_sel_hi:[1,0]
	v_pk_mul_f32 v[4:5], v[68:69], v[92:93] op_sel_hi:[1,0]
	v_pk_mul_f32 v[2:3], v[74:75], v[92:93] op_sel_hi:[1,0]
	v_pk_mul_f32 v[0:1], v[72:73], v[92:93] op_sel_hi:[1,0]
	s_mov_b64 s[2:3], 0

.LBB0_1354:
	s_waitcnt lgkmcnt(0)
	v_and_b32_e32 v0, s4, v173
	v_cmp_ne_u32_e32 vcc, 0, v0
	s_cmp_eq_u64 vcc, 0
	s_cselect_b64 s[2:3], -1, 0
	s_cmp_gt_i32 s13, s77
	s_cselect_b64 s[14:15], -1, 0
	s_or_b64 s[2:3], s[2:3], s[14:15]
	v_mov_b32_e32 v181, v196
	s_and_b64 vcc, exec, s[2:3]
	s_cbranch_vccnz .LBB0_1376
	v_cmp_eq_u32_e32 vcc, 0, v0
	s_or_b32 s4, s13, 63
	v_cmp_le_i32_e64 s[74:75], s4, v154
	v_cndmask_b32_e32 v186, 0, v211, vcc
	v_cmp_ge_u32_e64 s[2:3], s13, v186
	s_and_b64 s[2:3], s[2:3], s[74:75]
	v_and_b32_e32 v187, 63, v181
	v_cndmask_b32_e64 v0, 0, 1, s[2:3]
	v_cmp_ne_u32_e64 s[2:3], 0, v0
	v_and_b32_e32 v185, 15, v181
	v_and_b32_e32 v0, 48, v181
	v_or_b32_e32 v183, 48, v187
	s_mov_b64 s[74:75], -1
	s_cmp_lg_u64 s[2:3], exec
	v_add_u32_e32 v184, s96, v0
	v_mul_u32_u24_e32 v182, 0x90, v185
	v_mul_u32_u24_e32 v163, 0x90, v183
	s_cbranch_scc0 .LBB0_1369
	v_mad_u32_u24 v0, v185, s88, v184
	ds_read_b128 v[36:39], v0 offset:9216
	ds_read_b128 v[40:43], v0 offset:9280
	ds_read_b128 v[56:59], v0 offset:11520
	ds_read_b128 v[60:63], v0 offset:11584
	ds_read_b128 v[64:67], v0 offset:13824
	ds_read_b128 v[68:71], v0 offset:13888
	v_mad_u32_u24 v0, v183, s88, v184
	ds_read_b128 v[72:75], v0 offset:9216
	ds_read_b128 v[32:35], v0 offset:9280
	s_cmp_gt_i32 s4, s93
	s_mov_b64 s[2:3], -1
	s_cbranch_scc1 .LBB0_1362
	s_waitcnt lgkmcnt(7)
	v_mfma_f32_16x16x32_bf16 v[0:3], v[36:39], v[104:107], 0
	s_waitcnt lgkmcnt(5)
	v_mfma_f32_16x16x32_bf16 v[4:7], v[56:59], v[104:107], 0
	s_waitcnt lgkmcnt(3)
	v_mfma_f32_16x16x32_bf16 v[8:11], v[64:67], v[104:107], 0
	s_waitcnt lgkmcnt(1)
	v_mfma_f32_16x16x32_bf16 v[128:131], v[72:75], v[104:107], 0
	v_mfma_f32_16x16x32_bf16 v[0:3], v[40:43], v[108:111], v[0:3]
	v_mfma_f32_16x16x32_bf16 v[4:7], v[60:63], v[108:111], v[4:7]
	v_mfma_f32_16x16x32_bf16 v[8:11], v[68:71], v[108:111], v[8:11]
	s_waitcnt lgkmcnt(0)
	v_mfma_f32_16x16x32_bf16 v[128:131], v[32:35], v[108:111], v[128:131]
	s_nop 7
	s_nop 0
	v_max3_f32 v92, v158, v0, v1
	v_max3_f32 v92, v92, v2, v3
	v_max3_f32 v92, v92, v4, v5
	v_max3_f32 v92, v92, v6, v7
	v_max3_f32 v92, v92, v8, v9
	v_max3_f32 v92, v92, v10, v11
	v_max3_f32 v92, v92, v128, v129
	v_max3_f32 v92, v92, v130, v131
	s_nop 0
	v_cndmask_b32_e32 v92, v92, v158, vcc
	v_mov_b32_e32 v132, v92
	s_nop 1
	v_permlane16_swap_b32_e32 v132, v92
	s_waitcnt lgkmcnt(0)
	v_max3_f32 v92, v92, v132, v158
	v_mov_b32_e32 v132, v92
	s_nop 1
	v_permlane32_swap_b32_e32 v132, v92
	s_waitcnt lgkmcnt(0)
	v_max3_f32 v92, v92, v132, v158
	v_max3_f32 v153, v175, v92, v158
	s_nop 0
	v_cndmask_b32_e32 v92, v153, v212, vcc
	v_sub_f32_e32 v3, v3, v92
	v_sub_f32_e32 v2, v2, v92
	v_sub_f32_e32 v1, v1, v92
	v_sub_f32_e32 v0, v0, v92
	v_sub_f32_e32 v7, v7, v92
	v_sub_f32_e32 v6, v6, v92
	v_exp_f32_e32 v140, v0
	v_exp_f32_e32 v141, v1
	v_exp_f32_e32 v142, v2
	v_exp_f32_e32 v143, v3
	v_sub_f32_e32 v0, v5, v92
	v_sub_f32_e32 v1, v4, v92
	v_exp_f32_e32 v144, v1
	v_exp_f32_e32 v146, v6
	v_exp_f32_e32 v147, v7
	v_exp_f32_e32 v145, v0
	v_sub_f32_e32 v4, v11, v92
	v_sub_f32_e32 v5, v10, v92
	v_sub_f32_e32 v6, v9, v92
	v_sub_f32_e32 v7, v8, v92
	v_exp_f32_e32 v132, v7
	v_exp_f32_e32 v133, v6
	v_exp_f32_e32 v134, v5
	v_exp_f32_e32 v135, v4
	v_sub_f32_e32 v4, v131, v92
	v_sub_f32_e32 v5, v130, v92
	v_sub_f32_e32 v6, v129, v92
	v_sub_f32_e32 v7, v128, v92
	v_exp_f32_e32 v136, v7
	v_exp_f32_e32 v138, v5
	v_exp_f32_e32 v139, v4
	v_exp_f32_e32 v137, v6
	v_pk_add_f32 v[0:1], v[140:141], 0 op_sel_hi:[1,0]
	v_pk_add_f32 v[2:3], v[142:143], 0 op_sel_hi:[1,0]
	v_pk_add_f32 v[0:1], v[144:145], v[0:1]
	v_pk_add_f32 v[2:3], v[146:147], v[2:3]
	v_pk_add_f32 v[0:1], v[132:133], v[0:1]
	v_pk_add_f32 v[2:3], v[134:135], v[2:3]
	v_pk_add_f32 v[0:1], v[136:137], v[0:1]
	v_pk_add_f32 v[2:3], v[138:139], v[2:3]
	v_add_f32_e32 v0, v0, v1
	v_add_f32_e32 v1, v2, v3
	v_add_f32_e32 v0, v0, v1
	v_mov_b32_e32 v1, v0
	s_nop 1
	v_permlane16_swap_b32_e32 v1, v0
	v_sub_f32_e32 v2, v175, v153
	v_exp_f32_e32 v92, v2
	s_waitcnt lgkmcnt(0)
	v_add_f32_e32 v180, v0, v1
	v_mov_b32_e32 v188, v180
	s_nop 1
	v_permlane32_swap_b32_e32 v188, v180
	v_cmp_eq_f32_e32 vcc, 1.0, v92
	s_cmp_lg_u64 vcc, exec
	s_cbranch_scc0 .LBB0_1359
	v_pk_mul_f32 v[130:131], v[78:79], v[92:93] op_sel_hi:[1,0]
	v_pk_mul_f32 v[128:129], v[76:77], v[92:93] op_sel_hi:[1,0]
	v_pk_mul_f32 v[10:11], v[82:83], v[92:93] op_sel_hi:[1,0]
	v_pk_mul_f32 v[8:9], v[80:81], v[92:93] op_sel_hi:[1,0]
	v_pk_mul_f32 v[6:7], v[86:87], v[92:93] op_sel_hi:[1,0]
	v_pk_mul_f32 v[4:5], v[84:85], v[92:93] op_sel_hi:[1,0]
	v_pk_mul_f32 v[2:3], v[90:91], v[92:93] op_sel_hi:[1,0]
	v_pk_mul_f32 v[0:1], v[88:89], v[92:93] op_sel_hi:[1,0]
	s_mov_b64 s[2:3], 0

.LBB0_1362:
	s_and_b64 vcc, exec, s[2:3]
	s_cbranch_vccz .LBB0_1368
	s_waitcnt lgkmcnt(7)
	v_mfma_f32_16x16x32_bf16 v[0:3], v[36:39], v[104:107], 0
	v_lshrrev_b32_e32 v37, 4, v187
	v_lshl_or_b32 v36, v37, 2, s13
	v_cmp_ge_u32_e32 vcc, v36, v186
	s_waitcnt lgkmcnt(6)
	v_mfma_f32_16x16x32_bf16 v[0:3], v[40:43], v[108:111], v[0:3]
	v_cmp_le_i32_e64 s[2:3], v36, v154
	s_and_b64 vcc, vcc, s[2:3]
	v_cmp_lt_i32_e64 s[2:3], v36, v154
	s_waitcnt lgkmcnt(5)
	v_mfma_f32_16x16x32_bf16 v[4:7], v[56:59], v[104:107], 0
	s_waitcnt lgkmcnt(3)
	v_mfma_f32_16x16x32_bf16 v[8:11], v[64:67], v[104:107], 0
	s_waitcnt lgkmcnt(1)
	v_mfma_f32_16x16x32_bf16 v[38:41], v[72:75], v[104:107], 0
	v_mfma_f32_16x16x32_bf16 v[4:7], v[60:63], v[108:111], v[4:7]
	v_mfma_f32_16x16x32_bf16 v[8:11], v[68:71], v[108:111], v[8:11]
	s_waitcnt lgkmcnt(0)
	v_mfma_f32_16x16x32_bf16 v[32:35], v[32:35], v[108:111], v[38:41]
	s_nop 7
	s_nop 0
	v_cndmask_b32_e32 v0, v158, v0, vcc
	s_nop 1
	v_or_b32_e32 v38, 1, v36
	v_cmp_ge_u32_e32 vcc, v38, v186
	s_and_b64 vcc, s[2:3], vcc
	v_or_b32_e32 v39, 2, v36
	v_cndmask_b32_e32 v1, v158, v1, vcc
	v_cmp_ge_u32_e32 vcc, v39, v186
	v_cmp_le_i32_e64 s[2:3], v36, v152
	s_and_b64 vcc, s[2:3], vcc
	v_or_b32_e32 v39, 3, v36
	v_cndmask_b32_e32 v2, v158, v2, vcc
	v_cmp_ge_u32_e32 vcc, v39, v186
	v_cmp_le_i32_e64 s[2:3], v39, v154
	s_and_b64 vcc, vcc, s[2:3]
	v_or_b32_e32 v39, 16, v36
	v_cndmask_b32_e32 v3, v158, v3, vcc
	v_cmp_ge_u32_e32 vcc, v39, v186
	v_cmp_le_i32_e64 s[2:3], v39, v154
	s_and_b64 vcc, vcc, s[2:3]
	v_or_b32_e32 v39, 17, v36
	v_cndmask_b32_e32 v4, v158, v4, vcc
	v_cmp_ge_u32_e32 vcc, v39, v186
	v_cmp_le_i32_e64 s[2:3], v39, v154
	s_and_b64 vcc, vcc, s[2:3]
	v_or_b32_e32 v39, 18, v36
	v_cndmask_b32_e32 v5, v158, v5, vcc
	v_cmp_ge_u32_e32 vcc, v39, v186
	v_cmp_le_i32_e64 s[2:3], v39, v154
	s_and_b64 vcc, vcc, s[2:3]
	v_or_b32_e32 v39, 19, v36
	v_cndmask_b32_e32 v6, v158, v6, vcc
	v_cmp_ge_u32_e32 vcc, v39, v186
	v_cmp_le_i32_e64 s[2:3], v39, v154
	s_and_b64 vcc, vcc, s[2:3]
	v_or_b32_e32 v39, 32, v36
	v_cndmask_b32_e32 v7, v158, v7, vcc
	v_cmp_ge_u32_e32 vcc, v39, v186
	v_cmp_le_i32_e64 s[2:3], v39, v154
	s_and_b64 vcc, vcc, s[2:3]
	v_or_b32_e32 v39, 33, v36
	v_cndmask_b32_e32 v8, v158, v8, vcc
	v_cmp_ge_u32_e32 vcc, v39, v186
	v_cmp_le_i32_e64 s[2:3], v39, v154
	s_and_b64 vcc, vcc, s[2:3]
	v_or_b32_e32 v39, 34, v36
	v_cndmask_b32_e32 v9, v158, v9, vcc
	v_cmp_ge_u32_e32 vcc, v39, v186
	v_cmp_le_i32_e64 s[2:3], v39, v154
	s_and_b64 vcc, vcc, s[2:3]
	v_or_b32_e32 v39, 35, v36
	v_cndmask_b32_e32 v10, v158, v10, vcc
	v_cmp_ge_u32_e32 vcc, v39, v186
	v_cmp_le_i32_e64 s[2:3], v39, v154
	s_and_b64 vcc, vcc, s[2:3]
	v_or_b32_e32 v39, 48, v36
	v_cndmask_b32_e32 v11, v158, v11, vcc
	v_cmp_ge_u32_e32 vcc, v39, v186
	v_cmp_le_i32_e64 s[2:3], v39, v154
	s_and_b64 vcc, vcc, s[2:3]
	v_or_b32_e32 v39, 49, v36
	v_max3_f32 v38, v0, s87, v1
	v_cndmask_b32_e32 v32, v158, v32, vcc
	v_cmp_ge_u32_e32 vcc, v39, v186
	v_cmp_le_i32_e64 s[2:3], v39, v154
	v_max3_f32 v38, v38, v2, v3
	s_and_b64 vcc, vcc, s[2:3]
	v_or_b32_e32 v39, 50, v36
	v_max3_f32 v38, v38, v4, v5
	v_cndmask_b32_e32 v33, v158, v33, vcc
	v_cmp_ge_u32_e32 vcc, v39, v186
	v_cmp_le_i32_e64 s[2:3], v39, v154
	v_max3_f32 v38, v38, v6, v7
	s_and_b64 vcc, vcc, s[2:3]
	v_or_b32_e32 v36, 51, v36
	v_max3_f32 v38, v38, v8, v9
	v_cndmask_b32_e32 v34, v158, v34, vcc
	v_cmp_ge_u32_e32 vcc, v36, v186
	v_cmp_le_i32_e64 s[2:3], v36, v154
	v_max3_f32 v38, v38, v10, v11
	s_and_b64 vcc, vcc, s[2:3]
	v_max3_f32 v38, v38, v32, v33
	v_cndmask_b32_e32 v35, v158, v35, vcc
	v_max3_f32 v36, v38, v34, v35
	v_mov_b32_e32 v38, v36
	s_nop 1
	v_permlane16_swap_b32_e32 v38, v36
	s_waitcnt lgkmcnt(0)
	v_max3_f32 v36, v36, v38, v158
	v_mov_b32_e32 v38, v36
	s_nop 1
	v_permlane32_swap_b32_e32 v38, v36
	s_waitcnt lgkmcnt(0)
	v_max3_f32 v36, v36, v38, v158
	v_cmp_lt_f32_e32 vcc, s86, v0
	v_max3_f32 v153, v175, v36, v158
	s_mov_b64 s[2:3], -1
	v_sub_f32_e32 v36, v0, v153
	v_exp_f32_e32 v36, v36
	v_sub_f32_e32 v38, v1, v153
	v_exp_f32_e32 v38, v38
	v_cndmask_b32_e32 v56, 0, v36, vcc
	v_cmp_lt_f32_e32 vcc, s86, v1
	v_sub_f32_e32 v1, v2, v153
	v_exp_f32_e32 v1, v1
	v_cndmask_b32_e32 v57, 0, v38, vcc
	v_sub_f32_e32 v36, v3, v153
	v_cmp_lt_f32_e32 vcc, s86, v2
	v_exp_f32_e32 v36, v36
	v_sub_f32_e32 v2, v5, v153
	v_cndmask_b32_e32 v60, 0, v1, vcc
	v_sub_f32_e32 v1, v4, v153
	v_exp_f32_e32 v1, v1
	v_exp_f32_e32 v2, v2
	v_cmp_lt_f32_e32 vcc, s86, v3
	v_add_f32_e32 v0, 0, v56
	v_add_f32_e32 v0, v57, v0
	v_cndmask_b32_e32 v61, 0, v36, vcc
	v_cmp_lt_f32_e32 vcc, s86, v4
	v_add_f32_e32 v0, v60, v0
	v_add_f32_e32 v0, v61, v0
	v_cndmask_b32_e32 v62, 0, v1, vcc
	v_cmp_lt_f32_e32 vcc, s86, v5
	v_sub_f32_e32 v1, v6, v153
	v_exp_f32_e32 v1, v1
	v_cndmask_b32_e32 v63, 0, v2, vcc
	v_sub_f32_e32 v2, v7, v153
	v_exp_f32_e32 v2, v2
	v_cmp_lt_f32_e32 vcc, s86, v6
	v_add_f32_e32 v0, v62, v0
	v_add_f32_e32 v0, v63, v0
	v_cndmask_b32_e32 v64, 0, v1, vcc
	v_cmp_lt_f32_e32 vcc, s86, v7
	v_sub_f32_e32 v1, v8, v153
	v_exp_f32_e32 v1, v1
	v_cndmask_b32_e32 v65, 0, v2, vcc
	v_sub_f32_e32 v2, v9, v153
	v_exp_f32_e32 v2, v2
	v_cmp_lt_f32_e32 vcc, s86, v8
	v_add_f32_e32 v0, v64, v0
	v_add_f32_e32 v0, v65, v0
	v_cndmask_b32_e32 v38, 0, v1, vcc
	v_cmp_lt_f32_e32 vcc, s86, v9
	v_sub_f32_e32 v1, v10, v153
	v_exp_f32_e32 v1, v1
	v_cndmask_b32_e32 v39, 0, v2, vcc
	v_sub_f32_e32 v2, v11, v153
	v_exp_f32_e32 v2, v2
	v_cmp_lt_f32_e32 vcc, s86, v10
	v_add_f32_e32 v0, v38, v0
	v_add_f32_e32 v0, v39, v0
	v_cndmask_b32_e32 v40, 0, v1, vcc
	v_cmp_lt_f32_e32 vcc, s86, v11
	v_sub_f32_e32 v1, v32, v153
	v_exp_f32_e32 v1, v1
	v_cndmask_b32_e32 v41, 0, v2, vcc
	v_sub_f32_e32 v2, v33, v153
	v_exp_f32_e32 v2, v2
	v_cmp_lt_f32_e32 vcc, s86, v32
	v_add_f32_e32 v0, v40, v0
	v_add_f32_e32 v0, v41, v0
	v_cndmask_b32_e32 v42, 0, v1, vcc
	v_cmp_lt_f32_e32 vcc, s86, v33
	v_sub_f32_e32 v1, v34, v153
	v_exp_f32_e32 v1, v1
	v_cndmask_b32_e32 v43, 0, v2, vcc
	v_sub_f32_e32 v2, v35, v153
	v_exp_f32_e32 v2, v2
	v_add_f32_e32 v0, v42, v0
	v_cmp_lt_f32_e32 vcc, s86, v34
	v_add_f32_e32 v0, v43, v0
	s_nop 0
	v_cndmask_b32_e32 v58, 0, v1, vcc
	v_cmp_lt_f32_e32 vcc, s86, v35
	v_add_f32_e32 v0, v58, v0
	s_nop 0
	v_cndmask_b32_e32 v59, 0, v2, vcc
	v_add_f32_e32 v0, v59, v0
	v_mov_b32_e32 v1, v0
	s_nop 1
	v_permlane16_swap_b32_e32 v1, v0
	v_sub_f32_e32 v2, v175, v153
	v_exp_f32_e32 v36, v2
	s_waitcnt lgkmcnt(0)
	v_add_f32_e32 v66, v0, v1
	v_mov_b32_e32 v67, v66
	s_nop 1
	v_permlane32_swap_b32_e32 v67, v66
	v_cmp_eq_f32_e32 vcc, 1.0, v36
	s_cmp_lg_u64 vcc, exec
	s_cbranch_scc0 .LBB0_1365
	v_pk_mul_f32 v[34:35], v[78:79], v[36:37] op_sel_hi:[1,0]
	v_pk_mul_f32 v[32:33], v[76:77], v[36:37] op_sel_hi:[1,0]
	v_pk_mul_f32 v[10:11], v[82:83], v[36:37] op_sel_hi:[1,0]
	v_pk_mul_f32 v[8:9], v[80:81], v[36:37] op_sel_hi:[1,0]
	v_pk_mul_f32 v[6:7], v[86:87], v[36:37] op_sel_hi:[1,0]
	v_pk_mul_f32 v[4:5], v[84:85], v[36:37] op_sel_hi:[1,0]
	v_pk_mul_f32 v[2:3], v[90:91], v[36:37] op_sel_hi:[1,0]
	v_pk_mul_f32 v[0:1], v[88:89], v[36:37] op_sel_hi:[1,0]
	s_mov_b64 s[2:3], 0

.LBB0_1369:
	s_andn2_b64 vcc, exec, s[74:75]
	s_cbranch_vccnz .LBB0_1375
	s_waitcnt lgkmcnt(0)
	v_mad_u32_u24 v32, v185, s88, v184
	ds_read_b128 v[0:3], v32 offset:9216
	s_nop 0
	ds_read_b128 v[8:11], v32 offset:9280
	ds_read_b128 v[4:7], v32 offset:11520
	v_mad_u32_u24 v36, v183, s88, v184
	s_mov_b64 s[2:3], -1
	s_waitcnt lgkmcnt(2)
	v_mfma_f32_16x16x32_bf16 v[0:3], v[0:3], v[104:107], 0
	s_waitcnt lgkmcnt(1)
	v_mfma_f32_16x16x32_bf16 v[0:3], v[8:11], v[108:111], v[0:3]
	ds_read_b128 v[8:11], v32 offset:11584
	s_waitcnt lgkmcnt(1)
	v_mfma_f32_16x16x32_bf16 v[4:7], v[4:7], v[104:107], 0
	s_waitcnt lgkmcnt(0)
	v_mfma_f32_16x16x32_bf16 v[4:7], v[8:11], v[108:111], v[4:7]
	ds_read_b128 v[8:11], v32 offset:13824
	ds_read_b128 v[32:35], v32 offset:13888
	s_waitcnt lgkmcnt(1)
	v_mfma_f32_16x16x32_bf16 v[8:11], v[8:11], v[104:107], 0
	s_waitcnt lgkmcnt(0)
	v_mfma_f32_16x16x32_bf16 v[8:11], v[32:35], v[108:111], v[8:11]
	ds_read_b128 v[32:35], v36 offset:9216
	ds_read_b128 v[36:39], v36 offset:9280
	s_waitcnt lgkmcnt(1)
	v_mfma_f32_16x16x32_bf16 v[32:35], v[32:35], v[104:107], 0
	s_waitcnt lgkmcnt(0)
	v_mfma_f32_16x16x32_bf16 v[32:35], v[36:39], v[108:111], v[32:35]
	s_nop 7
	s_nop 0
	v_max3_f32 v36, v158, v0, v1
	v_max3_f32 v36, v36, v2, v3
	v_max3_f32 v36, v36, v4, v5
	v_max3_f32 v36, v36, v6, v7
	v_max3_f32 v36, v36, v8, v9
	v_max3_f32 v36, v36, v10, v11
	v_max3_f32 v36, v36, v32, v33
	v_max3_f32 v36, v36, v34, v35
	v_mov_b32_e32 v37, v36
	s_nop 1
	v_permlane16_swap_b32_e32 v37, v36
	s_waitcnt lgkmcnt(0)
	v_max3_f32 v36, v36, v37, v158
	v_mov_b32_e32 v37, v36
	s_nop 1
	v_permlane32_swap_b32_e32 v37, v36
	s_waitcnt lgkmcnt(0)
	v_max3_f32 v36, v36, v37, v158
	v_max3_f32 v153, v175, v36, v158
	s_nop 0
	v_sub_f32_e32 v3, v3, v153
	v_sub_f32_e32 v2, v2, v153
	v_sub_f32_e32 v1, v1, v153
	v_sub_f32_e32 v0, v0, v153
	v_sub_f32_e32 v7, v7, v153
	v_sub_f32_e32 v6, v6, v153
	v_exp_f32_e32 v56, v0
	v_exp_f32_e32 v57, v1
	v_exp_f32_e32 v58, v2
	v_exp_f32_e32 v59, v3
	v_sub_f32_e32 v0, v5, v153
	v_sub_f32_e32 v1, v4, v153
	v_exp_f32_e32 v60, v1
	v_exp_f32_e32 v62, v6
	v_exp_f32_e32 v63, v7
	v_exp_f32_e32 v61, v0
	v_sub_f32_e32 v4, v11, v153
	v_sub_f32_e32 v5, v10, v153
	v_sub_f32_e32 v6, v9, v153
	v_sub_f32_e32 v7, v8, v153
	v_exp_f32_e32 v36, v7
	v_exp_f32_e32 v37, v6
	v_exp_f32_e32 v38, v5
	v_exp_f32_e32 v39, v4
	v_sub_f32_e32 v4, v35, v153
	v_sub_f32_e32 v5, v34, v153
	v_sub_f32_e32 v6, v33, v153
	v_sub_f32_e32 v7, v32, v153
	v_exp_f32_e32 v40, v7
	v_exp_f32_e32 v42, v5
	v_exp_f32_e32 v43, v4
	v_exp_f32_e32 v41, v6
	v_pk_add_f32 v[0:1], v[56:57], 0 op_sel_hi:[1,0]
	v_pk_add_f32 v[2:3], v[58:59], 0 op_sel_hi:[1,0]
	v_pk_add_f32 v[0:1], v[60:61], v[0:1]
	v_pk_add_f32 v[2:3], v[62:63], v[2:3]
	v_pk_add_f32 v[0:1], v[36:37], v[0:1]
	v_pk_add_f32 v[2:3], v[38:39], v[2:3]
	v_pk_add_f32 v[0:1], v[40:41], v[0:1]
	v_pk_add_f32 v[2:3], v[42:43], v[2:3]
	v_add_f32_e32 v0, v0, v1
	v_add_f32_e32 v1, v2, v3
	v_add_f32_e32 v0, v0, v1
	v_mov_b32_e32 v1, v0
	s_nop 1
	v_permlane16_swap_b32_e32 v1, v0
	v_sub_f32_e32 v2, v175, v153
	v_exp_f32_e32 v64, v2
	s_waitcnt lgkmcnt(0)
	v_add_f32_e32 v65, v0, v1
	ds_bpermute_b32 v66, v217, v65
	v_cmp_eq_f32_e32 vcc, 1.0, v64
	s_cmp_lg_u64 vcc, exec
	s_cbranch_scc0 .LBB0_1372
	v_pk_mul_f32 v[34:35], v[78:79], v[64:65] op_sel_hi:[1,0]
	v_pk_mul_f32 v[32:33], v[76:77], v[64:65] op_sel_hi:[1,0]
	v_pk_mul_f32 v[10:11], v[82:83], v[64:65] op_sel_hi:[1,0]
	v_pk_mul_f32 v[8:9], v[80:81], v[64:65] op_sel_hi:[1,0]
	v_pk_mul_f32 v[6:7], v[86:87], v[64:65] op_sel_hi:[1,0]
	v_pk_mul_f32 v[4:5], v[84:85], v[64:65] op_sel_hi:[1,0]
	v_pk_mul_f32 v[2:3], v[90:91], v[64:65] op_sel_hi:[1,0]
	v_pk_mul_f32 v[0:1], v[88:89], v[64:65] op_sel_hi:[1,0]
	s_mov_b64 s[2:3], 0

.LBB0_1395:
	s_mul_i32 s2, s1, 0x4800
	s_lshl_b32 s14, s14, 6
	s_add_i32 s13, s2, 0
	s_or_b32 s15, s14, 63
	s_cmp_lt_i32 s15, s0
	s_cselect_b64 s[2:3], -1, 0
	s_cmp_gt_i32 s14, s76
	s_cselect_b64 s[92:93], -1, 0
	s_or_b64 s[2:3], s[92:93], s[2:3]
	v_mov_b32_e32 v136, v196
	s_and_b64 vcc, exec, s[2:3]
	s_cbranch_vccnz .LBB0_1405
	v_cmp_ge_i32_e32 vcc, s14, v130
	v_cmp_le_i32_e64 s[2:3], s15, v152
	s_and_b64 s[2:3], vcc, s[2:3]
	v_and_b32_e32 v80, 15, v136
	v_cndmask_b32_e64 v48, 0, 1, s[2:3]
	v_cmp_ne_u32_e32 vcc, 0, v48
	v_and_b32_e32 v48, 48, v136
	v_add_u32_e32 v72, s13, v48
	v_mad_u32_u24 v68, v80, s88, v72
	ds_read_b128 v[48:51], v68
	ds_read_b128 v[52:55], v68 offset:64
	ds_read_b128 v[56:59], v68 offset:2304
	ds_read_b128 v[60:63], v68 offset:2368
	ds_read_b128 v[64:67], v68 offset:4608
	ds_read_b128 v[68:71], v68 offset:4672
	v_and_b32_e32 v92, 63, v136
	v_or_b32_e32 v81, 48, v92
	v_mad_u32_u24 v76, v81, s88, v72
	ds_read_b128 v[72:75], v76
	ds_read_b128 v[76:79], v76 offset:64
	s_cmp_lg_u64 vcc, exec
	v_mul_u32_u24_e32 v137, 0x90, v80
	v_mul_u32_u24_e32 v134, 0x90, v81
	s_mov_b64 s[2:3], -1
	s_cbranch_scc0 .LBB0_1400
	s_waitcnt lgkmcnt(7)
	v_mfma_f32_16x16x32_bf16 v[80:83], v[48:51], v[96:99], 0
	v_lshrrev_b32_e32 v139, 4, v92
	v_lshl_or_b32 v92, v139, 2, s14
	v_cmp_ge_i32_e32 vcc, v92, v130
	s_waitcnt lgkmcnt(5)
	v_mfma_f32_16x16x32_bf16 v[84:87], v[56:59], v[96:99], 0
	v_cmp_le_i32_e64 s[2:3], v92, v152
	s_and_b64 vcc, vcc, s[2:3]
	v_or_b32_e32 v135, 1, v92
	s_waitcnt lgkmcnt(3)
	v_mfma_f32_16x16x32_bf16 v[88:91], v[64:67], v[96:99], 0
	v_cmp_lt_i32_e64 s[2:3], v92, v152
	v_or_b32_e32 v138, 2, v92
	s_waitcnt lgkmcnt(1)
	v_mfma_f32_16x16x32_bf16 v[112:115], v[72:75], v[96:99], 0
	v_mfma_f32_16x16x32_bf16 v[80:83], v[52:55], v[100:103], v[80:83]
	v_mfma_f32_16x16x32_bf16 v[84:87], v[60:63], v[100:103], v[84:87]
	v_mfma_f32_16x16x32_bf16 v[88:91], v[68:71], v[100:103], v[88:91]
	s_waitcnt lgkmcnt(0)
	v_mfma_f32_16x16x32_bf16 v[112:115], v[76:79], v[100:103], v[112:115]
	s_nop 7
	s_nop 3
	v_cndmask_b32_e32 v80, v158, v80, vcc
	v_cmp_ge_i32_e32 vcc, v135, v130
	s_and_b64 vcc, s[2:3], vcc
	v_cmp_le_i32_e64 s[2:3], v138, v152
	v_cndmask_b32_e32 v81, v158, v81, vcc
	v_cmp_ge_i32_e32 vcc, v138, v130
	s_and_b64 vcc, vcc, s[2:3]
	v_or_b32_e32 v138, 3, v92
	v_cndmask_b32_e32 v82, v158, v82, vcc
	v_cmp_ge_i32_e32 vcc, v138, v130
	v_cmp_le_i32_e64 s[2:3], v138, v152
	s_and_b64 vcc, vcc, s[2:3]
	v_or_b32_e32 v138, 16, v92
	v_cndmask_b32_e32 v83, v158, v83, vcc
	v_cmp_ge_i32_e32 vcc, v138, v130
	v_cmp_le_i32_e64 s[2:3], v138, v152
	s_and_b64 vcc, vcc, s[2:3]
	v_or_b32_e32 v138, 17, v92
	v_cndmask_b32_e32 v84, v158, v84, vcc
	v_cmp_ge_i32_e32 vcc, v138, v130
	v_cmp_le_i32_e64 s[2:3], v138, v152
	s_and_b64 vcc, vcc, s[2:3]
	v_or_b32_e32 v138, 18, v92
	v_cndmask_b32_e32 v85, v158, v85, vcc
	v_cmp_ge_i32_e32 vcc, v138, v130
	v_cmp_le_i32_e64 s[2:3], v138, v152
	s_and_b64 vcc, vcc, s[2:3]
	v_or_b32_e32 v138, 19, v92
	v_cndmask_b32_e32 v86, v158, v86, vcc
	v_cmp_ge_i32_e32 vcc, v138, v130
	v_cmp_le_i32_e64 s[2:3], v138, v152
	s_and_b64 vcc, vcc, s[2:3]
	v_or_b32_e32 v138, 32, v92
	v_cndmask_b32_e32 v87, v158, v87, vcc
	v_cmp_ge_i32_e32 vcc, v138, v130
	v_cmp_le_i32_e64 s[2:3], v138, v152
	s_and_b64 vcc, vcc, s[2:3]
	v_or_b32_e32 v138, 33, v92
	v_cndmask_b32_e32 v88, v158, v88, vcc
	v_cmp_ge_i32_e32 vcc, v138, v130
	v_cmp_le_i32_e64 s[2:3], v138, v152
	s_and_b64 vcc, vcc, s[2:3]
	v_or_b32_e32 v138, 34, v92
	v_cndmask_b32_e32 v89, v158, v89, vcc
	v_cmp_ge_i32_e32 vcc, v138, v130
	v_cmp_le_i32_e64 s[2:3], v138, v152
	s_and_b64 vcc, vcc, s[2:3]
	v_or_b32_e32 v138, 35, v92
	v_cndmask_b32_e32 v90, v158, v90, vcc
	v_cmp_ge_i32_e32 vcc, v138, v130
	v_cmp_le_i32_e64 s[2:3], v138, v152
	s_and_b64 vcc, vcc, s[2:3]
	v_or_b32_e32 v138, 48, v92
	v_cndmask_b32_e32 v91, v158, v91, vcc
	v_cmp_ge_i32_e32 vcc, v138, v130
	v_cmp_le_i32_e64 s[2:3], v138, v152
	s_and_b64 vcc, vcc, s[2:3]
	v_or_b32_e32 v138, 49, v92
	v_max3_f32 v135, v80, s87, v81
	v_cndmask_b32_e32 v112, v158, v112, vcc
	v_cmp_ge_i32_e32 vcc, v138, v130
	v_cmp_le_i32_e64 s[2:3], v138, v152
	v_max3_f32 v135, v135, v82, v83
	s_and_b64 vcc, vcc, s[2:3]
	v_or_b32_e32 v138, 50, v92
	v_max3_f32 v135, v135, v84, v85
	v_cndmask_b32_e32 v113, v158, v113, vcc
	v_cmp_ge_i32_e32 vcc, v138, v130
	v_cmp_le_i32_e64 s[2:3], v138, v152
	v_max3_f32 v135, v135, v86, v87
	s_and_b64 vcc, vcc, s[2:3]
	v_or_b32_e32 v92, 51, v92
	v_max3_f32 v135, v135, v88, v89
	v_cndmask_b32_e32 v114, v158, v114, vcc
	v_cmp_ge_i32_e32 vcc, v92, v130
	v_cmp_le_i32_e64 s[2:3], v92, v152
	v_max3_f32 v135, v135, v90, v91
	s_and_b64 vcc, vcc, s[2:3]
	v_max3_f32 v135, v135, v112, v113
	v_cndmask_b32_e32 v92, v158, v115, vcc
	v_max3_f32 v115, v135, v114, v92
	v_mov_b32_e32 v135, v115
	s_nop 1
	v_permlane16_swap_b32_e32 v135, v115
	s_waitcnt lgkmcnt(0)
	v_max3_f32 v115, v115, v135, v158
	v_mov_b32_e32 v135, v115
	s_nop 1
	v_permlane32_swap_b32_e32 v135, v115
	s_waitcnt lgkmcnt(0)
	v_max3_f32 v115, v115, v135, v158
	v_cmp_lt_f32_e32 vcc, s86, v80
	v_max3_f32 v135, v133, v115, v158
	s_nop 0
	v_sub_f32_e32 v115, v80, v135
	v_exp_f32_e32 v115, v115
	v_sub_f32_e32 v138, v81, v135
	v_exp_f32_e32 v138, v138
	v_cndmask_b32_e32 v146, 0, v115, vcc
	v_cmp_lt_f32_e32 vcc, s86, v81
	v_sub_f32_e32 v81, v82, v135
	v_exp_f32_e32 v81, v81
	v_cndmask_b32_e32 v153, 0, v138, vcc
	v_sub_f32_e32 v115, v83, v135
	v_cmp_lt_f32_e32 vcc, s86, v82
	v_exp_f32_e32 v115, v115
	v_sub_f32_e32 v82, v85, v135
	v_cndmask_b32_e32 v162, 0, v81, vcc
	v_sub_f32_e32 v81, v84, v135
	v_exp_f32_e32 v81, v81
	v_exp_f32_e32 v82, v82
	v_cmp_lt_f32_e32 vcc, s86, v83
	v_add_f32_e32 v80, 0, v146
	v_add_f32_e32 v80, v153, v80
	v_cndmask_b32_e32 v163, 0, v115, vcc
	v_cmp_lt_f32_e32 vcc, s86, v84
	v_add_f32_e32 v80, v162, v80
	v_add_f32_e32 v80, v163, v80
	v_cndmask_b32_e32 v164, 0, v81, vcc
	v_cmp_lt_f32_e32 vcc, s86, v85
	v_sub_f32_e32 v81, v86, v135
	v_exp_f32_e32 v81, v81
	v_cndmask_b32_e32 v165, 0, v82, vcc
	v_sub_f32_e32 v82, v87, v135
	v_exp_f32_e32 v82, v82
	v_cmp_lt_f32_e32 vcc, s86, v86
	v_add_f32_e32 v80, v164, v80
	v_add_f32_e32 v80, v165, v80
	v_cndmask_b32_e32 v166, 0, v81, vcc
	v_cmp_lt_f32_e32 vcc, s86, v87
	v_sub_f32_e32 v81, v88, v135
	v_exp_f32_e32 v81, v81
	v_cndmask_b32_e32 v167, 0, v82, vcc
	v_sub_f32_e32 v82, v89, v135
	v_exp_f32_e32 v82, v82
	v_cmp_lt_f32_e32 vcc, s86, v88
	v_add_f32_e32 v80, v166, v80
	v_add_f32_e32 v80, v167, v80
	v_cndmask_b32_e32 v140, 0, v81, vcc
	v_cmp_lt_f32_e32 vcc, s86, v89
	v_sub_f32_e32 v81, v90, v135
	v_exp_f32_e32 v81, v81
	v_cndmask_b32_e32 v141, 0, v82, vcc
	v_sub_f32_e32 v82, v91, v135
	v_exp_f32_e32 v82, v82
	v_cmp_lt_f32_e32 vcc, s86, v90
	v_add_f32_e32 v80, v140, v80
	v_add_f32_e32 v80, v141, v80
	v_cndmask_b32_e32 v142, 0, v81, vcc
	v_cmp_lt_f32_e32 vcc, s86, v91
	v_sub_f32_e32 v81, v112, v135
	v_exp_f32_e32 v81, v81
	v_cndmask_b32_e32 v143, 0, v82, vcc
	v_sub_f32_e32 v82, v113, v135
	v_exp_f32_e32 v82, v82
	v_cmp_lt_f32_e32 vcc, s86, v112
	v_add_f32_e32 v80, v142, v80
	v_add_f32_e32 v80, v143, v80
	v_cndmask_b32_e32 v144, 0, v81, vcc
	v_cmp_lt_f32_e32 vcc, s86, v113
	v_sub_f32_e32 v81, v114, v135
	v_exp_f32_e32 v81, v81
	v_cndmask_b32_e32 v145, 0, v82, vcc
	v_sub_f32_e32 v82, v92, v135
	v_exp_f32_e32 v82, v82
	v_add_f32_e32 v80, v144, v80
	v_cmp_lt_f32_e32 vcc, s86, v114
	v_add_f32_e32 v80, v145, v80
	v_mov_b64_e32 v[86:87], v[14:15]
	v_cndmask_b32_e32 v147, 0, v81, vcc
	v_cmp_lt_f32_e32 vcc, s86, v92
	v_add_f32_e32 v80, v147, v80
	v_mov_b64_e32 v[90:91], v[22:23]
	v_cndmask_b32_e32 v155, 0, v82, vcc
	v_add_f32_e32 v80, v155, v80
	v_mov_b32_e32 v81, v80
	s_nop 1
	v_permlane16_swap_b32_e32 v81, v80
	v_sub_f32_e32 v82, v133, v135
	v_exp_f32_e32 v92, v82
	v_mov_b64_e32 v[114:115], v[46:47]
	v_mov_b64_e32 v[84:85], v[12:13]
	s_waitcnt lgkmcnt(0)
	v_add_f32_e32 v138, v80, v81
	v_mov_b32_e32 v168, v138
	s_nop 1
	v_permlane32_swap_b32_e32 v168, v138
	v_cmp_eq_f32_e32 vcc, 1.0, v92
	v_mov_b64_e32 v[82:83], v[6:7]
	s_cmp_eq_u64 vcc, exec
	v_mov_b64_e32 v[80:81], v[4:5]
	v_mov_b64_e32 v[88:89], v[20:21]
	v_mov_b64_e32 v[112:113], v[44:45]
	s_cbranch_scc1 .LBB0_1399
	v_pk_mul_f32 v[114:115], v[46:47], v[92:93] op_sel_hi:[1,0]
	v_pk_mul_f32 v[112:113], v[44:45], v[92:93] op_sel_hi:[1,0]
	v_pk_mul_f32 v[90:91], v[22:23], v[92:93] op_sel_hi:[1,0]
	v_pk_mul_f32 v[88:89], v[20:21], v[92:93] op_sel_hi:[1,0]
	v_pk_mul_f32 v[86:87], v[14:15], v[92:93] op_sel_hi:[1,0]
	v_pk_mul_f32 v[84:85], v[12:13], v[92:93] op_sel_hi:[1,0]
	v_pk_mul_f32 v[82:83], v[6:7], v[92:93] op_sel_hi:[1,0]
	v_pk_mul_f32 v[80:81], v[4:5], v[92:93] op_sel_hi:[1,0]

.LBB0_1400:
	s_and_b64 vcc, exec, s[2:3]
	s_cbranch_vccz .LBB0_1404
	s_waitcnt lgkmcnt(7)
	v_mfma_f32_16x16x32_bf16 v[48:51], v[48:51], v[96:99], 0
	s_waitcnt lgkmcnt(6)
	v_mfma_f32_16x16x32_bf16 v[48:51], v[52:55], v[100:103], v[48:51]
	s_waitcnt lgkmcnt(5)
	v_mfma_f32_16x16x32_bf16 v[52:55], v[56:59], v[96:99], 0
	s_waitcnt lgkmcnt(3)
	v_mfma_f32_16x16x32_bf16 v[56:59], v[64:67], v[96:99], 0
	s_waitcnt lgkmcnt(2)
	v_mfma_f32_16x16x32_bf16 v[64:67], v[68:71], v[100:103], v[56:59]
	s_waitcnt lgkmcnt(1)
	v_mfma_f32_16x16x32_bf16 v[56:59], v[72:75], v[96:99], 0
	v_mfma_f32_16x16x32_bf16 v[52:55], v[60:63], v[100:103], v[52:55]
	s_waitcnt lgkmcnt(0)
	v_mfma_f32_16x16x32_bf16 v[68:71], v[76:79], v[100:103], v[56:59]
	s_nop 7
	s_nop 0
	v_max3_f32 v56, v158, v48, v49
	v_max3_f32 v56, v56, v50, v51
	v_max3_f32 v56, v56, v52, v53
	v_max3_f32 v56, v56, v54, v55
	v_max3_f32 v56, v56, v64, v65
	v_max3_f32 v56, v56, v66, v67
	v_max3_f32 v56, v56, v68, v69
	v_max3_f32 v56, v56, v70, v71
	v_mov_b32_e32 v57, v56
	s_nop 1
	v_permlane16_swap_b32_e32 v57, v56
	s_waitcnt lgkmcnt(0)
	v_max3_f32 v56, v56, v57, v158
	v_mov_b32_e32 v57, v56
	s_nop 1
	v_permlane32_swap_b32_e32 v57, v56
	s_waitcnt lgkmcnt(0)
	v_max3_f32 v56, v56, v57, v158
	v_max3_f32 v135, v133, v56, v158
	s_nop 0
	v_sub_f32_e32 v51, v51, v135
	v_sub_f32_e32 v50, v50, v135
	v_sub_f32_e32 v49, v49, v135
	v_sub_f32_e32 v48, v48, v135
	v_sub_f32_e32 v55, v55, v135
	v_sub_f32_e32 v54, v54, v135
	v_exp_f32_e32 v56, v48
	v_exp_f32_e32 v57, v49
	v_exp_f32_e32 v58, v50
	v_exp_f32_e32 v59, v51
	v_sub_f32_e32 v48, v53, v135
	v_sub_f32_e32 v49, v52, v135
	v_exp_f32_e32 v60, v49
	v_exp_f32_e32 v62, v54
	v_exp_f32_e32 v63, v55
	v_exp_f32_e32 v61, v48
	v_pk_add_f32 v[48:49], v[56:57], 0 op_sel_hi:[1,0]
	v_pk_add_f32 v[50:51], v[58:59], 0 op_sel_hi:[1,0]
	v_sub_f32_e32 v53, v71, v135
	v_pk_add_f32 v[72:73], v[62:63], v[50:51]
	v_pk_add_f32 v[74:75], v[60:61], v[48:49]
	v_sub_f32_e32 v51, v67, v135
	v_sub_f32_e32 v50, v66, v135
	v_sub_f32_e32 v49, v65, v135
	v_sub_f32_e32 v48, v64, v135
	v_exp_f32_e32 v48, v48
	v_exp_f32_e32 v49, v49
	v_exp_f32_e32 v50, v50
	v_exp_f32_e32 v51, v51
	v_sub_f32_e32 v54, v70, v135
	v_sub_f32_e32 v64, v69, v135
	v_sub_f32_e32 v52, v68, v135
	v_exp_f32_e32 v52, v52
	v_exp_f32_e32 v54, v54
	v_exp_f32_e32 v55, v53
	v_exp_f32_e32 v53, v64
	v_pk_add_f32 v[64:65], v[48:49], v[74:75]
	v_pk_add_f32 v[66:67], v[50:51], v[72:73]
	v_pk_add_f32 v[64:65], v[52:53], v[64:65]
	v_pk_add_f32 v[66:67], v[54:55], v[66:67]
	v_add_f32_e32 v64, v64, v65
	v_add_f32_e32 v65, v66, v67
	v_add_f32_e32 v65, v64, v65
	v_mov_b32_e32 v66, v65
	s_nop 1
	v_permlane16_swap_b32_e32 v66, v65
	v_sub_f32_e32 v64, v133, v135
	v_exp_f32_e32 v64, v64
	s_waitcnt lgkmcnt(0)
	v_add_f32_e32 v65, v65, v66
	ds_bpermute_b32 v66, v217, v65
	v_cmp_eq_f32_e32 vcc, 1.0, v64
	s_cmp_eq_u64 vcc, exec
	s_cbranch_scc1 .LBB0_1403
	v_pk_mul_f32 v[46:47], v[46:47], v[64:65] op_sel_hi:[1,0]
	v_pk_mul_f32 v[44:45], v[44:45], v[64:65] op_sel_hi:[1,0]
	v_pk_mul_f32 v[22:23], v[22:23], v[64:65] op_sel_hi:[1,0]
	v_pk_mul_f32 v[20:21], v[20:21], v[64:65] op_sel_hi:[1,0]
	v_pk_mul_f32 v[14:15], v[14:15], v[64:65] op_sel_hi:[1,0]
	v_pk_mul_f32 v[12:13], v[12:13], v[64:65] op_sel_hi:[1,0]
	v_pk_mul_f32 v[6:7], v[6:7], v[64:65] op_sel_hi:[1,0]
	v_pk_mul_f32 v[4:5], v[4:5], v[64:65] op_sel_hi:[1,0]

.LBB0_1405:
	s_cmp_lt_i32 s15, s78
	s_cselect_b64 s[2:3], -1, 0
	s_cmp_gt_i32 s14, s77
	s_cselect_b64 s[92:93], -1, 0
	s_or_b64 s[2:3], s[92:93], s[2:3]
	v_mov_b32_e32 v136, v196
	s_and_b64 vcc, exec, s[2:3]
	s_cbranch_vccnz .LBB0_1415
	v_cmp_ge_i32_e32 vcc, s14, v131
	v_cmp_le_i32_e64 s[2:3], s15, v154
	s_and_b64 s[2:3], vcc, s[2:3]
	v_and_b32_e32 v80, 15, v136
	s_waitcnt lgkmcnt(7)
	v_cndmask_b32_e64 v48, 0, 1, s[2:3]
	v_cmp_ne_u32_e32 vcc, 0, v48
	v_and_b32_e32 v48, 48, v136
	s_waitcnt lgkmcnt(1)
	v_add_u32_e32 v72, s13, v48
	v_mad_u32_u24 v68, v80, s88, v72
	ds_read_b128 v[48:51], v68
	ds_read_b128 v[52:55], v68 offset:64
	ds_read_b128 v[56:59], v68 offset:2304
	ds_read_b128 v[60:63], v68 offset:2368
	ds_read_b128 v[64:67], v68 offset:4608
	ds_read_b128 v[68:71], v68 offset:4672
	v_and_b32_e32 v92, 63, v136
	v_or_b32_e32 v81, 48, v92
	s_waitcnt lgkmcnt(6)
	v_mad_u32_u24 v76, v81, s88, v72
	ds_read_b128 v[72:75], v76
	ds_read_b128 v[76:79], v76 offset:64
	s_cmp_lg_u64 vcc, exec
	v_mul_u32_u24_e32 v137, 0x90, v80
	v_mul_u32_u24_e32 v134, 0x90, v81
	s_mov_b64 s[2:3], -1
	s_cbranch_scc0 .LBB0_1410
	s_waitcnt lgkmcnt(7)
	v_mfma_f32_16x16x32_bf16 v[80:83], v[48:51], v[104:107], 0
	v_lshrrev_b32_e32 v139, 4, v92
	v_lshl_or_b32 v92, v139, 2, s14
	v_cmp_ge_i32_e32 vcc, v92, v131
	s_waitcnt lgkmcnt(5)
	v_mfma_f32_16x16x32_bf16 v[84:87], v[56:59], v[104:107], 0
	v_cmp_le_i32_e64 s[2:3], v92, v154
	s_and_b64 vcc, vcc, s[2:3]
	v_or_b32_e32 v135, 1, v92
	s_waitcnt lgkmcnt(3)
	v_mfma_f32_16x16x32_bf16 v[88:91], v[64:67], v[104:107], 0
	v_cmp_lt_i32_e64 s[2:3], v92, v154
	v_or_b32_e32 v138, 2, v92
	s_waitcnt lgkmcnt(1)
	v_mfma_f32_16x16x32_bf16 v[112:115], v[72:75], v[104:107], 0
	v_mfma_f32_16x16x32_bf16 v[80:83], v[52:55], v[108:111], v[80:83]
	v_mfma_f32_16x16x32_bf16 v[84:87], v[60:63], v[108:111], v[84:87]
	v_mfma_f32_16x16x32_bf16 v[88:91], v[68:71], v[108:111], v[88:91]
	s_waitcnt lgkmcnt(0)
	v_mfma_f32_16x16x32_bf16 v[112:115], v[76:79], v[108:111], v[112:115]
	s_nop 7
	s_nop 3
	v_cndmask_b32_e32 v80, v158, v80, vcc
	v_cmp_ge_i32_e32 vcc, v135, v131
	s_and_b64 vcc, s[2:3], vcc
	v_cmp_le_i32_e64 s[2:3], v92, v152
	v_cndmask_b32_e32 v81, v158, v81, vcc
	v_cmp_ge_i32_e32 vcc, v138, v131
	s_and_b64 vcc, s[2:3], vcc
	v_or_b32_e32 v138, 3, v92
	v_cndmask_b32_e32 v82, v158, v82, vcc
	v_cmp_ge_i32_e32 vcc, v138, v131
	v_cmp_le_i32_e64 s[2:3], v138, v154
	s_and_b64 vcc, vcc, s[2:3]
	v_or_b32_e32 v138, 16, v92
	v_cndmask_b32_e32 v83, v158, v83, vcc
	v_cmp_ge_i32_e32 vcc, v138, v131
	v_cmp_le_i32_e64 s[2:3], v138, v154
	s_and_b64 vcc, vcc, s[2:3]
	v_or_b32_e32 v138, 17, v92
	v_cndmask_b32_e32 v84, v158, v84, vcc
	v_cmp_ge_i32_e32 vcc, v138, v131
	v_cmp_le_i32_e64 s[2:3], v138, v154
	s_and_b64 vcc, vcc, s[2:3]
	v_or_b32_e32 v138, 18, v92
	v_cndmask_b32_e32 v85, v158, v85, vcc
	v_cmp_ge_i32_e32 vcc, v138, v131
	v_cmp_le_i32_e64 s[2:3], v138, v154
	s_and_b64 vcc, vcc, s[2:3]
	v_or_b32_e32 v138, 19, v92
	v_cndmask_b32_e32 v86, v158, v86, vcc
	v_cmp_ge_i32_e32 vcc, v138, v131
	v_cmp_le_i32_e64 s[2:3], v138, v154
	s_and_b64 vcc, vcc, s[2:3]
	v_or_b32_e32 v138, 32, v92
	v_cndmask_b32_e32 v87, v158, v87, vcc
	v_cmp_ge_i32_e32 vcc, v138, v131
	v_cmp_le_i32_e64 s[2:3], v138, v154
	s_and_b64 vcc, vcc, s[2:3]
	v_or_b32_e32 v138, 33, v92
	v_cndmask_b32_e32 v88, v158, v88, vcc
	v_cmp_ge_i32_e32 vcc, v138, v131
	v_cmp_le_i32_e64 s[2:3], v138, v154
	s_and_b64 vcc, vcc, s[2:3]
	v_or_b32_e32 v138, 34, v92
	v_cndmask_b32_e32 v89, v158, v89, vcc
	v_cmp_ge_i32_e32 vcc, v138, v131
	v_cmp_le_i32_e64 s[2:3], v138, v154
	s_and_b64 vcc, vcc, s[2:3]
	v_or_b32_e32 v138, 35, v92
	v_cndmask_b32_e32 v90, v158, v90, vcc
	v_cmp_ge_i32_e32 vcc, v138, v131
	v_cmp_le_i32_e64 s[2:3], v138, v154
	s_and_b64 vcc, vcc, s[2:3]
	v_or_b32_e32 v138, 48, v92
	v_cndmask_b32_e32 v91, v158, v91, vcc
	v_cmp_ge_i32_e32 vcc, v138, v131
	v_cmp_le_i32_e64 s[2:3], v138, v154
	s_and_b64 vcc, vcc, s[2:3]
	v_or_b32_e32 v138, 49, v92
	v_max3_f32 v135, v80, s87, v81
	v_cndmask_b32_e32 v112, v158, v112, vcc
	v_cmp_ge_i32_e32 vcc, v138, v131
	v_cmp_le_i32_e64 s[2:3], v138, v154
	v_max3_f32 v135, v135, v82, v83
	s_and_b64 vcc, vcc, s[2:3]
	v_or_b32_e32 v138, 50, v92
	v_max3_f32 v135, v135, v84, v85
	v_cndmask_b32_e32 v113, v158, v113, vcc
	v_cmp_ge_i32_e32 vcc, v138, v131
	v_cmp_le_i32_e64 s[2:3], v138, v154
	v_max3_f32 v135, v135, v86, v87
	s_and_b64 vcc, vcc, s[2:3]
	v_or_b32_e32 v92, 51, v92
	v_max3_f32 v135, v135, v88, v89
	v_cndmask_b32_e32 v114, v158, v114, vcc
	v_cmp_ge_i32_e32 vcc, v92, v131
	v_cmp_le_i32_e64 s[2:3], v92, v154
	v_max3_f32 v135, v135, v90, v91
	s_and_b64 vcc, vcc, s[2:3]
	v_max3_f32 v135, v135, v112, v113
	v_cndmask_b32_e32 v92, v158, v115, vcc
	v_max3_f32 v115, v135, v114, v92
	v_mov_b32_e32 v135, v115
	s_nop 1
	v_permlane16_swap_b32_e32 v135, v115
	s_waitcnt lgkmcnt(0)
	v_max3_f32 v115, v115, v135, v158
	v_mov_b32_e32 v135, v115
	s_nop 1
	v_permlane32_swap_b32_e32 v135, v115
	s_waitcnt lgkmcnt(0)
	v_max3_f32 v115, v115, v135, v158
	v_cmp_lt_f32_e32 vcc, s86, v80
	v_max3_f32 v135, v95, v115, v158
	s_nop 0
	v_sub_f32_e32 v115, v80, v135
	v_exp_f32_e32 v115, v115
	v_sub_f32_e32 v138, v81, v135
	v_exp_f32_e32 v138, v138
	v_cndmask_b32_e32 v146, 0, v115, vcc
	v_cmp_lt_f32_e32 vcc, s86, v81
	v_sub_f32_e32 v81, v82, v135
	v_exp_f32_e32 v81, v81
	v_cndmask_b32_e32 v153, 0, v138, vcc
	v_sub_f32_e32 v115, v83, v135
	v_cmp_lt_f32_e32 vcc, s86, v82
	v_exp_f32_e32 v115, v115
	v_sub_f32_e32 v82, v85, v135
	v_cndmask_b32_e32 v162, 0, v81, vcc
	v_sub_f32_e32 v81, v84, v135
	v_exp_f32_e32 v81, v81
	v_exp_f32_e32 v82, v82
	v_cmp_lt_f32_e32 vcc, s86, v83
	v_add_f32_e32 v80, 0, v146
	v_add_f32_e32 v80, v153, v80
	v_cndmask_b32_e32 v163, 0, v115, vcc
	v_cmp_lt_f32_e32 vcc, s86, v84
	v_add_f32_e32 v80, v162, v80
	v_add_f32_e32 v80, v163, v80
	v_cndmask_b32_e32 v164, 0, v81, vcc
	v_cmp_lt_f32_e32 vcc, s86, v85
	v_sub_f32_e32 v81, v86, v135
	v_exp_f32_e32 v81, v81
	v_cndmask_b32_e32 v165, 0, v82, vcc
	v_sub_f32_e32 v82, v87, v135
	v_exp_f32_e32 v82, v82
	v_cmp_lt_f32_e32 vcc, s86, v86
	v_add_f32_e32 v80, v164, v80
	v_add_f32_e32 v80, v165, v80
	v_cndmask_b32_e32 v166, 0, v81, vcc
	v_cmp_lt_f32_e32 vcc, s86, v87
	v_sub_f32_e32 v81, v88, v135
	v_exp_f32_e32 v81, v81
	v_cndmask_b32_e32 v167, 0, v82, vcc
	v_sub_f32_e32 v82, v89, v135
	v_exp_f32_e32 v82, v82
	v_cmp_lt_f32_e32 vcc, s86, v88
	v_add_f32_e32 v80, v166, v80
	v_add_f32_e32 v80, v167, v80
	v_cndmask_b32_e32 v140, 0, v81, vcc
	v_cmp_lt_f32_e32 vcc, s86, v89
	v_sub_f32_e32 v81, v90, v135
	v_exp_f32_e32 v81, v81
	v_cndmask_b32_e32 v141, 0, v82, vcc
	v_sub_f32_e32 v82, v91, v135
	v_exp_f32_e32 v82, v82
	v_cmp_lt_f32_e32 vcc, s86, v90
	v_add_f32_e32 v80, v140, v80
	v_add_f32_e32 v80, v141, v80
	v_cndmask_b32_e32 v142, 0, v81, vcc
	v_cmp_lt_f32_e32 vcc, s86, v91
	v_sub_f32_e32 v81, v112, v135
	v_exp_f32_e32 v81, v81
	v_cndmask_b32_e32 v143, 0, v82, vcc
	v_sub_f32_e32 v82, v113, v135
	v_exp_f32_e32 v82, v82
	v_cmp_lt_f32_e32 vcc, s86, v112
	v_add_f32_e32 v80, v142, v80
	v_add_f32_e32 v80, v143, v80
	v_cndmask_b32_e32 v144, 0, v81, vcc
	v_cmp_lt_f32_e32 vcc, s86, v113
	v_sub_f32_e32 v81, v114, v135
	v_exp_f32_e32 v81, v81
	v_cndmask_b32_e32 v145, 0, v82, vcc
	v_sub_f32_e32 v82, v92, v135
	v_exp_f32_e32 v82, v82
	v_add_f32_e32 v80, v144, v80
	v_cmp_lt_f32_e32 vcc, s86, v114
	v_add_f32_e32 v80, v145, v80
	v_mov_b64_e32 v[86:87], v[10:11]
	v_cndmask_b32_e32 v147, 0, v81, vcc
	v_cmp_lt_f32_e32 vcc, s86, v92
	v_add_f32_e32 v80, v147, v80
	v_mov_b64_e32 v[90:91], v[18:19]
	v_cndmask_b32_e32 v155, 0, v82, vcc
	v_add_f32_e32 v80, v155, v80
	v_mov_b32_e32 v81, v80
	s_nop 1
	v_permlane16_swap_b32_e32 v81, v80
	v_sub_f32_e32 v82, v95, v135
	v_exp_f32_e32 v92, v82
	v_mov_b64_e32 v[114:115], v[42:43]
	v_mov_b64_e32 v[84:85], v[8:9]
	s_waitcnt lgkmcnt(0)
	v_add_f32_e32 v138, v80, v81
	v_mov_b32_e32 v168, v138
	s_nop 1
	v_permlane32_swap_b32_e32 v168, v138
	v_cmp_eq_f32_e32 vcc, 1.0, v92
	v_mov_b64_e32 v[82:83], v[2:3]
	s_cmp_eq_u64 vcc, exec
	v_mov_b64_e32 v[80:81], v[0:1]
	v_mov_b64_e32 v[88:89], v[16:17]
	v_mov_b64_e32 v[112:113], v[40:41]
	s_cbranch_scc1 .LBB0_1409
	v_pk_mul_f32 v[114:115], v[42:43], v[92:93] op_sel_hi:[1,0]
	v_pk_mul_f32 v[112:113], v[40:41], v[92:93] op_sel_hi:[1,0]
	v_pk_mul_f32 v[90:91], v[18:19], v[92:93] op_sel_hi:[1,0]
	v_pk_mul_f32 v[88:89], v[16:17], v[92:93] op_sel_hi:[1,0]
	v_pk_mul_f32 v[86:87], v[10:11], v[92:93] op_sel_hi:[1,0]
	v_pk_mul_f32 v[84:85], v[8:9], v[92:93] op_sel_hi:[1,0]
	v_pk_mul_f32 v[82:83], v[2:3], v[92:93] op_sel_hi:[1,0]
	v_pk_mul_f32 v[80:81], v[0:1], v[92:93] op_sel_hi:[1,0]

.LBB0_1410:
	s_and_b64 vcc, exec, s[2:3]
	s_cbranch_vccz .LBB0_1414
	s_waitcnt lgkmcnt(7)
	v_mfma_f32_16x16x32_bf16 v[48:51], v[48:51], v[104:107], 0
	s_waitcnt lgkmcnt(6)
	v_mfma_f32_16x16x32_bf16 v[48:51], v[52:55], v[108:111], v[48:51]
	s_waitcnt lgkmcnt(5)
	v_mfma_f32_16x16x32_bf16 v[52:55], v[56:59], v[104:107], 0
	s_waitcnt lgkmcnt(3)
	v_mfma_f32_16x16x32_bf16 v[56:59], v[64:67], v[104:107], 0
	s_waitcnt lgkmcnt(2)
	v_mfma_f32_16x16x32_bf16 v[64:67], v[68:71], v[108:111], v[56:59]
	s_waitcnt lgkmcnt(1)
	v_mfma_f32_16x16x32_bf16 v[56:59], v[72:75], v[104:107], 0
	v_mfma_f32_16x16x32_bf16 v[52:55], v[60:63], v[108:111], v[52:55]
	s_waitcnt lgkmcnt(0)
	v_mfma_f32_16x16x32_bf16 v[68:71], v[76:79], v[108:111], v[56:59]
	s_nop 7
	s_nop 0
	v_max3_f32 v56, v158, v48, v49
	v_max3_f32 v56, v56, v50, v51
	v_max3_f32 v56, v56, v52, v53
	v_max3_f32 v56, v56, v54, v55
	v_max3_f32 v56, v56, v64, v65
	v_max3_f32 v56, v56, v66, v67
	v_max3_f32 v56, v56, v68, v69
	v_max3_f32 v56, v56, v70, v71
	v_mov_b32_e32 v57, v56
	s_nop 1
	v_permlane16_swap_b32_e32 v57, v56
	s_waitcnt lgkmcnt(0)
	v_max3_f32 v56, v56, v57, v158
	v_mov_b32_e32 v57, v56
	s_nop 1
	v_permlane32_swap_b32_e32 v57, v56
	s_waitcnt lgkmcnt(0)
	v_max3_f32 v56, v56, v57, v158
	v_max3_f32 v135, v95, v56, v158
	s_nop 0
	v_sub_f32_e32 v51, v51, v135
	v_sub_f32_e32 v50, v50, v135
	v_sub_f32_e32 v49, v49, v135
	v_sub_f32_e32 v48, v48, v135
	v_sub_f32_e32 v55, v55, v135
	v_sub_f32_e32 v54, v54, v135
	v_exp_f32_e32 v56, v48
	v_exp_f32_e32 v57, v49
	v_exp_f32_e32 v58, v50
	v_exp_f32_e32 v59, v51
	v_sub_f32_e32 v48, v53, v135
	v_sub_f32_e32 v49, v52, v135
	v_exp_f32_e32 v60, v49
	v_exp_f32_e32 v62, v54
	v_exp_f32_e32 v63, v55
	v_exp_f32_e32 v61, v48
	v_pk_add_f32 v[48:49], v[56:57], 0 op_sel_hi:[1,0]
	v_pk_add_f32 v[50:51], v[58:59], 0 op_sel_hi:[1,0]
	v_sub_f32_e32 v53, v71, v135
	v_pk_add_f32 v[72:73], v[62:63], v[50:51]
	v_pk_add_f32 v[74:75], v[60:61], v[48:49]
	v_sub_f32_e32 v51, v67, v135
	v_sub_f32_e32 v50, v66, v135
	v_sub_f32_e32 v49, v65, v135
	v_sub_f32_e32 v48, v64, v135
	v_exp_f32_e32 v48, v48
	v_exp_f32_e32 v49, v49
	v_exp_f32_e32 v50, v50
	v_exp_f32_e32 v51, v51
	v_sub_f32_e32 v54, v70, v135
	v_sub_f32_e32 v64, v69, v135
	v_sub_f32_e32 v52, v68, v135
	v_exp_f32_e32 v52, v52
	v_exp_f32_e32 v54, v54
	v_exp_f32_e32 v55, v53
	v_exp_f32_e32 v53, v64
	v_pk_add_f32 v[64:65], v[48:49], v[74:75]
	v_pk_add_f32 v[66:67], v[50:51], v[72:73]
	v_pk_add_f32 v[64:65], v[52:53], v[64:65]
	v_pk_add_f32 v[66:67], v[54:55], v[66:67]
	v_add_f32_e32 v64, v64, v65
	v_add_f32_e32 v65, v66, v67
	v_add_f32_e32 v65, v64, v65
	v_mov_b32_e32 v66, v65
	s_nop 1
	v_permlane16_swap_b32_e32 v66, v65
	v_sub_f32_e32 v64, v95, v135
	v_exp_f32_e32 v64, v64
	s_waitcnt lgkmcnt(0)
	v_add_f32_e32 v65, v65, v66
	ds_bpermute_b32 v66, v217, v65
	v_cmp_eq_f32_e32 vcc, 1.0, v64
	s_cmp_eq_u64 vcc, exec
	s_cbranch_scc1 .LBB0_1413
	v_pk_mul_f32 v[42:43], v[42:43], v[64:65] op_sel_hi:[1,0]
	v_pk_mul_f32 v[40:41], v[40:41], v[64:65] op_sel_hi:[1,0]
	v_pk_mul_f32 v[18:19], v[18:19], v[64:65] op_sel_hi:[1,0]
	v_pk_mul_f32 v[16:17], v[16:17], v[64:65] op_sel_hi:[1,0]
	v_pk_mul_f32 v[10:11], v[10:11], v[64:65] op_sel_hi:[1,0]
	v_pk_mul_f32 v[8:9], v[8:9], v[64:65] op_sel_hi:[1,0]
	v_pk_mul_f32 v[2:3], v[2:3], v[64:65] op_sel_hi:[1,0]
	v_pk_mul_f32 v[0:1], v[0:1], v[64:65] op_sel_hi:[1,0]

.LBB0_1415:
	s_cmp_lt_i32 s74, 0
	s_cbranch_scc1 .LBB0_1436
	s_lshl_b32 s14, s74, 6
	s_or_b32 s15, s14, 63
	s_cmp_lt_i32 s15, s0
	s_cselect_b64 s[2:3], -1, 0
	s_cmp_gt_i32 s14, s76
	s_cselect_b64 s[74:75], -1, 0
	s_or_b64 s[2:3], s[74:75], s[2:3]
	v_mov_b32_e32 v136, v196
	s_and_b64 vcc, exec, s[2:3]
	s_cbranch_vccnz .LBB0_1426
	v_cmp_ge_i32_e32 vcc, s14, v130
	v_cmp_le_i32_e64 s[2:3], s15, v152
	s_and_b64 s[2:3], vcc, s[2:3]
	v_and_b32_e32 v80, 15, v136
	s_waitcnt lgkmcnt(7)
	v_cndmask_b32_e64 v48, 0, 1, s[2:3]
	v_cmp_ne_u32_e32 vcc, 0, v48
	v_and_b32_e32 v48, 48, v136
	s_waitcnt lgkmcnt(1)
	v_add_u32_e32 v72, s13, v48
	v_mad_u32_u24 v68, v80, s88, v72
	ds_read_b128 v[48:51], v68 offset:9216
	ds_read_b128 v[52:55], v68 offset:9280
	ds_read_b128 v[56:59], v68 offset:11520
	ds_read_b128 v[60:63], v68 offset:11584
	ds_read_b128 v[64:67], v68 offset:13824
	ds_read_b128 v[68:71], v68 offset:13888
	v_and_b32_e32 v92, 63, v136
	v_or_b32_e32 v81, 48, v92
	s_waitcnt lgkmcnt(6)
	v_mad_u32_u24 v76, v81, s88, v72
	ds_read_b128 v[72:75], v76 offset:9216
	ds_read_b128 v[76:79], v76 offset:9280
	s_cmp_lg_u64 vcc, exec
	v_mul_u32_u24_e32 v137, 0x90, v80
	v_mul_u32_u24_e32 v134, 0x90, v81
	s_mov_b64 s[2:3], -1
	s_cbranch_scc0 .LBB0_1421
	s_waitcnt lgkmcnt(7)
	v_mfma_f32_16x16x32_bf16 v[80:83], v[48:51], v[96:99], 0
	v_lshrrev_b32_e32 v139, 4, v92
	v_lshl_or_b32 v92, v139, 2, s14
	v_cmp_ge_i32_e32 vcc, v92, v130
	s_waitcnt lgkmcnt(5)
	v_mfma_f32_16x16x32_bf16 v[84:87], v[56:59], v[96:99], 0
	v_cmp_le_i32_e64 s[2:3], v92, v152
	s_and_b64 vcc, vcc, s[2:3]
	v_or_b32_e32 v135, 1, v92
	s_waitcnt lgkmcnt(3)
	v_mfma_f32_16x16x32_bf16 v[88:91], v[64:67], v[96:99], 0
	v_cmp_lt_i32_e64 s[2:3], v92, v152
	v_or_b32_e32 v138, 2, v92
	s_waitcnt lgkmcnt(1)
	v_mfma_f32_16x16x32_bf16 v[112:115], v[72:75], v[96:99], 0
	v_mfma_f32_16x16x32_bf16 v[80:83], v[52:55], v[100:103], v[80:83]
	v_mfma_f32_16x16x32_bf16 v[84:87], v[60:63], v[100:103], v[84:87]
	v_mfma_f32_16x16x32_bf16 v[88:91], v[68:71], v[100:103], v[88:91]
	s_waitcnt lgkmcnt(0)
	v_mfma_f32_16x16x32_bf16 v[112:115], v[76:79], v[100:103], v[112:115]
	s_nop 7
	s_nop 3
	v_cndmask_b32_e32 v80, v158, v80, vcc
	v_cmp_ge_i32_e32 vcc, v135, v130
	s_and_b64 vcc, s[2:3], vcc
	v_cmp_le_i32_e64 s[2:3], v138, v152
	v_cndmask_b32_e32 v81, v158, v81, vcc
	v_cmp_ge_i32_e32 vcc, v138, v130
	s_and_b64 vcc, vcc, s[2:3]
	v_or_b32_e32 v138, 3, v92
	v_cndmask_b32_e32 v82, v158, v82, vcc
	v_cmp_ge_i32_e32 vcc, v138, v130
	v_cmp_le_i32_e64 s[2:3], v138, v152
	s_and_b64 vcc, vcc, s[2:3]
	v_or_b32_e32 v138, 16, v92
	v_cndmask_b32_e32 v83, v158, v83, vcc
	v_cmp_ge_i32_e32 vcc, v138, v130
	v_cmp_le_i32_e64 s[2:3], v138, v152
	s_and_b64 vcc, vcc, s[2:3]
	v_or_b32_e32 v138, 17, v92
	v_cndmask_b32_e32 v84, v158, v84, vcc
	v_cmp_ge_i32_e32 vcc, v138, v130
	v_cmp_le_i32_e64 s[2:3], v138, v152
	s_and_b64 vcc, vcc, s[2:3]
	v_or_b32_e32 v138, 18, v92
	v_cndmask_b32_e32 v85, v158, v85, vcc
	v_cmp_ge_i32_e32 vcc, v138, v130
	v_cmp_le_i32_e64 s[2:3], v138, v152
	s_and_b64 vcc, vcc, s[2:3]
	v_or_b32_e32 v138, 19, v92
	v_cndmask_b32_e32 v86, v158, v86, vcc
	v_cmp_ge_i32_e32 vcc, v138, v130
	v_cmp_le_i32_e64 s[2:3], v138, v152
	s_and_b64 vcc, vcc, s[2:3]
	v_or_b32_e32 v138, 32, v92
	v_cndmask_b32_e32 v87, v158, v87, vcc
	v_cmp_ge_i32_e32 vcc, v138, v130
	v_cmp_le_i32_e64 s[2:3], v138, v152
	s_and_b64 vcc, vcc, s[2:3]
	v_or_b32_e32 v138, 33, v92
	v_cndmask_b32_e32 v88, v158, v88, vcc
	v_cmp_ge_i32_e32 vcc, v138, v130
	v_cmp_le_i32_e64 s[2:3], v138, v152
	s_and_b64 vcc, vcc, s[2:3]
	v_or_b32_e32 v138, 34, v92
	v_cndmask_b32_e32 v89, v158, v89, vcc
	v_cmp_ge_i32_e32 vcc, v138, v130
	v_cmp_le_i32_e64 s[2:3], v138, v152
	s_and_b64 vcc, vcc, s[2:3]
	v_or_b32_e32 v138, 35, v92
	v_cndmask_b32_e32 v90, v158, v90, vcc
	v_cmp_ge_i32_e32 vcc, v138, v130
	v_cmp_le_i32_e64 s[2:3], v138, v152
	s_and_b64 vcc, vcc, s[2:3]
	v_or_b32_e32 v138, 48, v92
	v_cndmask_b32_e32 v91, v158, v91, vcc
	v_cmp_ge_i32_e32 vcc, v138, v130
	v_cmp_le_i32_e64 s[2:3], v138, v152
	s_and_b64 vcc, vcc, s[2:3]
	v_or_b32_e32 v138, 49, v92
	v_max3_f32 v135, v80, s87, v81
	v_cndmask_b32_e32 v112, v158, v112, vcc
	v_cmp_ge_i32_e32 vcc, v138, v130
	v_cmp_le_i32_e64 s[2:3], v138, v152
	v_max3_f32 v135, v135, v82, v83
	s_and_b64 vcc, vcc, s[2:3]
	v_or_b32_e32 v138, 50, v92
	v_max3_f32 v135, v135, v84, v85
	v_cndmask_b32_e32 v113, v158, v113, vcc
	v_cmp_ge_i32_e32 vcc, v138, v130
	v_cmp_le_i32_e64 s[2:3], v138, v152
	v_max3_f32 v135, v135, v86, v87
	s_and_b64 vcc, vcc, s[2:3]
	v_or_b32_e32 v92, 51, v92
	v_max3_f32 v135, v135, v88, v89
	v_cndmask_b32_e32 v114, v158, v114, vcc
	v_cmp_ge_i32_e32 vcc, v92, v130
	v_cmp_le_i32_e64 s[2:3], v92, v152
	v_max3_f32 v135, v135, v90, v91
	s_and_b64 vcc, vcc, s[2:3]
	v_max3_f32 v135, v135, v112, v113
	v_cndmask_b32_e32 v92, v158, v115, vcc
	v_max3_f32 v115, v135, v114, v92
	v_mov_b32_e32 v135, v115
	s_nop 1
	v_permlane16_swap_b32_e32 v135, v115
	s_waitcnt lgkmcnt(0)
	v_max3_f32 v115, v115, v135, v158
	v_mov_b32_e32 v135, v115
	s_nop 1
	v_permlane32_swap_b32_e32 v135, v115
	s_waitcnt lgkmcnt(0)
	v_max3_f32 v115, v115, v135, v158
	v_cmp_lt_f32_e32 vcc, s86, v80
	v_max3_f32 v135, v133, v115, v158
	s_nop 0
	v_sub_f32_e32 v115, v80, v135
	v_exp_f32_e32 v115, v115
	v_sub_f32_e32 v138, v81, v135
	v_exp_f32_e32 v138, v138
	v_cndmask_b32_e32 v146, 0, v115, vcc
	v_cmp_lt_f32_e32 vcc, s86, v81
	v_sub_f32_e32 v81, v82, v135
	v_exp_f32_e32 v81, v81
	v_cndmask_b32_e32 v153, 0, v138, vcc
	v_sub_f32_e32 v115, v83, v135
	v_cmp_lt_f32_e32 vcc, s86, v82
	v_exp_f32_e32 v115, v115
	v_sub_f32_e32 v82, v85, v135
	v_cndmask_b32_e32 v162, 0, v81, vcc
	v_sub_f32_e32 v81, v84, v135
	v_exp_f32_e32 v81, v81
	v_exp_f32_e32 v82, v82
	v_cmp_lt_f32_e32 vcc, s86, v83
	v_add_f32_e32 v80, 0, v146
	v_add_f32_e32 v80, v153, v80
	v_cndmask_b32_e32 v163, 0, v115, vcc
	v_cmp_lt_f32_e32 vcc, s86, v84
	v_add_f32_e32 v80, v162, v80
	v_add_f32_e32 v80, v163, v80
	v_cndmask_b32_e32 v164, 0, v81, vcc
	v_cmp_lt_f32_e32 vcc, s86, v85
	v_sub_f32_e32 v81, v86, v135
	v_exp_f32_e32 v81, v81
	v_cndmask_b32_e32 v165, 0, v82, vcc
	v_sub_f32_e32 v82, v87, v135
	v_exp_f32_e32 v82, v82
	v_cmp_lt_f32_e32 vcc, s86, v86
	v_add_f32_e32 v80, v164, v80
	v_add_f32_e32 v80, v165, v80
	v_cndmask_b32_e32 v166, 0, v81, vcc
	v_cmp_lt_f32_e32 vcc, s86, v87
	v_sub_f32_e32 v81, v88, v135
	v_exp_f32_e32 v81, v81
	v_cndmask_b32_e32 v167, 0, v82, vcc
	v_sub_f32_e32 v82, v89, v135
	v_exp_f32_e32 v82, v82
	v_cmp_lt_f32_e32 vcc, s86, v88
	v_add_f32_e32 v80, v166, v80
	v_add_f32_e32 v80, v167, v80
	v_cndmask_b32_e32 v140, 0, v81, vcc
	v_cmp_lt_f32_e32 vcc, s86, v89
	v_sub_f32_e32 v81, v90, v135
	v_exp_f32_e32 v81, v81
	v_cndmask_b32_e32 v141, 0, v82, vcc
	v_sub_f32_e32 v82, v91, v135
	v_exp_f32_e32 v82, v82
	v_cmp_lt_f32_e32 vcc, s86, v90
	v_add_f32_e32 v80, v140, v80
	v_add_f32_e32 v80, v141, v80
	v_cndmask_b32_e32 v142, 0, v81, vcc
	v_cmp_lt_f32_e32 vcc, s86, v91
	v_sub_f32_e32 v81, v112, v135
	v_exp_f32_e32 v81, v81
	v_cndmask_b32_e32 v143, 0, v82, vcc
	v_sub_f32_e32 v82, v113, v135
	v_exp_f32_e32 v82, v82
	v_cmp_lt_f32_e32 vcc, s86, v112
	v_add_f32_e32 v80, v142, v80
	v_add_f32_e32 v80, v143, v80
	v_cndmask_b32_e32 v144, 0, v81, vcc
	v_cmp_lt_f32_e32 vcc, s86, v113
	v_sub_f32_e32 v81, v114, v135
	v_exp_f32_e32 v81, v81
	v_cndmask_b32_e32 v145, 0, v82, vcc
	v_sub_f32_e32 v82, v92, v135
	v_exp_f32_e32 v82, v82
	v_add_f32_e32 v80, v144, v80
	v_cmp_lt_f32_e32 vcc, s86, v114
	v_add_f32_e32 v80, v145, v80
	v_mov_b64_e32 v[86:87], v[14:15]
	v_cndmask_b32_e32 v147, 0, v81, vcc
	v_cmp_lt_f32_e32 vcc, s86, v92
	v_add_f32_e32 v80, v147, v80
	v_mov_b64_e32 v[90:91], v[22:23]
	v_cndmask_b32_e32 v155, 0, v82, vcc
	v_add_f32_e32 v80, v155, v80
	v_mov_b32_e32 v81, v80
	s_nop 1
	v_permlane16_swap_b32_e32 v81, v80
	v_sub_f32_e32 v82, v133, v135
	v_exp_f32_e32 v92, v82
	v_mov_b64_e32 v[114:115], v[46:47]
	v_mov_b64_e32 v[84:85], v[12:13]
	s_waitcnt lgkmcnt(0)
	v_add_f32_e32 v138, v80, v81
	v_mov_b32_e32 v168, v138
	s_nop 1
	v_permlane32_swap_b32_e32 v168, v138
	v_cmp_eq_f32_e32 vcc, 1.0, v92
	v_mov_b64_e32 v[82:83], v[6:7]
	s_cmp_eq_u64 vcc, exec
	v_mov_b64_e32 v[80:81], v[4:5]
	v_mov_b64_e32 v[88:89], v[20:21]
	v_mov_b64_e32 v[112:113], v[44:45]
	s_cbranch_scc1 .LBB0_1420
	v_pk_mul_f32 v[114:115], v[46:47], v[92:93] op_sel_hi:[1,0]
	v_pk_mul_f32 v[112:113], v[44:45], v[92:93] op_sel_hi:[1,0]
	v_pk_mul_f32 v[90:91], v[22:23], v[92:93] op_sel_hi:[1,0]
	v_pk_mul_f32 v[88:89], v[20:21], v[92:93] op_sel_hi:[1,0]
	v_pk_mul_f32 v[86:87], v[14:15], v[92:93] op_sel_hi:[1,0]
	v_pk_mul_f32 v[84:85], v[12:13], v[92:93] op_sel_hi:[1,0]
	v_pk_mul_f32 v[82:83], v[6:7], v[92:93] op_sel_hi:[1,0]
	v_pk_mul_f32 v[80:81], v[4:5], v[92:93] op_sel_hi:[1,0]

.LBB0_1426:
	s_cmp_lt_i32 s15, s78
	s_cselect_b64 s[2:3], -1, 0
	s_cmp_gt_i32 s14, s77
	s_cselect_b64 s[74:75], -1, 0
	s_or_b64 s[2:3], s[74:75], s[2:3]
	v_mov_b32_e32 v136, v196
	s_and_b64 vcc, exec, s[2:3]
	s_cbranch_vccnz .LBB0_1436
	v_cmp_ge_i32_e32 vcc, s14, v131
	v_cmp_le_i32_e64 s[2:3], s15, v154
	s_and_b64 s[2:3], vcc, s[2:3]
	v_and_b32_e32 v80, 15, v136
	s_waitcnt lgkmcnt(7)
	v_cndmask_b32_e64 v48, 0, 1, s[2:3]
	v_cmp_ne_u32_e32 vcc, 0, v48
	v_and_b32_e32 v48, 48, v136
	s_waitcnt lgkmcnt(1)
	v_add_u32_e32 v72, s13, v48
	v_mad_u32_u24 v68, v80, s88, v72
	ds_read_b128 v[48:51], v68 offset:9216
	ds_read_b128 v[52:55], v68 offset:9280
	ds_read_b128 v[56:59], v68 offset:11520
	ds_read_b128 v[60:63], v68 offset:11584
	ds_read_b128 v[64:67], v68 offset:13824
	ds_read_b128 v[68:71], v68 offset:13888
	v_and_b32_e32 v92, 63, v136
	v_or_b32_e32 v81, 48, v92
	s_waitcnt lgkmcnt(6)
	v_mad_u32_u24 v76, v81, s88, v72
	ds_read_b128 v[72:75], v76 offset:9216
	ds_read_b128 v[76:79], v76 offset:9280
	s_cmp_lg_u64 vcc, exec
	v_mul_u32_u24_e32 v137, 0x90, v80
	v_mul_u32_u24_e32 v134, 0x90, v81
	s_mov_b64 s[2:3], -1
	s_cbranch_scc0 .LBB0_1431
	s_waitcnt lgkmcnt(7)
	v_mfma_f32_16x16x32_bf16 v[80:83], v[48:51], v[104:107], 0
	v_lshrrev_b32_e32 v139, 4, v92
	v_lshl_or_b32 v92, v139, 2, s14
	v_cmp_ge_i32_e32 vcc, v92, v131
	s_waitcnt lgkmcnt(5)
	v_mfma_f32_16x16x32_bf16 v[84:87], v[56:59], v[104:107], 0
	v_cmp_le_i32_e64 s[2:3], v92, v154
	s_and_b64 vcc, vcc, s[2:3]
	v_or_b32_e32 v135, 1, v92
	s_waitcnt lgkmcnt(3)
	v_mfma_f32_16x16x32_bf16 v[88:91], v[64:67], v[104:107], 0
	v_cmp_lt_i32_e64 s[2:3], v92, v154
	v_or_b32_e32 v138, 2, v92
	s_waitcnt lgkmcnt(1)
	v_mfma_f32_16x16x32_bf16 v[112:115], v[72:75], v[104:107], 0
	v_mfma_f32_16x16x32_bf16 v[80:83], v[52:55], v[108:111], v[80:83]
	v_mfma_f32_16x16x32_bf16 v[84:87], v[60:63], v[108:111], v[84:87]
	v_mfma_f32_16x16x32_bf16 v[88:91], v[68:71], v[108:111], v[88:91]
	s_waitcnt lgkmcnt(0)
	v_mfma_f32_16x16x32_bf16 v[112:115], v[76:79], v[108:111], v[112:115]
	s_nop 7
	s_nop 3
	v_cndmask_b32_e32 v80, v158, v80, vcc
	v_cmp_ge_i32_e32 vcc, v135, v131
	s_and_b64 vcc, s[2:3], vcc
	v_cmp_le_i32_e64 s[2:3], v92, v152
	v_cndmask_b32_e32 v81, v158, v81, vcc
	v_cmp_ge_i32_e32 vcc, v138, v131
	s_and_b64 vcc, s[2:3], vcc
	v_or_b32_e32 v138, 3, v92
	v_cndmask_b32_e32 v82, v158, v82, vcc
	v_cmp_ge_i32_e32 vcc, v138, v131
	v_cmp_le_i32_e64 s[2:3], v138, v154
	s_and_b64 vcc, vcc, s[2:3]
	v_or_b32_e32 v138, 16, v92
	v_cndmask_b32_e32 v83, v158, v83, vcc
	v_cmp_ge_i32_e32 vcc, v138, v131
	v_cmp_le_i32_e64 s[2:3], v138, v154
	s_and_b64 vcc, vcc, s[2:3]
	v_or_b32_e32 v138, 17, v92
	v_cndmask_b32_e32 v84, v158, v84, vcc
	v_cmp_ge_i32_e32 vcc, v138, v131
	v_cmp_le_i32_e64 s[2:3], v138, v154
	s_and_b64 vcc, vcc, s[2:3]
	v_or_b32_e32 v138, 18, v92
	v_cndmask_b32_e32 v85, v158, v85, vcc
	v_cmp_ge_i32_e32 vcc, v138, v131
	v_cmp_le_i32_e64 s[2:3], v138, v154
	s_and_b64 vcc, vcc, s[2:3]
	v_or_b32_e32 v138, 19, v92
	v_cndmask_b32_e32 v86, v158, v86, vcc
	v_cmp_ge_i32_e32 vcc, v138, v131
	v_cmp_le_i32_e64 s[2:3], v138, v154
	s_and_b64 vcc, vcc, s[2:3]
	v_or_b32_e32 v138, 32, v92
	v_cndmask_b32_e32 v87, v158, v87, vcc
	v_cmp_ge_i32_e32 vcc, v138, v131
	v_cmp_le_i32_e64 s[2:3], v138, v154
	s_and_b64 vcc, vcc, s[2:3]
	v_or_b32_e32 v138, 33, v92
	v_cndmask_b32_e32 v88, v158, v88, vcc
	v_cmp_ge_i32_e32 vcc, v138, v131
	v_cmp_le_i32_e64 s[2:3], v138, v154
	s_and_b64 vcc, vcc, s[2:3]
	v_or_b32_e32 v138, 34, v92
	v_cndmask_b32_e32 v89, v158, v89, vcc
	v_cmp_ge_i32_e32 vcc, v138, v131
	v_cmp_le_i32_e64 s[2:3], v138, v154
	s_and_b64 vcc, vcc, s[2:3]
	v_or_b32_e32 v138, 35, v92
	v_cndmask_b32_e32 v90, v158, v90, vcc
	v_cmp_ge_i32_e32 vcc, v138, v131
	v_cmp_le_i32_e64 s[2:3], v138, v154
	s_and_b64 vcc, vcc, s[2:3]
	v_or_b32_e32 v138, 48, v92
	v_cndmask_b32_e32 v91, v158, v91, vcc
	v_cmp_ge_i32_e32 vcc, v138, v131
	v_cmp_le_i32_e64 s[2:3], v138, v154
	s_and_b64 vcc, vcc, s[2:3]
	v_or_b32_e32 v138, 49, v92
	v_max3_f32 v135, v80, s87, v81
	v_cndmask_b32_e32 v112, v158, v112, vcc
	v_cmp_ge_i32_e32 vcc, v138, v131
	v_cmp_le_i32_e64 s[2:3], v138, v154
	v_max3_f32 v135, v135, v82, v83
	s_and_b64 vcc, vcc, s[2:3]
	v_or_b32_e32 v138, 50, v92
	v_max3_f32 v135, v135, v84, v85
	v_cndmask_b32_e32 v113, v158, v113, vcc
	v_cmp_ge_i32_e32 vcc, v138, v131
	v_cmp_le_i32_e64 s[2:3], v138, v154
	v_max3_f32 v135, v135, v86, v87
	s_and_b64 vcc, vcc, s[2:3]
	v_or_b32_e32 v92, 51, v92
	v_max3_f32 v135, v135, v88, v89
	v_cndmask_b32_e32 v114, v158, v114, vcc
	v_cmp_ge_i32_e32 vcc, v92, v131
	v_cmp_le_i32_e64 s[2:3], v92, v154
	v_max3_f32 v135, v135, v90, v91
	s_and_b64 vcc, vcc, s[2:3]
	v_max3_f32 v135, v135, v112, v113
	v_cndmask_b32_e32 v92, v158, v115, vcc
	v_max3_f32 v115, v135, v114, v92
	v_mov_b32_e32 v135, v115
	s_nop 1
	v_permlane16_swap_b32_e32 v135, v115
	s_waitcnt lgkmcnt(0)
	v_max3_f32 v115, v115, v135, v158
	v_mov_b32_e32 v135, v115
	s_nop 1
	v_permlane32_swap_b32_e32 v135, v115
	s_waitcnt lgkmcnt(0)
	v_max3_f32 v115, v115, v135, v158
	v_cmp_lt_f32_e32 vcc, s86, v80
	v_max3_f32 v135, v95, v115, v158
	s_nop 0
	v_sub_f32_e32 v115, v80, v135
	v_exp_f32_e32 v115, v115
	v_sub_f32_e32 v138, v81, v135
	v_exp_f32_e32 v138, v138
	v_cndmask_b32_e32 v146, 0, v115, vcc
	v_cmp_lt_f32_e32 vcc, s86, v81
	v_sub_f32_e32 v81, v82, v135
	v_exp_f32_e32 v81, v81
	v_cndmask_b32_e32 v153, 0, v138, vcc
	v_sub_f32_e32 v115, v83, v135
	v_cmp_lt_f32_e32 vcc, s86, v82
	v_exp_f32_e32 v115, v115
	v_sub_f32_e32 v82, v85, v135
	v_cndmask_b32_e32 v162, 0, v81, vcc
	v_sub_f32_e32 v81, v84, v135
	v_exp_f32_e32 v81, v81
	v_exp_f32_e32 v82, v82
	v_cmp_lt_f32_e32 vcc, s86, v83
	v_add_f32_e32 v80, 0, v146
	v_add_f32_e32 v80, v153, v80
	v_cndmask_b32_e32 v163, 0, v115, vcc
	v_cmp_lt_f32_e32 vcc, s86, v84
	v_add_f32_e32 v80, v162, v80
	v_add_f32_e32 v80, v163, v80
	v_cndmask_b32_e32 v164, 0, v81, vcc
	v_cmp_lt_f32_e32 vcc, s86, v85
	v_sub_f32_e32 v81, v86, v135
	v_exp_f32_e32 v81, v81
	v_cndmask_b32_e32 v165, 0, v82, vcc
	v_sub_f32_e32 v82, v87, v135
	v_exp_f32_e32 v82, v82
	v_cmp_lt_f32_e32 vcc, s86, v86
	v_add_f32_e32 v80, v164, v80
	v_add_f32_e32 v80, v165, v80
	v_cndmask_b32_e32 v166, 0, v81, vcc
	v_cmp_lt_f32_e32 vcc, s86, v87
	v_sub_f32_e32 v81, v88, v135
	v_exp_f32_e32 v81, v81
	v_cndmask_b32_e32 v167, 0, v82, vcc
	v_sub_f32_e32 v82, v89, v135
	v_exp_f32_e32 v82, v82
	v_cmp_lt_f32_e32 vcc, s86, v88
	v_add_f32_e32 v80, v166, v80
	v_add_f32_e32 v80, v167, v80
	v_cndmask_b32_e32 v140, 0, v81, vcc
	v_cmp_lt_f32_e32 vcc, s86, v89
	v_sub_f32_e32 v81, v90, v135
	v_exp_f32_e32 v81, v81
	v_cndmask_b32_e32 v141, 0, v82, vcc
	v_sub_f32_e32 v82, v91, v135
	v_exp_f32_e32 v82, v82
	v_cmp_lt_f32_e32 vcc, s86, v90
	v_add_f32_e32 v80, v140, v80
	v_add_f32_e32 v80, v141, v80
	v_cndmask_b32_e32 v142, 0, v81, vcc
	v_cmp_lt_f32_e32 vcc, s86, v91
	v_sub_f32_e32 v81, v112, v135
	v_exp_f32_e32 v81, v81
	v_cndmask_b32_e32 v143, 0, v82, vcc
	v_sub_f32_e32 v82, v113, v135
	v_exp_f32_e32 v82, v82
	v_cmp_lt_f32_e32 vcc, s86, v112
	v_add_f32_e32 v80, v142, v80
	v_add_f32_e32 v80, v143, v80
	v_cndmask_b32_e32 v144, 0, v81, vcc
	v_cmp_lt_f32_e32 vcc, s86, v113
	v_sub_f32_e32 v81, v114, v135
	v_exp_f32_e32 v81, v81
	v_cndmask_b32_e32 v145, 0, v82, vcc
	v_sub_f32_e32 v82, v92, v135
	v_exp_f32_e32 v82, v82
	v_add_f32_e32 v80, v144, v80
	v_cmp_lt_f32_e32 vcc, s86, v114
	v_add_f32_e32 v80, v145, v80
	v_mov_b64_e32 v[86:87], v[10:11]
	v_cndmask_b32_e32 v147, 0, v81, vcc
	v_cmp_lt_f32_e32 vcc, s86, v92
	v_add_f32_e32 v80, v147, v80
	v_mov_b64_e32 v[90:91], v[18:19]
	v_cndmask_b32_e32 v155, 0, v82, vcc
	v_add_f32_e32 v80, v155, v80
	v_mov_b32_e32 v81, v80
	s_nop 1
	v_permlane16_swap_b32_e32 v81, v80
	v_sub_f32_e32 v82, v95, v135
	v_exp_f32_e32 v92, v82
	v_mov_b64_e32 v[114:115], v[42:43]
	v_mov_b64_e32 v[84:85], v[8:9]
	s_waitcnt lgkmcnt(0)
	v_add_f32_e32 v138, v80, v81
	v_mov_b32_e32 v168, v138
	s_nop 1
	v_permlane32_swap_b32_e32 v168, v138
	v_cmp_eq_f32_e32 vcc, 1.0, v92
	v_mov_b64_e32 v[82:83], v[2:3]
	s_cmp_eq_u64 vcc, exec
	v_mov_b64_e32 v[80:81], v[0:1]
	v_mov_b64_e32 v[88:89], v[16:17]
	v_mov_b64_e32 v[112:113], v[40:41]
	s_cbranch_scc1 .LBB0_1430
	v_pk_mul_f32 v[114:115], v[42:43], v[92:93] op_sel_hi:[1,0]
	v_pk_mul_f32 v[112:113], v[40:41], v[92:93] op_sel_hi:[1,0]
	v_pk_mul_f32 v[90:91], v[18:19], v[92:93] op_sel_hi:[1,0]
	v_pk_mul_f32 v[88:89], v[16:17], v[92:93] op_sel_hi:[1,0]
	v_pk_mul_f32 v[86:87], v[10:11], v[92:93] op_sel_hi:[1,0]
	v_pk_mul_f32 v[84:85], v[8:9], v[92:93] op_sel_hi:[1,0]
	v_pk_mul_f32 v[82:83], v[2:3], v[92:93] op_sel_hi:[1,0]
	v_pk_mul_f32 v[80:81], v[0:1], v[92:93] op_sel_hi:[1,0]

.LBB0_1975:
	s_lshl_b32 s12, s11, 6
	v_mov_b32_e32 v189, v196
	s_cmp_gt_i32 s12, s20
	s_cbranch_scc1 .LBB0_1989
	s_mul_i32 s2, s21, 0x4800
	s_add_i32 s11, s2, 0
	s_mul_i32 s2, s21, 0x6800
	s_add_i32 s2, s2, 0
	v_and_b32_e32 v80, 48, v189
	v_and_b32_e32 v188, 15, v189
	v_add_u32_e32 v126, s2, v80
	v_mad_u32_u24 v80, v188, s84, v126
	ds_read_b128 v[122:125], v80
	ds_read_b128 v[118:121], v80 offset:64
	ds_read_b128 v[114:117], v80 offset:128
	ds_read_b128 v[110:113], v80 offset:3328
	ds_read_b128 v[106:109], v80 offset:3392
	ds_read_b128 v[102:105], v80 offset:3456
	ds_read_b128 v[98:101], v80 offset:6656
	ds_read_b128 v[94:97], v80 offset:6720
	v_and_b32_e32 v92, 63, v189
	v_or_b32_e32 v159, 48, v92
	v_mad_u32_u24 v81, v159, s84, v126
	ds_read_b128 v[88:91], v80 offset:6784
	ds_read_b128 v[84:87], v81
	ds_read_b128 v[80:83], v81 offset:64
	s_or_b32 s3, s12, 63
	v_cmp_le_i32_e32 vcc, s3, v184
	v_mul_u32_u24_e32 v127, 0xd0, v159
	s_cmp_lg_u64 vcc, exec
	s_mov_b64 s[2:3], -1
	v_add_u32_e32 v190, v126, v127
	s_cbranch_scc0 .LBB0_1982
	ds_read_b128 v[154:157], v190 offset:128
	s_waitcnt lgkmcnt(11)
	v_mfma_f32_16x16x32_bf16 v[126:129], v[122:125], v[32:35], 0
	v_lshrrev_b32_e32 v191, 4, v92
	v_lshl_or_b32 v175, v191, 2, s12
	v_cmp_lt_i32_e64 s[2:3], v175, v184
	s_waitcnt lgkmcnt(8)
	v_mfma_f32_16x16x32_bf16 v[130:133], v[110:113], v[32:35], 0
	v_or_b32_e32 v178, 2, v175
	v_or_b32_e32 v227, 3, v175
	v_cmp_lt_i32_e32 vcc, v205, v198
	s_waitcnt lgkmcnt(5)
	v_mfma_f32_16x16x32_bf16 v[134:137], v[98:101], v[32:35], 0
	v_or_b32_e32 v228, 17, v175
	v_cndmask_b32_e32 v92, v197, v205, vcc
	v_cmp_gt_i32_e32 vcc, v175, v184
	s_waitcnt lgkmcnt(2)
	v_mfma_f32_16x16x32_bf16 v[138:141], v[84:87], v[32:35], 0
	v_lshlrev_b32_e32 v176, 2, v92
	v_or_b32_e32 v229, 18, v175
	v_or_b32_e32 v230, 19, v175
	v_mfma_f32_16x16x32_bf16 v[126:129], v[118:121], v[36:39], v[126:129]
	v_or_b32_e32 v231, 32, v175
	v_or_b32_e32 v232, 33, v175
	v_or_b32_e32 v233, 34, v175
	v_mfma_f32_16x16x32_bf16 v[130:133], v[106:109], v[36:39], v[130:133]
	v_or_b32_e32 v234, 35, v175
	v_or_b32_e32 v235, 48, v175
	v_or_b32_e32 v236, 49, v175
	v_mfma_f32_16x16x32_bf16 v[134:137], v[94:97], v[36:39], v[134:137]
	v_or_b32_e32 v237, 50, v175
	v_or_b32_e32 v238, 51, v175
	s_waitcnt lgkmcnt(1)
	v_mfma_f32_16x16x32_bf16 v[138:141], v[80:83], v[36:39], v[138:141]
	v_mfma_f32_16x16x32_bf16 v[126:129], v[114:117], v[40:43], v[126:129]
	v_mfma_f32_16x16x32_bf16 v[130:133], v[102:105], v[40:43], v[130:133]
	v_mfma_f32_16x16x32_bf16 v[134:137], v[88:91], v[40:43], v[134:137]
	s_waitcnt lgkmcnt(0)
	v_mfma_f32_16x16x32_bf16 v[138:141], v[154:157], v[40:43], v[138:141]
	s_nop 7
	s_nop 3
	v_cndmask_b32_e64 v192, v158, v127, s[2:3]
	v_cmp_le_i32_e64 s[2:3], v178, v184
	v_or_b32_e32 v127, 16, v175
	v_cndmask_b32_e32 v92, v126, v158, vcc
	v_cndmask_b32_e64 v193, v158, v128, s[2:3]
	v_cmp_le_i32_e64 s[2:3], v227, v184
	v_max3_f32 v126, v92, s87, v192
	s_nop 0
	v_cndmask_b32_e64 v194, v158, v129, s[2:3]
	v_cmp_le_i32_e64 s[2:3], v127, v184
	v_max3_f32 v126, v126, v193, v194
	s_nop 0
	v_cndmask_b32_e64 v130, v158, v130, s[2:3]
	v_cmp_le_i32_e64 s[2:3], v228, v184
	s_nop 1
	v_cndmask_b32_e64 v131, v158, v131, s[2:3]
	v_cmp_le_i32_e64 s[2:3], v229, v184
	v_max3_f32 v126, v126, v130, v131
	s_nop 0
	v_cndmask_b32_e64 v132, v158, v132, s[2:3]
	v_cmp_le_i32_e64 s[2:3], v230, v184
	s_nop 1
	v_cndmask_b32_e64 v133, v158, v133, s[2:3]
	v_max3_f32 v142, v126, v132, v133
	v_mfma_f32_16x16x32_bf16 v[126:129], v[122:125], v[44:47], 0
	v_cmp_le_i32_e64 s[2:3], v231, v184
	v_mfma_f32_16x16x32_bf16 v[126:129], v[118:121], v[48:51], v[126:129]
	s_nop 0
	v_cndmask_b32_e64 v134, v158, v134, s[2:3]
	v_cmp_le_i32_e64 s[2:3], v232, v184
	s_nop 1
	v_cndmask_b32_e64 v135, v158, v135, s[2:3]
	v_max3_f32 v146, v142, v134, v135
	v_mfma_f32_16x16x32_bf16 v[142:145], v[114:117], v[52:55], v[126:129]
	v_cmp_le_i32_e64 s[2:3], v233, v184
	v_mfma_f32_16x16x32_bf16 v[126:129], v[110:113], v[44:47], 0
	s_nop 0
	v_cndmask_b32_e64 v136, v158, v136, s[2:3]
	v_cmp_le_i32_e64 s[2:3], v234, v184
	v_mfma_f32_16x16x32_bf16 v[126:129], v[106:109], v[48:51], v[126:129]
	s_nop 0
	v_cndmask_b32_e64 v137, v158, v137, s[2:3]
	v_max3_f32 v150, v146, v136, v137
	v_cmp_le_i32_e64 s[2:3], v235, v184
	v_mfma_f32_16x16x32_bf16 v[146:149], v[102:105], v[52:55], v[126:129]
	s_nop 0
	v_cndmask_b32_e64 v138, v158, v138, s[2:3]
	v_cmp_le_i32_e64 s[2:3], v236, v184
	v_mfma_f32_16x16x32_bf16 v[126:129], v[98:101], v[44:47], 0
	s_nop 0
	v_cndmask_b32_e64 v139, v158, v139, s[2:3]
	v_cmp_le_i32_e64 s[2:3], v237, v184
	v_mfma_f32_16x16x32_bf16 v[126:129], v[94:97], v[48:51], v[126:129]
	v_max3_f32 v150, v150, v138, v139
	v_cndmask_b32_e64 v140, v158, v140, s[2:3]
	v_cmp_le_i32_e64 s[2:3], v238, v184
	s_nop 1
	v_cndmask_b32_e64 v141, v158, v141, s[2:3]
	v_cmp_lt_i32_e64 s[2:3], v204, v198
	v_max3_f32 v174, v150, v140, v141
	v_mfma_f32_16x16x32_bf16 v[150:153], v[88:91], v[52:55], v[126:129]
	v_mov_b32_e32 v195, v174
	s_nop 1
	v_permlane16_swap_b32_e32 v195, v174
	s_waitcnt lgkmcnt(0)
	v_max3_f32 v174, v174, v195, v158
	s_nop 0
	v_cndmask_b32_e64 v126, v197, v204, s[2:3]
	v_lshlrev_b32_e32 v177, 2, v126
	v_mov_b32_e32 v195, v174
	s_nop 1
	v_permlane32_swap_b32_e32 v195, v174
	s_waitcnt lgkmcnt(0)
	v_max3_f32 v174, v174, v195, v158
	v_cmp_lt_f32_e64 s[2:3], s86, v92
	v_max3_f32 v174, v172, v174, v158
	v_mfma_f32_16x16x32_bf16 v[126:129], v[84:87], v[44:47], 0
	v_sub_f32_e32 v195, v92, v174
	v_exp_f32_e32 v195, v195
	v_sub_f32_e32 v213, v192, v174
	v_exp_f32_e32 v213, v213
	v_mfma_f32_16x16x32_bf16 v[126:129], v[80:83], v[48:51], v[126:129]
	v_cndmask_b32_e64 v217, 0, v195, s[2:3]
	v_cmp_lt_f32_e64 s[2:3], s86, v192
	v_sub_f32_e32 v192, v193, v174
	v_exp_f32_e32 v192, v192
	v_cndmask_b32_e64 v218, 0, v213, s[2:3]
	v_sub_f32_e32 v195, v194, v174
	v_cmp_lt_f32_e64 s[2:3], s86, v193
	v_exp_f32_e32 v195, v195
	v_sub_f32_e32 v193, v131, v174
	v_cndmask_b32_e64 v219, 0, v192, s[2:3]
	v_sub_f32_e32 v192, v130, v174
	v_exp_f32_e32 v192, v192
	v_cmp_lt_f32_e64 s[2:3], s86, v194
	v_exp_f32_e32 v193, v193
	v_add_f32_e32 v92, 0, v217
	v_cndmask_b32_e64 v220, 0, v195, s[2:3]
	v_cmp_lt_f32_e64 s[2:3], s86, v130
	v_sub_f32_e32 v130, v132, v174
	v_exp_f32_e32 v130, v130
	v_cndmask_b32_e64 v221, 0, v192, s[2:3]
	v_cmp_lt_f32_e64 s[2:3], s86, v131
	v_sub_f32_e32 v131, v133, v174
	v_exp_f32_e32 v131, v131
	v_cndmask_b32_e64 v222, 0, v193, s[2:3]
	v_cmp_lt_f32_e64 s[2:3], s86, v132
	v_add_f32_e32 v92, v218, v92
	v_add_f32_e32 v92, v219, v92
	v_cndmask_b32_e64 v223, 0, v130, s[2:3]
	v_cmp_lt_f32_e64 s[2:3], s86, v133
	v_sub_f32_e32 v130, v134, v174
	v_exp_f32_e32 v130, v130
	v_cndmask_b32_e64 v224, 0, v131, s[2:3]
	v_sub_f32_e32 v131, v135, v174
	v_exp_f32_e32 v131, v131
	v_cmp_lt_f32_e64 s[2:3], s86, v134
	v_add_f32_e32 v92, v220, v92
	v_add_f32_e32 v92, v221, v92
	v_cndmask_b32_e64 v192, 0, v130, s[2:3]
	v_cmp_lt_f32_e64 s[2:3], s86, v135
	v_sub_f32_e32 v130, v136, v174
	v_exp_f32_e32 v130, v130
	v_cndmask_b32_e64 v193, 0, v131, s[2:3]
	v_sub_f32_e32 v131, v137, v174
	v_exp_f32_e32 v131, v131
	v_cmp_lt_f32_e64 s[2:3], s86, v136
	v_add_f32_e32 v92, v222, v92
	v_add_f32_e32 v92, v223, v92
	v_cndmask_b32_e64 v194, 0, v130, s[2:3]
	v_cmp_lt_f32_e64 s[2:3], s86, v137
	v_sub_f32_e32 v130, v138, v174
	v_exp_f32_e32 v130, v130
	v_cndmask_b32_e64 v195, 0, v131, s[2:3]
	v_sub_f32_e32 v131, v139, v174
	v_exp_f32_e32 v131, v131
	v_add_f32_e32 v92, v224, v92
	v_cmp_lt_f32_e64 s[2:3], s86, v138
	v_add_f32_e32 v92, v192, v92
	v_add_f32_e32 v92, v193, v92
	v_cndmask_b32_e64 v213, 0, v130, s[2:3]
	v_cmp_lt_f32_e64 s[2:3], s86, v139
	v_sub_f32_e32 v130, v140, v174
	v_exp_f32_e32 v130, v130
	v_cndmask_b32_e64 v214, 0, v131, s[2:3]
	v_sub_f32_e32 v131, v141, v174
	v_add_f32_e32 v92, v194, v92
	v_exp_f32_e32 v131, v131
	v_add_f32_e32 v92, v195, v92
	v_add_f32_e32 v92, v213, v92
	v_cmp_lt_f32_e64 s[2:3], s86, v140
	v_add_f32_e32 v92, v214, v92
	v_mfma_f32_16x16x32_bf16 v[154:157], v[154:157], v[52:55], v[126:129]
	v_cndmask_b32_e64 v215, 0, v130, s[2:3]
	v_cmp_lt_f32_e64 s[2:3], s86, v141
	v_add_f32_e32 v92, v215, v92
	v_mov_b64_e32 v[128:129], v[30:31]
	v_cndmask_b32_e64 v216, 0, v131, s[2:3]
	v_add_f32_e32 v130, v216, v92
	v_mov_b32_e32 v131, v130
	s_nop 1
	v_permlane16_swap_b32_e32 v131, v130
	v_sub_f32_e32 v92, v172, v174
	v_exp_f32_e32 v92, v92
	v_mov_b64_e32 v[136:137], v[74:75]
	v_mov_b64_e32 v[140:141], v[78:79]
	s_waitcnt lgkmcnt(0)
	v_add_f32_e32 v225, v130, v131
	ds_bpermute_b32 v226, v177, v225
	v_cmp_eq_f32_e64 s[2:3], 1.0, v92
	v_mov_b64_e32 v[132:133], v[70:71]
	s_cmp_eq_u64 s[2:3], exec
	v_mov_b64_e32 v[126:127], v[28:29]
	v_mov_b64_e32 v[130:131], v[68:69]
	v_mov_b64_e32 v[134:135], v[72:73]
	v_mov_b64_e32 v[138:139], v[76:77]
	s_cbranch_scc1 .LBB0_1979
	v_pk_mul_f32 v[140:141], v[78:79], v[92:93] op_sel_hi:[1,0]
	v_pk_mul_f32 v[138:139], v[76:77], v[92:93] op_sel_hi:[1,0]
	v_pk_mul_f32 v[136:137], v[74:75], v[92:93] op_sel_hi:[1,0]
	v_pk_mul_f32 v[134:135], v[72:73], v[92:93] op_sel_hi:[1,0]
	v_pk_mul_f32 v[132:133], v[70:71], v[92:93] op_sel_hi:[1,0]
	v_pk_mul_f32 v[130:131], v[68:69], v[92:93] op_sel_hi:[1,0]
	v_pk_mul_f32 v[128:129], v[30:31], v[92:93] op_sel_hi:[1,0]
	v_pk_mul_f32 v[126:127], v[28:29], v[92:93] op_sel_hi:[1,0]

.LBB0_1982:
	s_and_b64 vcc, exec, s[2:3]
	s_cbranch_vccz .LBB0_1988
	s_waitcnt lgkmcnt(10)
	v_mfma_f32_16x16x32_bf16 v[126:129], v[122:125], v[32:35], 0
	v_cmp_lt_i32_e32 vcc, v205, v198
	v_mfma_f32_16x16x32_bf16 v[122:125], v[122:125], v[44:47], 0
	s_waitcnt lgkmcnt(9)
	v_mfma_f32_16x16x32_bf16 v[126:129], v[118:121], v[36:39], v[126:129]
	v_mfma_f32_16x16x32_bf16 v[118:121], v[118:121], v[48:51], v[122:125]
	s_waitcnt lgkmcnt(8)
	v_mfma_f32_16x16x32_bf16 v[122:125], v[114:117], v[40:43], v[126:129]
	v_mfma_f32_16x16x32_bf16 v[114:117], v[114:117], v[52:55], v[118:121]
	s_waitcnt lgkmcnt(7)
	v_mfma_f32_16x16x32_bf16 v[118:121], v[110:113], v[32:35], 0
	v_mfma_f32_16x16x32_bf16 v[110:113], v[110:113], v[44:47], 0
	s_waitcnt lgkmcnt(6)
	v_mfma_f32_16x16x32_bf16 v[118:121], v[106:109], v[36:39], v[118:121]
	v_mfma_f32_16x16x32_bf16 v[106:109], v[106:109], v[48:51], v[110:113]
	s_waitcnt lgkmcnt(5)
	v_mfma_f32_16x16x32_bf16 v[110:113], v[102:105], v[40:43], v[118:121]
	v_mfma_f32_16x16x32_bf16 v[102:105], v[102:105], v[52:55], v[106:109]
	s_waitcnt lgkmcnt(4)
	v_mfma_f32_16x16x32_bf16 v[106:109], v[98:101], v[32:35], 0
	v_mfma_f32_16x16x32_bf16 v[98:101], v[98:101], v[44:47], 0
	s_waitcnt lgkmcnt(3)
	v_mfma_f32_16x16x32_bf16 v[106:109], v[94:97], v[36:39], v[106:109]
	v_mfma_f32_16x16x32_bf16 v[94:97], v[94:97], v[48:51], v[98:101]
	s_waitcnt lgkmcnt(2)
	v_mfma_f32_16x16x32_bf16 v[126:129], v[88:91], v[40:43], v[106:109]
	v_mfma_f32_16x16x32_bf16 v[88:91], v[88:91], v[52:55], v[94:97]
	s_waitcnt lgkmcnt(1)
	v_mfma_f32_16x16x32_bf16 v[94:97], v[84:87], v[32:35], 0
	v_mfma_f32_16x16x32_bf16 v[84:87], v[84:87], v[44:47], 0
	s_waitcnt lgkmcnt(0)
	v_mfma_f32_16x16x32_bf16 v[94:97], v[80:83], v[36:39], v[94:97]
	v_mfma_f32_16x16x32_bf16 v[80:83], v[80:83], v[48:51], v[84:87]
	s_nop 4
	ds_read_b128 v[84:87], v190 offset:128
	s_waitcnt lgkmcnt(0)
	v_mfma_f32_16x16x32_bf16 v[94:97], v[84:87], v[40:43], v[94:97]
	s_nop 7
	v_mfma_f32_16x16x32_bf16 v[80:83], v[84:87], v[52:55], v[80:83]
	v_max3_f32 v84, v158, v122, v123
	v_cndmask_b32_e32 v85, v197, v205, vcc
	v_max3_f32 v84, v84, v124, v125
	v_lshlrev_b32_e32 v118, 2, v85
	v_max3_f32 v84, v84, v110, v111
	v_cmp_lt_i32_e32 vcc, v204, v198
	v_max3_f32 v84, v84, v112, v113
	s_nop 0
	v_max3_f32 v84, v84, v126, v127
	v_max3_f32 v84, v84, v128, v129
	v_max3_f32 v84, v84, v94, v95
	v_max3_f32 v84, v84, v96, v97
	v_mov_b32_e32 v85, v84
	s_nop 1
	v_permlane16_swap_b32_e32 v85, v84
	s_waitcnt lgkmcnt(0)
	v_max3_f32 v84, v84, v85, v158
	v_cndmask_b32_e32 v85, v197, v204, vcc
	v_lshlrev_b32_e32 v119, 2, v85
	v_mov_b32_e32 v85, v84
	s_nop 1
	v_permlane32_swap_b32_e32 v85, v84
	s_waitcnt lgkmcnt(0)
	v_max3_f32 v84, v84, v85, v158
	v_max3_f32 v174, v172, v84, v158
	s_nop 0
	v_sub_f32_e32 v84, v125, v174
	v_sub_f32_e32 v85, v124, v174
	v_sub_f32_e32 v86, v123, v174
	v_sub_f32_e32 v87, v122, v174
	v_exp_f32_e32 v98, v87
	v_exp_f32_e32 v99, v86
	v_exp_f32_e32 v100, v85
	v_exp_f32_e32 v101, v84
	v_sub_f32_e32 v109, v113, v174
	v_sub_f32_e32 v108, v112, v174
	v_sub_f32_e32 v107, v111, v174
	v_sub_f32_e32 v106, v110, v174
	v_exp_f32_e32 v106, v106
	v_exp_f32_e32 v107, v107
	v_exp_f32_e32 v108, v108
	v_exp_f32_e32 v109, v109
	v_pk_add_f32 v[84:85], v[98:99], 0 op_sel_hi:[1,0]
	v_pk_add_f32 v[86:87], v[100:101], 0 op_sel_hi:[1,0]
	v_pk_add_f32 v[112:113], v[106:107], v[84:85]
	v_pk_add_f32 v[110:111], v[108:109], v[86:87]
	v_sub_f32_e32 v87, v129, v174
	v_sub_f32_e32 v86, v128, v174
	v_sub_f32_e32 v85, v127, v174
	v_sub_f32_e32 v84, v126, v174
	v_exp_f32_e32 v84, v84
	v_exp_f32_e32 v85, v85
	v_exp_f32_e32 v86, v86
	v_exp_f32_e32 v87, v87
	v_sub_f32_e32 v97, v97, v174
	v_sub_f32_e32 v96, v96, v174
	v_sub_f32_e32 v95, v95, v174
	v_sub_f32_e32 v94, v94, v174
	v_exp_f32_e32 v94, v94
	v_exp_f32_e32 v95, v95
	v_exp_f32_e32 v96, v96
	v_exp_f32_e32 v97, v97
	v_pk_add_f32 v[112:113], v[84:85], v[112:113]
	v_pk_add_f32 v[110:111], v[86:87], v[110:111]
	v_pk_add_f32 v[112:113], v[94:95], v[112:113]
	v_pk_add_f32 v[110:111], v[96:97], v[110:111]
	v_sub_f32_e32 v92, v172, v174
	v_pk_mov_b32 v[120:121], v[112:113], v[110:111] op_sel:[1,0]
	v_mov_b32_e32 v113, v111
	v_pk_add_f32 v[110:111], v[120:121], v[112:113]
	v_exp_f32_e32 v92, v92
	v_add_f32_e32 v110, v110, v111
	v_mov_b32_e32 v111, v110
	s_nop 1
	v_permlane16_swap_b32_e32 v111, v110
	v_cmp_eq_f32_e32 vcc, 1.0, v92
	s_cmp_eq_u64 vcc, exec
	s_waitcnt lgkmcnt(0)
	v_add_f32_e32 v120, v110, v111
	v_mov_b32_e32 v121, v120
	s_nop 1
	v_permlane32_swap_b32_e32 v121, v120
	s_cbranch_scc1 .LBB0_1985
	v_pk_mul_f32 v[78:79], v[78:79], v[92:93] op_sel_hi:[1,0]
	v_pk_mul_f32 v[76:77], v[76:77], v[92:93] op_sel_hi:[1,0]
	v_pk_mul_f32 v[74:75], v[74:75], v[92:93] op_sel_hi:[1,0]
	v_pk_mul_f32 v[72:73], v[72:73], v[92:93] op_sel_hi:[1,0]
	v_pk_mul_f32 v[70:71], v[70:71], v[92:93] op_sel_hi:[1,0]
	v_pk_mul_f32 v[68:69], v[68:69], v[92:93] op_sel_hi:[1,0]
	v_pk_mul_f32 v[30:31], v[30:31], v[92:93] op_sel_hi:[1,0]
	v_pk_mul_f32 v[28:29], v[28:29], v[92:93] op_sel_hi:[1,0]
.LBB0_1985:
	v_max3_f32 v110, v158, v114, v115
	v_max3_f32 v110, v110, v116, v117
	v_max3_f32 v110, v110, v102, v103
	v_max3_f32 v110, v110, v104, v105
	v_max3_f32 v110, v110, v88, v89
	v_max3_f32 v110, v110, v90, v91
	v_max3_f32 v110, v110, v80, v81
	v_max3_f32 v110, v110, v82, v83
	v_mov_b32_e32 v111, v110
	s_nop 1
	v_permlane16_swap_b32_e32 v111, v110
	s_waitcnt lgkmcnt(0)
	v_max3_f32 v110, v110, v111, v158
	v_mov_b32_e32 v111, v110
	s_nop 1
	v_permlane32_swap_b32_e32 v111, v110
	s_waitcnt lgkmcnt(0)
	v_max3_f32 v110, v110, v111, v158
	v_max3_f32 v175, v173, v110, v158
	s_nop 0
	v_sub_f32_e32 v111, v117, v175
	v_sub_f32_e32 v110, v116, v175
	v_sub_f32_e32 v112, v115, v175
	v_sub_f32_e32 v113, v114, v175
	v_sub_f32_e32 v114, v105, v175
	v_sub_f32_e32 v115, v104, v175
	v_exp_f32_e32 v104, v113
	v_exp_f32_e32 v105, v112
	v_exp_f32_e32 v110, v110
	v_exp_f32_e32 v111, v111
	v_sub_f32_e32 v103, v103, v175
	v_sub_f32_e32 v102, v102, v175
	v_exp_f32_e32 v102, v102
	v_exp_f32_e32 v112, v115
	v_exp_f32_e32 v113, v114
	v_exp_f32_e32 v103, v103
	v_sub_f32_e32 v91, v91, v175
	v_sub_f32_e32 v90, v90, v175
	v_sub_f32_e32 v89, v89, v175
	v_sub_f32_e32 v88, v88, v175
	v_exp_f32_e32 v88, v88
	v_exp_f32_e32 v89, v89
	v_exp_f32_e32 v90, v90
	v_exp_f32_e32 v91, v91
	v_sub_f32_e32 v83, v83, v175
	v_sub_f32_e32 v82, v82, v175
	v_sub_f32_e32 v81, v81, v175
	v_sub_f32_e32 v80, v80, v175
	v_exp_f32_e32 v80, v80
	v_exp_f32_e32 v82, v82
	v_exp_f32_e32 v83, v83
	v_exp_f32_e32 v81, v81
	v_pk_add_f32 v[114:115], v[104:105], 0 op_sel_hi:[1,0]
	v_pk_add_f32 v[116:117], v[110:111], 0 op_sel_hi:[1,0]
	v_pk_add_f32 v[114:115], v[102:103], v[114:115]
	v_pk_add_f32 v[116:117], v[112:113], v[116:117]
	v_pk_add_f32 v[114:115], v[88:89], v[114:115]
	v_pk_add_f32 v[116:117], v[90:91], v[116:117]
	v_pk_add_f32 v[114:115], v[80:81], v[114:115]
	v_pk_add_f32 v[116:117], v[82:83], v[116:117]
	s_nop 0
	v_pk_mov_b32 v[122:123], v[114:115], v[116:117] op_sel:[1,0]
	v_mov_b32_e32 v115, v117
	v_pk_add_f32 v[114:115], v[122:123], v[114:115]
	s_nop 0
	v_add_f32_e32 v115, v114, v115
	v_mov_b32_e32 v116, v115
	s_nop 1
	v_permlane16_swap_b32_e32 v116, v115
	v_sub_f32_e32 v114, v173, v175
	v_exp_f32_e32 v114, v114
	s_waitcnt lgkmcnt(0)
	v_add_f32_e32 v115, v115, v116
	ds_bpermute_b32 v116, v119, v115
	v_cmp_eq_f32_e32 vcc, 1.0, v114
	s_cmp_eq_u64 vcc, exec
	s_cbranch_scc1 .LBB0_1987
	v_pk_mul_f32 v[66:67], v[66:67], v[114:115] op_sel_hi:[1,0]
	v_pk_mul_f32 v[64:65], v[64:65], v[114:115] op_sel_hi:[1,0]
	v_pk_mul_f32 v[26:27], v[26:27], v[114:115] op_sel_hi:[1,0]
	v_pk_mul_f32 v[24:25], v[24:25], v[114:115] op_sel_hi:[1,0]
	v_pk_mul_f32 v[22:23], v[22:23], v[114:115] op_sel_hi:[1,0]
	v_pk_mul_f32 v[20:21], v[20:21], v[114:115] op_sel_hi:[1,0]
	v_pk_mul_f32 v[18:19], v[18:19], v[114:115] op_sel_hi:[1,0]
	v_pk_mul_f32 v[16:17], v[16:17], v[114:115] op_sel_hi:[1,0]

.LBB0_1989:
	s_cmp_lt_i32 s10, 0
	s_cbranch_scc1 .LBB0_2004
	s_lshl_b32 s11, s10, 6
	v_mov_b32_e32 v189, v196
	s_cmp_gt_i32 s11, s20
	s_cbranch_scc1 .LBB0_2004
	s_lshl_b32 s2, s21, 1
	s_or_b32 s2, s2, 1
	s_mul_i32 s3, s2, 0x2400
	s_add_i32 s10, s3, 0
	s_lshl_b32 s2, s2, 12
	s_add_i32 s2, s10, s2
	s_waitcnt lgkmcnt(0)
	v_and_b32_e32 v80, 48, v189
	v_and_b32_e32 v188, 15, v189
	v_add_u32_e32 v126, s2, v80
	v_mad_u32_u24 v80, v188, s84, v126
	ds_read_b128 v[122:125], v80
	ds_read_b128 v[118:121], v80 offset:64
	ds_read_b128 v[114:117], v80 offset:128
	ds_read_b128 v[110:113], v80 offset:3328
	ds_read_b128 v[106:109], v80 offset:3392
	ds_read_b128 v[102:105], v80 offset:3456
	ds_read_b128 v[98:101], v80 offset:6656
	ds_read_b128 v[94:97], v80 offset:6720
	v_and_b32_e32 v92, 63, v189
	v_or_b32_e32 v159, 48, v92
	v_mad_u32_u24 v81, v159, s84, v126
	ds_read_b128 v[88:91], v80 offset:6784
	ds_read_b128 v[84:87], v81
	ds_read_b128 v[80:83], v81 offset:64
	s_or_b32 s3, s11, 63
	v_cmp_le_i32_e32 vcc, s3, v184
	v_mul_u32_u24_e32 v127, 0xd0, v159
	s_cmp_lg_u64 vcc, exec
	s_mov_b64 s[2:3], -1
	v_add_u32_e32 v190, v126, v127
	s_cbranch_scc0 .LBB0_1997
	ds_read_b128 v[154:157], v190 offset:128
	s_waitcnt lgkmcnt(11)
	v_mfma_f32_16x16x32_bf16 v[126:129], v[122:125], v[32:35], 0
	v_lshrrev_b32_e32 v191, 4, v92
	v_lshl_or_b32 v175, v191, 2, s11
	v_cmp_lt_i32_e64 s[2:3], v175, v184
	s_waitcnt lgkmcnt(8)
	v_mfma_f32_16x16x32_bf16 v[130:133], v[110:113], v[32:35], 0
	v_or_b32_e32 v178, 2, v175
	v_or_b32_e32 v227, 3, v175
	v_cmp_lt_i32_e32 vcc, v205, v198
	s_waitcnt lgkmcnt(5)
	v_mfma_f32_16x16x32_bf16 v[134:137], v[98:101], v[32:35], 0
	v_or_b32_e32 v228, 17, v175
	v_cndmask_b32_e32 v92, v197, v205, vcc
	v_cmp_gt_i32_e32 vcc, v175, v184
	s_waitcnt lgkmcnt(2)
	v_mfma_f32_16x16x32_bf16 v[138:141], v[84:87], v[32:35], 0
	v_lshlrev_b32_e32 v176, 2, v92
	v_or_b32_e32 v229, 18, v175
	v_or_b32_e32 v230, 19, v175
	v_mfma_f32_16x16x32_bf16 v[126:129], v[118:121], v[36:39], v[126:129]
	v_or_b32_e32 v231, 32, v175
	v_or_b32_e32 v232, 33, v175
	v_or_b32_e32 v233, 34, v175
	v_mfma_f32_16x16x32_bf16 v[130:133], v[106:109], v[36:39], v[130:133]
	v_or_b32_e32 v234, 35, v175
	v_or_b32_e32 v235, 48, v175
	v_or_b32_e32 v236, 49, v175
	v_mfma_f32_16x16x32_bf16 v[134:137], v[94:97], v[36:39], v[134:137]
	v_or_b32_e32 v237, 50, v175
	v_or_b32_e32 v238, 51, v175
	s_waitcnt lgkmcnt(1)
	v_mfma_f32_16x16x32_bf16 v[138:141], v[80:83], v[36:39], v[138:141]
	v_mfma_f32_16x16x32_bf16 v[126:129], v[114:117], v[40:43], v[126:129]
	v_mfma_f32_16x16x32_bf16 v[130:133], v[102:105], v[40:43], v[130:133]
	v_mfma_f32_16x16x32_bf16 v[134:137], v[88:91], v[40:43], v[134:137]
	s_waitcnt lgkmcnt(0)
	v_mfma_f32_16x16x32_bf16 v[138:141], v[154:157], v[40:43], v[138:141]
	s_nop 7
	s_nop 3
	v_cndmask_b32_e64 v192, v158, v127, s[2:3]
	v_cmp_le_i32_e64 s[2:3], v178, v184
	v_or_b32_e32 v127, 16, v175
	v_cndmask_b32_e32 v92, v126, v158, vcc
	v_cndmask_b32_e64 v193, v158, v128, s[2:3]
	v_cmp_le_i32_e64 s[2:3], v227, v184
	v_max3_f32 v126, v92, s87, v192
	s_nop 0
	v_cndmask_b32_e64 v194, v158, v129, s[2:3]
	v_cmp_le_i32_e64 s[2:3], v127, v184
	v_max3_f32 v126, v126, v193, v194
	s_nop 0
	v_cndmask_b32_e64 v130, v158, v130, s[2:3]
	v_cmp_le_i32_e64 s[2:3], v228, v184
	s_nop 1
	v_cndmask_b32_e64 v131, v158, v131, s[2:3]
	v_cmp_le_i32_e64 s[2:3], v229, v184
	v_max3_f32 v126, v126, v130, v131
	s_nop 0
	v_cndmask_b32_e64 v132, v158, v132, s[2:3]
	v_cmp_le_i32_e64 s[2:3], v230, v184
	s_nop 1
	v_cndmask_b32_e64 v133, v158, v133, s[2:3]
	v_max3_f32 v142, v126, v132, v133
	v_mfma_f32_16x16x32_bf16 v[126:129], v[122:125], v[44:47], 0
	v_cmp_le_i32_e64 s[2:3], v231, v184
	v_mfma_f32_16x16x32_bf16 v[126:129], v[118:121], v[48:51], v[126:129]
	s_nop 0
	v_cndmask_b32_e64 v134, v158, v134, s[2:3]
	v_cmp_le_i32_e64 s[2:3], v232, v184
	s_nop 1
	v_cndmask_b32_e64 v135, v158, v135, s[2:3]
	v_max3_f32 v146, v142, v134, v135
	v_mfma_f32_16x16x32_bf16 v[142:145], v[114:117], v[52:55], v[126:129]
	v_cmp_le_i32_e64 s[2:3], v233, v184
	v_mfma_f32_16x16x32_bf16 v[126:129], v[110:113], v[44:47], 0
	s_nop 0
	v_cndmask_b32_e64 v136, v158, v136, s[2:3]
	v_cmp_le_i32_e64 s[2:3], v234, v184
	v_mfma_f32_16x16x32_bf16 v[126:129], v[106:109], v[48:51], v[126:129]
	s_nop 0
	v_cndmask_b32_e64 v137, v158, v137, s[2:3]
	v_max3_f32 v150, v146, v136, v137
	v_cmp_le_i32_e64 s[2:3], v235, v184
	v_mfma_f32_16x16x32_bf16 v[146:149], v[102:105], v[52:55], v[126:129]
	s_nop 0
	v_cndmask_b32_e64 v138, v158, v138, s[2:3]
	v_cmp_le_i32_e64 s[2:3], v236, v184
	v_mfma_f32_16x16x32_bf16 v[126:129], v[98:101], v[44:47], 0
	s_nop 0
	v_cndmask_b32_e64 v139, v158, v139, s[2:3]
	v_cmp_le_i32_e64 s[2:3], v237, v184
	v_mfma_f32_16x16x32_bf16 v[126:129], v[94:97], v[48:51], v[126:129]
	v_max3_f32 v150, v150, v138, v139
	v_cndmask_b32_e64 v140, v158, v140, s[2:3]
	v_cmp_le_i32_e64 s[2:3], v238, v184
	s_nop 1
	v_cndmask_b32_e64 v141, v158, v141, s[2:3]
	v_cmp_lt_i32_e64 s[2:3], v204, v198
	v_max3_f32 v174, v150, v140, v141
	v_mfma_f32_16x16x32_bf16 v[150:153], v[88:91], v[52:55], v[126:129]
	v_mov_b32_e32 v195, v174
	s_nop 1
	v_permlane16_swap_b32_e32 v195, v174
	s_waitcnt lgkmcnt(0)
	v_max3_f32 v174, v174, v195, v158
	s_nop 0
	v_cndmask_b32_e64 v126, v197, v204, s[2:3]
	v_lshlrev_b32_e32 v177, 2, v126
	v_mov_b32_e32 v195, v174
	s_nop 1
	v_permlane32_swap_b32_e32 v195, v174
	s_waitcnt lgkmcnt(0)
	v_max3_f32 v174, v174, v195, v158
	v_cmp_lt_f32_e64 s[2:3], s86, v92
	v_max3_f32 v174, v172, v174, v158
	v_mfma_f32_16x16x32_bf16 v[126:129], v[84:87], v[44:47], 0
	v_sub_f32_e32 v195, v92, v174
	v_exp_f32_e32 v195, v195
	v_sub_f32_e32 v213, v192, v174
	v_exp_f32_e32 v213, v213
	v_mfma_f32_16x16x32_bf16 v[126:129], v[80:83], v[48:51], v[126:129]
	v_cndmask_b32_e64 v217, 0, v195, s[2:3]
	v_cmp_lt_f32_e64 s[2:3], s86, v192
	v_sub_f32_e32 v192, v193, v174
	v_exp_f32_e32 v192, v192
	v_cndmask_b32_e64 v218, 0, v213, s[2:3]
	v_sub_f32_e32 v195, v194, v174
	v_cmp_lt_f32_e64 s[2:3], s86, v193
	v_exp_f32_e32 v195, v195
	v_sub_f32_e32 v193, v131, v174
	v_cndmask_b32_e64 v219, 0, v192, s[2:3]
	v_sub_f32_e32 v192, v130, v174
	v_exp_f32_e32 v192, v192
	v_cmp_lt_f32_e64 s[2:3], s86, v194
	v_exp_f32_e32 v193, v193
	v_add_f32_e32 v92, 0, v217
	v_cndmask_b32_e64 v220, 0, v195, s[2:3]
	v_cmp_lt_f32_e64 s[2:3], s86, v130
	v_sub_f32_e32 v130, v132, v174
	v_exp_f32_e32 v130, v130
	v_cndmask_b32_e64 v221, 0, v192, s[2:3]
	v_cmp_lt_f32_e64 s[2:3], s86, v131
	v_sub_f32_e32 v131, v133, v174
	v_exp_f32_e32 v131, v131
	v_cndmask_b32_e64 v222, 0, v193, s[2:3]
	v_cmp_lt_f32_e64 s[2:3], s86, v132
	v_add_f32_e32 v92, v218, v92
	v_add_f32_e32 v92, v219, v92
	v_cndmask_b32_e64 v223, 0, v130, s[2:3]
	v_cmp_lt_f32_e64 s[2:3], s86, v133
	v_sub_f32_e32 v130, v134, v174
	v_exp_f32_e32 v130, v130
	v_cndmask_b32_e64 v224, 0, v131, s[2:3]
	v_sub_f32_e32 v131, v135, v174
	v_exp_f32_e32 v131, v131
	v_cmp_lt_f32_e64 s[2:3], s86, v134
	v_add_f32_e32 v92, v220, v92
	v_add_f32_e32 v92, v221, v92
	v_cndmask_b32_e64 v192, 0, v130, s[2:3]
	v_cmp_lt_f32_e64 s[2:3], s86, v135
	v_sub_f32_e32 v130, v136, v174
	v_exp_f32_e32 v130, v130
	v_cndmask_b32_e64 v193, 0, v131, s[2:3]
	v_sub_f32_e32 v131, v137, v174
	v_exp_f32_e32 v131, v131
	v_cmp_lt_f32_e64 s[2:3], s86, v136
	v_add_f32_e32 v92, v222, v92
	v_add_f32_e32 v92, v223, v92
	v_cndmask_b32_e64 v194, 0, v130, s[2:3]
	v_cmp_lt_f32_e64 s[2:3], s86, v137
	v_sub_f32_e32 v130, v138, v174
	v_exp_f32_e32 v130, v130
	v_cndmask_b32_e64 v195, 0, v131, s[2:3]
	v_sub_f32_e32 v131, v139, v174
	v_exp_f32_e32 v131, v131
	v_add_f32_e32 v92, v224, v92
	v_cmp_lt_f32_e64 s[2:3], s86, v138
	v_add_f32_e32 v92, v192, v92
	v_add_f32_e32 v92, v193, v92
	v_cndmask_b32_e64 v213, 0, v130, s[2:3]
	v_cmp_lt_f32_e64 s[2:3], s86, v139
	v_sub_f32_e32 v130, v140, v174
	v_exp_f32_e32 v130, v130
	v_cndmask_b32_e64 v214, 0, v131, s[2:3]
	v_sub_f32_e32 v131, v141, v174
	v_add_f32_e32 v92, v194, v92
	v_exp_f32_e32 v131, v131
	v_add_f32_e32 v92, v195, v92
	v_add_f32_e32 v92, v213, v92
	v_cmp_lt_f32_e64 s[2:3], s86, v140
	v_add_f32_e32 v92, v214, v92
	v_mfma_f32_16x16x32_bf16 v[154:157], v[154:157], v[52:55], v[126:129]
	v_cndmask_b32_e64 v215, 0, v130, s[2:3]
	v_cmp_lt_f32_e64 s[2:3], s86, v141
	v_add_f32_e32 v92, v215, v92
	v_mov_b64_e32 v[128:129], v[30:31]
	v_cndmask_b32_e64 v216, 0, v131, s[2:3]
	v_add_f32_e32 v130, v216, v92
	v_mov_b32_e32 v131, v130
	s_nop 1
	v_permlane16_swap_b32_e32 v131, v130
	v_sub_f32_e32 v92, v172, v174
	v_exp_f32_e32 v92, v92
	v_mov_b64_e32 v[136:137], v[74:75]
	v_mov_b64_e32 v[140:141], v[78:79]
	s_waitcnt lgkmcnt(0)
	v_add_f32_e32 v225, v130, v131
	ds_bpermute_b32 v226, v177, v225
	v_cmp_eq_f32_e64 s[2:3], 1.0, v92
	v_mov_b64_e32 v[132:133], v[70:71]
	s_cmp_eq_u64 s[2:3], exec
	v_mov_b64_e32 v[126:127], v[28:29]
	v_mov_b64_e32 v[130:131], v[68:69]
	v_mov_b64_e32 v[134:135], v[72:73]
	v_mov_b64_e32 v[138:139], v[76:77]
	s_cbranch_scc1 .LBB0_1994
	v_pk_mul_f32 v[140:141], v[78:79], v[92:93] op_sel_hi:[1,0]
	v_pk_mul_f32 v[138:139], v[76:77], v[92:93] op_sel_hi:[1,0]
	v_pk_mul_f32 v[136:137], v[74:75], v[92:93] op_sel_hi:[1,0]
	v_pk_mul_f32 v[134:135], v[72:73], v[92:93] op_sel_hi:[1,0]
	v_pk_mul_f32 v[132:133], v[70:71], v[92:93] op_sel_hi:[1,0]
	v_pk_mul_f32 v[130:131], v[68:69], v[92:93] op_sel_hi:[1,0]
	v_pk_mul_f32 v[128:129], v[30:31], v[92:93] op_sel_hi:[1,0]
	v_pk_mul_f32 v[126:127], v[28:29], v[92:93] op_sel_hi:[1,0]
